# EpiUp token conv: shifted taps fused into v_fmac_f32_dpp (row_shr + row_shl from the previous row group) instead of two dpp movs per element plus packed fma; 94 of 126 chains
# speedup vs baseline: 1.0073x; 1.0030x over previous
;     DI void operator()(const AccT& acc, const Unit& u, int wr, int wc, int fr, int fq) const {
;         const int cl = u.pn * 128 + wc * 32 + 8 * fq;
;         LAS float* P = (LAS float*)(plds + (wr * 4 + wc) * 1024);
;         { const int lane = fq * 16 + fr, kind = lane >> 3, c4 = 4 * (lane & 7), k3 = kind & 3;
;           const float* src = (k3 == 0 ? cb : cw + (k3 - 1) * 5632) + (kind >= 4 ? 2816 : 0) + u.pn * 128 + wc * 32 + c4;
;           *(LAS f32x4*)(P + kind * 32 + c4) = *(const f32x4*)src; }
; #pragma unroll
;         for (int ai = 0; ai < 2; ++ai) {
;             const int tok0 = u.pm * 248 + 62 * (2 * ai + wr) - 2 + fr;
;             float rs[4];
; #pragma unroll
;             for (int m = 0; m < 4; ++m) { const int t = tok0 + 16 * m; const int tc = t < 0 ? 0 : (t >= S ? S - 1 : t); const float r = rs_from_ss(rowss[tc]); rs[m] = t < 0 ? 0.f : r; }
;             const int row0 = fr < 2 ? (S + 236 + fr) : tok0;
; #pragma unroll
;             for (int n = 0; n < 2; ++n) {
;                 const int lc = 8 * fq + 4 * n;
;                 unsigned wpk[4][2];
; #pragma unroll
;                 for (int jp = 0; jp < 2; ++jp) {
;                     const f32x2 bg = *(const LAS f32x2*)(P + lc + 2 * jp), g0 = *(const LAS f32x2*)(P + 32 + lc + 2 * jp), g1 = *(const LAS f32x2*)(P + 64 + lc + 2 * jp), g2 = *(const LAS f32x2*)(P + 96 + lc + 2 * jp);
;                     const f32x2 bv = *(const LAS f32x2*)(P + 128 + lc + 2 * jp), v0 = *(const LAS f32x2*)(P + 160 + lc + 2 * jp), v1 = *(const LAS f32x2*)(P + 192 + lc + 2 * jp), v2 = *(const LAS f32x2*)(P + 224 + lc + 2 * jp);
;                     f32x2 G[4], V[4];
; #pragma unroll
;                     for (int m = 0; m < 4; ++m) { G[m] = (f32x2){acc[ai][0][m][n][2 * jp], acc[ai][0][m][n][2 * jp + 1]} * rs[m]; V[m] = (f32x2){acc[ai][1][m][n][2 * jp], acc[ai][1][m][n][2 * jp + 1]} * rs[m]; }
; #pragma unroll
;                     for (int m = 0; m < 4; ++m) {
;                         const f32x2 zz = {0.f, 0.f}; const f32x2 Gp = m ? G[m - 1] : zz, Vp = m ? V[m - 1] : zz;
;                         const f32x2 gp1 = {dpp_prev1(G[m].x, Gp.x), dpp_prev1(G[m].y, Gp.y)}, gp2 = {dpp_prev2(G[m].x, Gp.x), dpp_prev2(G[m].y, Gp.y)};
;                         const f32x2 vp1 = {dpp_prev1(V[m].x, Vp.x), dpp_prev1(V[m].y, Vp.y)}, vp2 = {dpp_prev2(V[m].x, Vp.x), dpp_prev2(V[m].y, Vp.y)};
.LBB0_1122:
	s_lshl_b32 s10, s58, 7
	s_ashr_i32 s11, s10, 31
	v_lshl_add_u64 v[128:129], s[10:11], 2, v[168:169]
	s_mul_i32 s11, s57, 0xf8
	v_add_u32_e32 v204, s11, v170
	v_med3_i32 v132, v204, 0, s51
	v_lshlrev_b32_e32 v132, 3, v132
	global_load_dwordx2 v[180:181], v132, s[16:17]
	v_add_u32_e32 v205, 16, v204
	v_med3_i32 v132, v205, 0, s51
	v_add_u32_e32 v206, 32, v204
	v_add_u32_e32 v207, 48, v204
	v_lshlrev_b32_e32 v132, 3, v132
	v_med3_i32 v133, v206, 0, s51
	v_med3_i32 v134, v207, 0, s51
	global_load_dwordx4 v[128:131], v[128:129], off
	v_lshlrev_b32_e32 v133, 3, v133
	v_lshlrev_b32_e32 v134, 3, v134
	global_load_dwordx2 v[182:183], v132, s[16:17]
	global_load_dwordx2 v[210:211], v133, s[16:17]
	global_load_dwordx2 v[212:213], v134, s[16:17]
	v_or_b32_e32 v188, s10, v187
	v_ashrrev_i32_e32 v189, 31, v188
	v_cndmask_b32_e64 v208, v204, v190, s[6:7]
	s_waitcnt vmcnt(0)
	v_add_u32_e32 v250, 0x7c, v204
	v_med3_i32 v250, v250, 0, s51
	v_lshlrev_b32_e32 v250, 3, v250
	global_load_dwordx2 v[242:243], v250, s[16:17]
	v_add_u32_e32 v250, 0x8c, v204
	v_med3_i32 v250, v250, 0, s51
	v_lshlrev_b32_e32 v250, 3, v250
	global_load_dwordx2 v[244:245], v250, s[16:17]
	v_add_u32_e32 v250, 0x9c, v204
	v_med3_i32 v250, v250, 0, s51
	v_lshlrev_b32_e32 v250, 3, v250
	global_load_dwordx2 v[246:247], v250, s[16:17]
	v_add_u32_e32 v250, 0xac, v204
	v_med3_i32 v250, v250, 0, s51
	v_lshlrev_b32_e32 v250, 3, v250
	global_load_dwordx2 v[248:249], v250, s[16:17]
	v_ffbh_u32_e32 v184, v181
	v_min_u32_e32 v184, 32, v184
	v_lshlrev_b64 v[180:181], v184, v[180:181]
	v_min_u32_e32 v180, 1, v180
	v_or_b32_e32 v180, v181, v180
	v_cvt_f32_u32_e32 v180, v180
	v_sub_u32_e32 v184, 32, v184
	ds_write_b128 v191, v[128:131]
	v_ffbh_u32_e32 v186, v183
	v_ffbh_u32_e32 v209, v211
	v_min_u32_e32 v186, 32, v186
	v_ffbh_u32_e32 v214, v213
	v_min_u32_e32 v209, 32, v209
	v_lshlrev_b64 v[182:183], v186, v[182:183]
	v_min_u32_e32 v214, 32, v214
	v_lshlrev_b64 v[210:211], v209, v[210:211]
	v_min_u32_e32 v181, 1, v182
	v_lshlrev_b64 v[212:213], v214, v[212:213]
	v_min_u32_e32 v182, 1, v210
	v_or_b32_e32 v181, v183, v181
	v_min_u32_e32 v210, 1, v212
	v_or_b32_e32 v182, v211, v182
	v_cvt_f32_u32_e32 v181, v181
	v_or_b32_e32 v183, v213, v210
	v_cvt_f32_u32_e32 v182, v182
	v_cvt_f32_u32_e32 v183, v183
	v_sub_u32_e32 v186, 32, v186
	v_ldexp_f32 v180, v180, v184
	v_sub_u32_e32 v209, 32, v209
	v_fmamk_f32 v180, v180, 0x30800000, v203
	v_ldexp_f32 v181, v181, v186
	v_sub_u32_e32 v214, 32, v214
	v_ldexp_f32 v182, v182, v209
	v_mul_f32_e32 v184, 0x4b800000, v180
	v_fmamk_f32 v181, v181, 0x30800000, v203
	v_cmp_gt_f32_e32 vcc, s52, v180
	v_ldexp_f32 v183, v183, v214
	v_fmamk_f32 v182, v182, 0x30800000, v203
	v_cndmask_b32_e32 v180, v180, v184, vcc
	v_mul_f32_e32 v184, 0x4b800000, v181
	v_cmp_gt_f32_e64 s[10:11], s52, v181
	v_fmamk_f32 v183, v183, 0x30800000, v203
	v_mul_f32_e32 v186, 0x4b800000, v182
	v_rsq_f32_e32 v180, v180
	v_cndmask_b32_e64 v181, v181, v184, s[10:11]
	v_cmp_gt_f32_e64 s[12:13], s52, v182
	v_mul_f32_e32 v209, 0x4b800000, v183
	v_cmp_gt_f32_e64 s[14:15], s52, v183
	v_cndmask_b32_e64 v182, v182, v186, s[12:13]
	v_rsq_f32_e32 v181, v181
	v_cndmask_b32_e64 v183, v183, v209, s[14:15]
	v_rsq_f32_e32 v182, v182
	v_rsq_f32_e32 v183, v183
	v_mul_f32_e32 v184, 0x45800000, v180
	v_cndmask_b32_e32 v180, v180, v184, vcc
	v_mul_f32_e32 v184, 0x45800000, v181
	v_cmp_lt_i32_e32 vcc, -1, v204
	v_mul_f32_e32 v209, 0x45800000, v182
	v_mul_f32_e32 v210, 0x45800000, v183
	v_cndmask_b32_e32 v186, 0, v180, vcc
	v_cndmask_b32_e64 v180, v181, v184, s[10:11]
	v_cmp_lt_i32_e32 vcc, s53, v204
	v_cndmask_b32_e64 v181, v182, v209, s[12:13]
	v_cndmask_b32_e64 v183, v183, v210, s[14:15]
	v_cndmask_b32_e32 v184, 0, v180, vcc
	v_cmp_lt_i32_e32 vcc, s54, v204
	v_pk_mul_f32 v[124:125], v[124:125], v[186:187] op_sel_hi:[1,0]
	ds_read_b128 v[136:139], v200
	ds_read_b128 v[148:151], v200 offset:128
	ds_read_b128 v[152:155], v200 offset:256
	ds_read_b128 v[156:159], v200 offset:384
	ds_read_b128 v[128:131], v200 offset:512
	ds_read_b128 v[132:135], v200 offset:640
	ds_read_b128 v[140:143], v200 offset:768
	ds_read_b128 v[144:147], v200 offset:896
	v_cndmask_b32_e32 v182, 0, v181, vcc
	v_cmp_lt_i32_e32 vcc, s55, v204
	v_pk_mul_f32 v[108:109], v[108:109], v[182:183] op_sel_hi:[1,0]
	v_pk_mul_f32 v[210:211], v[104:105], v[182:183] op_sel_hi:[1,0]
	v_cndmask_b32_e32 v180, 0, v183, vcc
	v_mov_b32_e32 v183, 0
	v_pk_mul_f32 v[212:213], v[100:101], v[180:181] op_sel_hi:[1,0]
	v_pk_mul_f32 v[214:215], v[96:97], v[180:181] op_sel_hi:[1,0]
	v_mov_b32_e32 v181, 0
	v_mov_b32_dpp v183, v183 row_ror:2 row_mask:0xf bank_mask:0xf
	s_nop 1
	v_mov_b32_dpp v181, v181 row_ror:1 row_mask:0xf bank_mask:0xf
	s_waitcnt lgkmcnt(6)
	v_pk_mul_f32 v[120:121], v[120:121], v[186:187] op_sel_hi:[1,0]
	s_waitcnt lgkmcnt(5)
	s_waitcnt lgkmcnt(4)
	v_pk_fma_f32 v[96:97], v[156:157], v[124:125], v[136:137]
	v_fmac_f32_dpp v96, v124, v148 row_shr:2 row_mask:0xf bank_mask:0xf
	v_fmac_f32_dpp v97, v125, v149 row_shr:2 row_mask:0xf bank_mask:0xf
	v_fmac_f32_dpp v96, v124, v152 row_shr:1 row_mask:0xf bank_mask:0xf
	v_fmac_f32_dpp v97, v125, v153 row_shr:1 row_mask:0xf bank_mask:0xf
	v_pk_mul_f32 v[100:101], v[96:97], s[0:1] op_sel_hi:[1,0]
	v_exp_f32_e32 v100, v100
	v_exp_f32_e32 v101, v101
	s_nop 0
	v_pk_add_f32 v[100:101], v[100:101], 1.0 op_sel_hi:[1,0]
	v_rcp_f32_e32 v100, v100
	v_rcp_f32_e32 v101, v101
	s_waitcnt lgkmcnt(2)
	v_pk_mul_f32 v[116:117], v[116:117], v[184:185] op_sel_hi:[1,0]
	s_waitcnt lgkmcnt(1)
	v_pk_mul_f32 v[96:97], v[96:97], v[100:101]
	s_waitcnt lgkmcnt(0)
; #define LAS __attribute__((address_space(3)))
; DI unsigned pk2(float lo, float hi) { f32x2 v = {lo, hi}; bf16x2_t b = __builtin_convertvector(v, bf16x2_t); return __builtin_bit_cast(unsigned, b); }
;     DI void operator()(const AccT& acc, const Unit& u, int wr, int wc, int fr, int fq) const {
;     ...
;                     const f32x2 bg = *(const LAS f32x2*)(P + lc + 2 * jp), g0 = *(const LAS f32x2*)(P + 32 + lc + 2 * jp), g1 = *(const LAS f32x2*)(P + 64 + lc + 2 * jp), g2 = *(const LAS f32x2*)(P + 96 + lc + 2 * jp);
;                     const f32x2 bv = *(const LAS f32x2*)(P + 128 + lc + 2 * jp), v0 = *(const LAS f32x2*)(P + 160 + lc + 2 * jp), v1 = *(const LAS f32x2*)(P + 192 + lc + 2 * jp), v2 = *(const LAS f32x2*)(P + 224 + lc + 2 * jp);
;                     f32x2 G[4], V[4];
; #pragma unroll
;                     for (int m = 0; m < 4; ++m) { G[m] = (f32x2){acc[ai][0][m][n][2 * jp], acc[ai][0][m][n][2 * jp + 1]} * rs[m]; V[m] = (f32x2){acc[ai][1][m][n][2 * jp], acc[ai][1][m][n][2 * jp + 1]} * rs[m]; }
; #pragma unroll
;                     for (int m = 0; m < 4; ++m) {
;                         const f32x2 zz = {0.f, 0.f}; const f32x2 Gp = m ? G[m - 1] : zz, Vp = m ? V[m - 1] : zz;
;                         const f32x2 gp1 = {dpp_prev1(G[m].x, Gp.x), dpp_prev1(G[m].y, Gp.y)}, gp2 = {dpp_prev2(G[m].x, Gp.x), dpp_prev2(G[m].y, Gp.y)};
;                         const f32x2 vp1 = {dpp_prev1(V[m].x, Vp.x), dpp_prev1(V[m].y, Vp.y)}, vp2 = {dpp_prev2(V[m].x, Vp.x), dpp_prev2(V[m].y, Vp.y)};
;                         const f32x2 gc = bg + g0 * gp2 + g1 * gp1 + g2 * G[m];
;                         const f32x2 vc = bv + v0 * vp2 + v1 * vp1 + v2 * V[m];
;                         const f32x2 xe = gc * (-LOG2E);
;                         f32x2 dn = {__builtin_amdgcn_exp2f(xe.x), __builtin_amdgcn_exp2f(xe.y)}; dn = dn + 1.0f;
;                         const f32x2 rc = {__builtin_amdgcn_rcpf(dn.x), __builtin_amdgcn_rcpf(dn.y)};
;                         const f32x2 rr = gc * rc * vc;
;                         wpk[m][jp] = pk2(rr.x, rr.y); }
	v_pk_fma_f32 v[104:105], v[144:145], v[120:121], v[128:129]
	v_fmac_f32_dpp v104, v120, v132 row_shr:2 row_mask:0xf bank_mask:0xf
	v_fmac_f32_dpp v105, v121, v133 row_shr:2 row_mask:0xf bank_mask:0xf
	v_fmac_f32_dpp v104, v120, v140 row_shr:1 row_mask:0xf bank_mask:0xf
	v_fmac_f32_dpp v105, v121, v141 row_shr:1 row_mask:0xf bank_mask:0xf
	v_pk_mul_f32 v[96:97], v[104:105], v[96:97]
	v_pk_fma_f32 v[100:101], v[156:157], v[116:117], v[136:137]
	v_fmac_f32_dpp v100, v116, v148 row_shr:2 row_mask:0xf bank_mask:0xf
	v_fmac_f32_dpp v100, v124, v148 row_shl:14 row_mask:0xf bank_mask:0xf
	v_fmac_f32_dpp v101, v117, v149 row_shr:2 row_mask:0xf bank_mask:0xf
	v_fmac_f32_dpp v101, v125, v149 row_shl:14 row_mask:0xf bank_mask:0xf
	v_fmac_f32_dpp v100, v116, v152 row_shr:1 row_mask:0xf bank_mask:0xf
	v_fmac_f32_dpp v100, v124, v152 row_shl:15 row_mask:0xf bank_mask:0xf
	v_fmac_f32_dpp v101, v117, v153 row_shr:1 row_mask:0xf bank_mask:0xf
	v_fmac_f32_dpp v101, v125, v153 row_shl:15 row_mask:0xf bank_mask:0xf
	v_pk_mul_f32 v[112:113], v[112:113], v[184:185] op_sel_hi:[1,0]
	v_pk_mul_f32 v[104:105], v[100:101], s[0:1] op_sel_hi:[1,0]
	v_exp_f32_e32 v104, v104
	v_exp_f32_e32 v105, v105
	s_nop 0
	v_pk_add_f32 v[104:105], v[104:105], 1.0 op_sel_hi:[1,0]
	v_rcp_f32_e32 v104, v104
	v_rcp_f32_e32 v105, v105
	s_nop 0
	v_pk_mul_f32 v[100:101], v[100:101], v[104:105]
	v_pk_fma_f32 v[216:217], v[144:145], v[112:113], v[128:129]
	v_fmac_f32_dpp v216, v112, v132 row_shr:2 row_mask:0xf bank_mask:0xf
	v_fmac_f32_dpp v216, v120, v132 row_shl:14 row_mask:0xf bank_mask:0xf
	v_fmac_f32_dpp v217, v113, v133 row_shr:2 row_mask:0xf bank_mask:0xf
	v_fmac_f32_dpp v217, v121, v133 row_shl:14 row_mask:0xf bank_mask:0xf
	v_fmac_f32_dpp v216, v112, v140 row_shr:1 row_mask:0xf bank_mask:0xf
	v_fmac_f32_dpp v216, v120, v140 row_shl:15 row_mask:0xf bank_mask:0xf
	v_fmac_f32_dpp v217, v113, v141 row_shr:1 row_mask:0xf bank_mask:0xf
	v_fmac_f32_dpp v217, v121, v141 row_shl:15 row_mask:0xf bank_mask:0xf
	v_mov_b64_e32 v[120:121], v[216:217]
	v_pk_mul_f32 v[100:101], v[120:121], v[100:101]
	v_pk_fma_f32 v[104:105], v[156:157], v[108:109], v[136:137]
	v_fmac_f32_dpp v104, v108, v148 row_shr:2 row_mask:0xf bank_mask:0xf
	v_fmac_f32_dpp v104, v116, v148 row_shl:14 row_mask:0xf bank_mask:0xf
	v_fmac_f32_dpp v105, v109, v149 row_shr:2 row_mask:0xf bank_mask:0xf
	v_fmac_f32_dpp v105, v117, v149 row_shl:14 row_mask:0xf bank_mask:0xf
	v_fmac_f32_dpp v104, v108, v152 row_shr:1 row_mask:0xf bank_mask:0xf
	v_fmac_f32_dpp v104, v116, v152 row_shl:15 row_mask:0xf bank_mask:0xf
	v_fmac_f32_dpp v105, v109, v153 row_shr:1 row_mask:0xf bank_mask:0xf
	v_fmac_f32_dpp v105, v117, v153 row_shl:15 row_mask:0xf bank_mask:0xf
	v_pk_mul_f32 v[120:121], v[104:105], s[0:1] op_sel_hi:[1,0]
	v_exp_f32_e32 v120, v120
	v_exp_f32_e32 v121, v121
	v_mov_b32_dpp v116, v112 row_ror:1 row_mask:0xf bank_mask:0xf
	v_mov_b32_dpp v117, v113 row_ror:1 row_mask:0xf bank_mask:0xf
	v_mov_b32_dpp v124, v112 row_ror:2 row_mask:0xf bank_mask:0xf
	v_mov_b32_dpp v125, v113 row_ror:2 row_mask:0xf bank_mask:0xf
	v_pk_add_f32 v[112:113], v[120:121], 1.0 op_sel_hi:[1,0]
	v_mov_b32_dpp v124, v210 row_shr:2 row_mask:0xf bank_mask:0xf
	v_rcp_f32_e32 v112, v112
	v_rcp_f32_e32 v113, v113
	v_mov_b32_dpp v125, v211 row_shr:2 row_mask:0xf bank_mask:0xf
	v_mov_b32_dpp v116, v210 row_shr:1 row_mask:0xf bank_mask:0xf
	v_mov_b32_dpp v117, v211 row_shr:1 row_mask:0xf bank_mask:0xf
	v_pk_fma_f32 v[120:121], v[132:133], v[124:125], v[128:129]
	v_pk_mul_f32 v[104:105], v[104:105], v[112:113]
	v_pk_fma_f32 v[116:117], v[140:141], v[116:117], v[120:121]
	v_pk_fma_f32 v[116:117], v[144:145], v[210:211], v[116:117]
	v_pk_mul_f32 v[104:105], v[116:117], v[104:105]
	v_pk_fma_f32 v[112:113], v[156:157], v[212:213], v[136:137]
	v_fmac_f32_dpp v112, v212, v148 row_shr:2 row_mask:0xf bank_mask:0xf
	v_fmac_f32_dpp v112, v108, v148 row_shl:14 row_mask:0xf bank_mask:0xf
	v_fmac_f32_dpp v113, v213, v149 row_shr:2 row_mask:0xf bank_mask:0xf
	v_fmac_f32_dpp v113, v109, v149 row_shl:14 row_mask:0xf bank_mask:0xf
	v_fmac_f32_dpp v112, v212, v152 row_shr:1 row_mask:0xf bank_mask:0xf
	v_fmac_f32_dpp v112, v108, v152 row_shl:15 row_mask:0xf bank_mask:0xf
	v_fmac_f32_dpp v113, v213, v153 row_shr:1 row_mask:0xf bank_mask:0xf
	v_fmac_f32_dpp v113, v109, v153 row_shl:15 row_mask:0xf bank_mask:0xf
	v_pk_mul_f32 v[116:117], v[112:113], s[0:1] op_sel_hi:[1,0]
	v_exp_f32_e32 v116, v116
	v_exp_f32_e32 v117, v117
	s_nop 0
	v_pk_add_f32 v[116:117], v[116:117], 1.0 op_sel_hi:[1,0]
	v_rcp_f32_e32 v116, v116
	v_rcp_f32_e32 v117, v117
	s_nop 0
	v_pk_mul_f32 v[112:113], v[112:113], v[116:117]
	v_pk_mul_f32 v[116:117], v[122:123], v[186:187] op_sel_hi:[1,0]
	v_pk_fma_f32 v[108:109], v[144:145], v[214:215], v[128:129]
	v_fmac_f32_dpp v108, v214, v132 row_shr:2 row_mask:0xf bank_mask:0xf
	v_fmac_f32_dpp v108, v210, v132 row_shl:14 row_mask:0xf bank_mask:0xf
	v_fmac_f32_dpp v109, v215, v133 row_shr:2 row_mask:0xf bank_mask:0xf
	v_fmac_f32_dpp v109, v211, v133 row_shl:14 row_mask:0xf bank_mask:0xf
	v_fmac_f32_dpp v108, v214, v140 row_shr:1 row_mask:0xf bank_mask:0xf
	v_fmac_f32_dpp v108, v210, v140 row_shl:15 row_mask:0xf bank_mask:0xf
	v_fmac_f32_dpp v109, v215, v141 row_shr:1 row_mask:0xf bank_mask:0xf
	v_fmac_f32_dpp v109, v211, v141 row_shl:15 row_mask:0xf bank_mask:0xf
	v_pk_mul_f32 v[108:109], v[108:109], v[112:113]
	v_pk_mul_f32 v[112:113], v[126:127], v[186:187] op_sel_hi:[1,0]
	v_pk_fma_f32 v[120:121], v[112:113], v[158:159], v[138:139]
	s_nop 1
	v_fmac_f32_dpp v120, v112, v150 row_shr:2 row_mask:0xf bank_mask:0xf
	v_fmac_f32_dpp v121, v113, v151 row_shr:2 row_mask:0xf bank_mask:0xf
; #define LAS __attribute__((address_space(3)))
; DI unsigned pk2(float lo, float hi) { f32x2 v = {lo, hi}; bf16x2_t b = __builtin_convertvector(v, bf16x2_t); return __builtin_bit_cast(unsigned, b); }
;     DI void operator()(const AccT& acc, const Unit& u, int wr, int wc, int fr, int fq) const {
;     ...
;                     const f32x2 bg = *(const LAS f32x2*)(P + lc + 2 * jp), g0 = *(const LAS f32x2*)(P + 32 + lc + 2 * jp), g1 = *(const LAS f32x2*)(P + 64 + lc + 2 * jp), g2 = *(const LAS f32x2*)(P + 96 + lc + 2 * jp);
;                     const f32x2 bv = *(const LAS f32x2*)(P + 128 + lc + 2 * jp), v0 = *(const LAS f32x2*)(P + 160 + lc + 2 * jp), v1 = *(const LAS f32x2*)(P + 192 + lc + 2 * jp), v2 = *(const LAS f32x2*)(P + 224 + lc + 2 * jp);
;                     f32x2 G[4], V[4];
; #pragma unroll
;                     for (int m = 0; m < 4; ++m) { G[m] = (f32x2){acc[ai][0][m][n][2 * jp], acc[ai][0][m][n][2 * jp + 1]} * rs[m]; V[m] = (f32x2){acc[ai][1][m][n][2 * jp], acc[ai][1][m][n][2 * jp + 1]} * rs[m]; }
; #pragma unroll
;                     for (int m = 0; m < 4; ++m) {
;                         const f32x2 zz = {0.f, 0.f}; const f32x2 Gp = m ? G[m - 1] : zz, Vp = m ? V[m - 1] : zz;
;                         const f32x2 gp1 = {dpp_prev1(G[m].x, Gp.x), dpp_prev1(G[m].y, Gp.y)}, gp2 = {dpp_prev2(G[m].x, Gp.x), dpp_prev2(G[m].y, Gp.y)};
;                         const f32x2 vp1 = {dpp_prev1(V[m].x, Vp.x), dpp_prev1(V[m].y, Vp.y)}, vp2 = {dpp_prev2(V[m].x, Vp.x), dpp_prev2(V[m].y, Vp.y)};
;                         const f32x2 gc = bg + g0 * gp2 + g1 * gp1 + g2 * G[m];
;                         const f32x2 vc = bv + v0 * vp2 + v1 * vp1 + v2 * V[m];
;                         const f32x2 xe = gc * (-LOG2E);
;                         f32x2 dn = {__builtin_amdgcn_exp2f(xe.x), __builtin_amdgcn_exp2f(xe.y)}; dn = dn + 1.0f;
;                         const f32x2 rc = {__builtin_amdgcn_rcpf(dn.x), __builtin_amdgcn_rcpf(dn.y)};
;                         const f32x2 rr = gc * rc * vc;
;                         wpk[m][jp] = pk2(rr.x, rr.y); }
	v_fmac_f32_dpp v120, v112, v154 row_shr:1 row_mask:0xf bank_mask:0xf
	v_fmac_f32_dpp v121, v113, v155 row_shr:1 row_mask:0xf bank_mask:0xf
	v_pk_mul_f32 v[122:123], v[120:121], s[0:1] op_sel_hi:[1,0]
	v_exp_f32_e32 v122, v122
	v_exp_f32_e32 v123, v123
	s_nop 0
	v_pk_add_f32 v[122:123], v[122:123], 1.0 op_sel_hi:[1,0]
	v_rcp_f32_e32 v122, v122
	v_rcp_f32_e32 v123, v123
	v_cvt_pk_bf16_f32 v228, v96, v97
	v_pk_mul_f32 v[120:121], v[120:121], v[122:123]
	v_pk_fma_f32 v[124:125], v[116:117], v[146:147], v[130:131]
	v_fmac_f32_dpp v124, v116, v134 row_shr:2 row_mask:0xf bank_mask:0xf
	v_fmac_f32_dpp v125, v117, v135 row_shr:2 row_mask:0xf bank_mask:0xf
	v_fmac_f32_dpp v124, v116, v142 row_shr:1 row_mask:0xf bank_mask:0xf
	v_fmac_f32_dpp v125, v117, v143 row_shr:1 row_mask:0xf bank_mask:0xf
	v_pk_mul_f32 v[120:121], v[124:125], v[120:121]
	v_pk_mul_f32 v[118:119], v[118:119], v[184:185] op_sel_hi:[1,0]
	v_cvt_pk_bf16_f32 v229, v120, v121
	v_pk_fma_f32 v[120:121], v[118:119], v[158:159], v[138:139]
	v_fmac_f32_dpp v120, v118, v150 row_shr:2 row_mask:0xf bank_mask:0xf
	v_fmac_f32_dpp v120, v112, v150 row_shl:14 row_mask:0xf bank_mask:0xf
	v_fmac_f32_dpp v121, v119, v151 row_shr:2 row_mask:0xf bank_mask:0xf
	v_fmac_f32_dpp v121, v113, v151 row_shl:14 row_mask:0xf bank_mask:0xf
	v_fmac_f32_dpp v120, v118, v154 row_shr:1 row_mask:0xf bank_mask:0xf
	v_fmac_f32_dpp v120, v112, v154 row_shl:15 row_mask:0xf bank_mask:0xf
	v_fmac_f32_dpp v121, v119, v155 row_shr:1 row_mask:0xf bank_mask:0xf
	v_fmac_f32_dpp v121, v113, v155 row_shl:15 row_mask:0xf bank_mask:0xf
	v_pk_mul_f32 v[122:123], v[120:121], s[0:1] op_sel_hi:[1,0]
	v_exp_f32_e32 v122, v122
	v_exp_f32_e32 v123, v123
	v_mov_b32_dpp v112, v116 row_ror:1 row_mask:0xf bank_mask:0xf
	v_mov_b32_dpp v113, v117 row_ror:1 row_mask:0xf bank_mask:0xf
	v_mov_b32_dpp v124, v116 row_ror:2 row_mask:0xf bank_mask:0xf
	v_mov_b32_dpp v125, v117 row_ror:2 row_mask:0xf bank_mask:0xf
	v_pk_add_f32 v[116:117], v[122:123], 1.0 op_sel_hi:[1,0]
	v_pk_mul_f32 v[114:115], v[114:115], v[184:185] op_sel_hi:[1,0]
	v_rcp_f32_e32 v116, v116
	v_rcp_f32_e32 v117, v117
	v_mov_b32_dpp v124, v114 row_shr:2 row_mask:0xf bank_mask:0xf
	v_mov_b32_dpp v125, v115 row_shr:2 row_mask:0xf bank_mask:0xf
	v_mov_b32_dpp v112, v114 row_shr:1 row_mask:0xf bank_mask:0xf
	v_mov_b32_dpp v113, v115 row_shr:1 row_mask:0xf bank_mask:0xf
	v_pk_fma_f32 v[122:123], v[134:135], v[124:125], v[130:131]
	v_pk_mul_f32 v[116:117], v[120:121], v[116:117]
	v_pk_fma_f32 v[112:113], v[142:143], v[112:113], v[122:123]
	v_cvt_pk_bf16_f32 v232, v100, v101
	v_pk_fma_f32 v[112:113], v[114:115], v[146:147], v[112:113]
	v_pk_mul_f32 v[110:111], v[110:111], v[182:183] op_sel_hi:[1,0]
	v_pk_mul_f32 v[112:113], v[112:113], v[116:117]
	v_cvt_pk_bf16_f32 v233, v112, v113
	v_pk_fma_f32 v[112:113], v[110:111], v[158:159], v[138:139]
	v_fmac_f32_dpp v112, v110, v150 row_shr:2 row_mask:0xf bank_mask:0xf
	v_fmac_f32_dpp v112, v118, v150 row_shl:14 row_mask:0xf bank_mask:0xf
	v_fmac_f32_dpp v113, v111, v151 row_shr:2 row_mask:0xf bank_mask:0xf
	v_fmac_f32_dpp v113, v119, v151 row_shl:14 row_mask:0xf bank_mask:0xf
	v_fmac_f32_dpp v112, v110, v154 row_shr:1 row_mask:0xf bank_mask:0xf
	v_fmac_f32_dpp v112, v118, v154 row_shl:15 row_mask:0xf bank_mask:0xf
	v_fmac_f32_dpp v113, v111, v155 row_shr:1 row_mask:0xf bank_mask:0xf
	v_fmac_f32_dpp v113, v119, v155 row_shl:15 row_mask:0xf bank_mask:0xf
	v_pk_mul_f32 v[116:117], v[112:113], s[0:1] op_sel_hi:[1,0]
	v_exp_f32_e32 v116, v116
	v_exp_f32_e32 v117, v117
	v_mov_b32_dpp v118, v114 row_ror:1 row_mask:0xf bank_mask:0xf
	v_mov_b32_dpp v119, v115 row_ror:1 row_mask:0xf bank_mask:0xf
	v_mov_b32_dpp v120, v114 row_ror:2 row_mask:0xf bank_mask:0xf
	v_mov_b32_dpp v121, v115 row_ror:2 row_mask:0xf bank_mask:0xf
	v_pk_add_f32 v[114:115], v[116:117], 1.0 op_sel_hi:[1,0]
	v_pk_mul_f32 v[106:107], v[106:107], v[182:183] op_sel_hi:[1,0]
	v_rcp_f32_e32 v114, v114
	v_rcp_f32_e32 v115, v115
	v_mov_b32_dpp v120, v106 row_shr:2 row_mask:0xf bank_mask:0xf
	v_mov_b32_dpp v121, v107 row_shr:2 row_mask:0xf bank_mask:0xf
	v_mov_b32_dpp v118, v106 row_shr:1 row_mask:0xf bank_mask:0xf
	v_mov_b32_dpp v119, v107 row_shr:1 row_mask:0xf bank_mask:0xf
	v_pk_fma_f32 v[116:117], v[134:135], v[120:121], v[130:131]
	v_pk_mul_f32 v[112:113], v[112:113], v[114:115]
	v_pk_fma_f32 v[116:117], v[142:143], v[118:119], v[116:117]
	v_pk_fma_f32 v[116:117], v[106:107], v[146:147], v[116:117]
	v_pk_mul_f32 v[112:113], v[116:117], v[112:113]
	v_cvt_pk_bf16_f32 v236, v104, v105
	v_pk_mul_f32 v[102:103], v[102:103], v[180:181] op_sel_hi:[1,0]
	v_cvt_pk_bf16_f32 v237, v112, v113
	v_pk_fma_f32 v[114:115], v[102:103], v[158:159], v[138:139]
	v_fmac_f32_dpp v114, v102, v150 row_shr:2 row_mask:0xf bank_mask:0xf
	v_fmac_f32_dpp v114, v110, v150 row_shl:14 row_mask:0xf bank_mask:0xf
	v_fmac_f32_dpp v115, v103, v151 row_shr:2 row_mask:0xf bank_mask:0xf
	v_fmac_f32_dpp v115, v111, v151 row_shl:14 row_mask:0xf bank_mask:0xf
	v_fmac_f32_dpp v114, v102, v154 row_shr:1 row_mask:0xf bank_mask:0xf
	v_fmac_f32_dpp v114, v110, v154 row_shl:15 row_mask:0xf bank_mask:0xf
	v_fmac_f32_dpp v115, v103, v155 row_shr:1 row_mask:0xf bank_mask:0xf
	v_fmac_f32_dpp v115, v111, v155 row_shl:15 row_mask:0xf bank_mask:0xf
	v_mov_b64_e32 v[102:103], v[114:115]
	v_pk_mul_f32 v[112:113], v[102:103], s[0:1] op_sel_hi:[1,0]
	v_exp_f32_e32 v112, v112
	v_exp_f32_e32 v113, v113
	v_mov_b32_dpp v110, v106 row_ror:1 row_mask:0xf bank_mask:0xf
	v_mov_b32_dpp v111, v107 row_ror:1 row_mask:0xf bank_mask:0xf
	v_mov_b32_dpp v116, v106 row_ror:2 row_mask:0xf bank_mask:0xf
	v_mov_b32_dpp v117, v107 row_ror:2 row_mask:0xf bank_mask:0xf
; #define LAS __attribute__((address_space(3)))
; DI unsigned pk2(float lo, float hi) { f32x2 v = {lo, hi}; bf16x2_t b = __builtin_convertvector(v, bf16x2_t); return __builtin_bit_cast(unsigned, b); }
;     DI void operator()(const AccT& acc, const Unit& u, int wr, int wc, int fr, int fq) const {
;     ...
;                     const f32x2 bg = *(const LAS f32x2*)(P + lc + 2 * jp), g0 = *(const LAS f32x2*)(P + 32 + lc + 2 * jp), g1 = *(const LAS f32x2*)(P + 64 + lc + 2 * jp), g2 = *(const LAS f32x2*)(P + 96 + lc + 2 * jp);
;                     const f32x2 bv = *(const LAS f32x2*)(P + 128 + lc + 2 * jp), v0 = *(const LAS f32x2*)(P + 160 + lc + 2 * jp), v1 = *(const LAS f32x2*)(P + 192 + lc + 2 * jp), v2 = *(const LAS f32x2*)(P + 224 + lc + 2 * jp);
;                     f32x2 G[4], V[4];
; #pragma unroll
;                     for (int m = 0; m < 4; ++m) { G[m] = (f32x2){acc[ai][0][m][n][2 * jp], acc[ai][0][m][n][2 * jp + 1]} * rs[m]; V[m] = (f32x2){acc[ai][1][m][n][2 * jp], acc[ai][1][m][n][2 * jp + 1]} * rs[m]; }
; #pragma unroll
;                     for (int m = 0; m < 4; ++m) {
;                         const f32x2 zz = {0.f, 0.f}; const f32x2 Gp = m ? G[m - 1] : zz, Vp = m ? V[m - 1] : zz;
;                         const f32x2 gp1 = {dpp_prev1(G[m].x, Gp.x), dpp_prev1(G[m].y, Gp.y)}, gp2 = {dpp_prev2(G[m].x, Gp.x), dpp_prev2(G[m].y, Gp.y)};
;                         const f32x2 vp1 = {dpp_prev1(V[m].x, Vp.x), dpp_prev1(V[m].y, Vp.y)}, vp2 = {dpp_prev2(V[m].x, Vp.x), dpp_prev2(V[m].y, Vp.y)};
;                         const f32x2 gc = bg + g0 * gp2 + g1 * gp1 + g2 * G[m];
;                         const f32x2 vc = bv + v0 * vp2 + v1 * vp1 + v2 * V[m];
;                         const f32x2 xe = gc * (-LOG2E);
;                         f32x2 dn = {__builtin_amdgcn_exp2f(xe.x), __builtin_amdgcn_exp2f(xe.y)}; dn = dn + 1.0f;
;                         const f32x2 rc = {__builtin_amdgcn_rcpf(dn.x), __builtin_amdgcn_rcpf(dn.y)};
;                         const f32x2 rr = gc * rc * vc;
;                         wpk[m][jp] = pk2(rr.x, rr.y); }
;                 }
; #pragma unroll
;                 for (int m = 0; m < 4; ++m) { const int row = m ? tok0 + 16 * m : row0;
;                     *(u32x2*)(ACT + (size_t)row * 2816 + cl + 4 * n) = (u32x2){wpk[m][0], wpk[m][1]}; }
	v_pk_add_f32 v[106:107], v[112:113], 1.0 op_sel_hi:[1,0]
	v_pk_mul_f32 v[98:99], v[98:99], v[180:181] op_sel_hi:[1,0]
	v_rcp_f32_e32 v106, v106
	v_rcp_f32_e32 v107, v107
	v_mov_b32_dpp v116, v98 row_shr:2 row_mask:0xf bank_mask:0xf
	v_mov_b32_dpp v117, v99 row_shr:2 row_mask:0xf bank_mask:0xf
	v_mov_b32_dpp v110, v98 row_shr:1 row_mask:0xf bank_mask:0xf
	v_mov_b32_dpp v111, v99 row_shr:1 row_mask:0xf bank_mask:0xf
	v_pk_fma_f32 v[112:113], v[134:135], v[116:117], v[130:131]
	v_pk_mul_f32 v[102:103], v[102:103], v[106:107]
	v_pk_fma_f32 v[110:111], v[142:143], v[110:111], v[112:113]
	v_mov_b64_e32 v[128:129], s[4:5]
	v_pk_fma_f32 v[98:99], v[98:99], v[146:147], v[110:111]
	v_cvt_pk_bf16_f32 v252, v108, v109
	v_pk_mul_f32 v[98:99], v[98:99], v[102:103]
	v_lshlrev_b64 v[130:131], 1, v[188:189]
	v_cvt_pk_bf16_f32 v253, v98, v99
	v_mad_i64_i32 v[98:99], s[10:11], v208, s48, v[128:129]
	v_lshl_add_u64 v[132:133], v[98:99], 0, v[130:131]
	v_mad_i64_i32 v[96:97], s[10:11], v205, s48, v[128:129]
	v_lshl_add_u64 v[134:135], v[96:97], 0, v[130:131]
	v_mad_i64_i32 v[96:97], s[10:11], v206, s48, v[128:129]
	v_lshl_add_u64 v[136:137], v[96:97], 0, v[130:131]
	v_mad_i64_i32 v[96:97], s[10:11], v207, s48, v[128:129]
	v_lshl_add_u64 v[138:139], v[96:97], 0, v[130:131]
	v_pk_mul_f32 v[92:93], v[92:93], v[186:187] op_sel_hi:[1,0]
	v_pk_mul_f32 v[142:143], v[68:69], v[180:181] op_sel_hi:[1,0]
	v_pk_mul_f32 v[144:145], v[64:65], v[180:181] op_sel_hi:[1,0]
	ds_read_b128 v[104:107], v200 offset:16
	ds_read_b128 v[116:119], v200 offset:144
	ds_read_b128 v[120:123], v200 offset:272
	ds_read_b128 v[124:127], v200 offset:400
	ds_read_b128 v[96:99], v200 offset:528
	ds_read_b128 v[100:103], v200 offset:656
	ds_read_b128 v[108:111], v200 offset:784
	ds_read_b128 v[112:115], v200 offset:912
	s_waitcnt lgkmcnt(6)
	v_pk_mul_f32 v[88:89], v[88:89], v[186:187] op_sel_hi:[1,0]
	s_waitcnt lgkmcnt(5)
	s_waitcnt lgkmcnt(4)
	v_pk_fma_f32 v[64:65], v[92:93], v[124:125], v[104:105]
	v_fmac_f32_dpp v64, v92, v116 row_shr:2 row_mask:0xf bank_mask:0xf
	v_fmac_f32_dpp v65, v93, v117 row_shr:2 row_mask:0xf bank_mask:0xf
	v_fmac_f32_dpp v64, v92, v120 row_shr:1 row_mask:0xf bank_mask:0xf
	v_fmac_f32_dpp v65, v93, v121 row_shr:1 row_mask:0xf bank_mask:0xf
	v_pk_mul_f32 v[68:69], v[64:65], s[0:1] op_sel_hi:[1,0]
	v_pk_mul_f32 v[140:141], v[72:73], v[182:183] op_sel_hi:[1,0]
	v_exp_f32_e32 v68, v68
	v_exp_f32_e32 v69, v69
	s_nop 0
	v_pk_add_f32 v[68:69], v[68:69], 1.0 op_sel_hi:[1,0]
	v_rcp_f32_e32 v68, v68
	v_rcp_f32_e32 v69, v69
	s_waitcnt lgkmcnt(2)
	v_pk_mul_f32 v[64:65], v[64:65], v[68:69]
	s_waitcnt lgkmcnt(1)
	v_pk_mul_f32 v[84:85], v[84:85], v[184:185] op_sel_hi:[1,0]
	s_waitcnt lgkmcnt(0)
	v_pk_fma_f32 v[72:73], v[88:89], v[112:113], v[96:97]
	v_fmac_f32_dpp v72, v88, v100 row_shr:2 row_mask:0xf bank_mask:0xf
	v_fmac_f32_dpp v73, v89, v101 row_shr:2 row_mask:0xf bank_mask:0xf
	v_fmac_f32_dpp v72, v88, v108 row_shr:1 row_mask:0xf bank_mask:0xf
	v_fmac_f32_dpp v73, v89, v109 row_shr:1 row_mask:0xf bank_mask:0xf
	v_pk_mul_f32 v[64:65], v[72:73], v[64:65]
	v_pk_fma_f32 v[68:69], v[84:85], v[124:125], v[104:105]
	v_fmac_f32_dpp v68, v84, v116 row_shr:2 row_mask:0xf bank_mask:0xf
	v_fmac_f32_dpp v68, v92, v116 row_shl:14 row_mask:0xf bank_mask:0xf
	v_fmac_f32_dpp v69, v85, v117 row_shr:2 row_mask:0xf bank_mask:0xf
	v_fmac_f32_dpp v69, v93, v117 row_shl:14 row_mask:0xf bank_mask:0xf
	v_fmac_f32_dpp v68, v84, v120 row_shr:1 row_mask:0xf bank_mask:0xf
	v_fmac_f32_dpp v68, v92, v120 row_shl:15 row_mask:0xf bank_mask:0xf
	v_fmac_f32_dpp v69, v85, v121 row_shr:1 row_mask:0xf bank_mask:0xf
	v_fmac_f32_dpp v69, v93, v121 row_shl:15 row_mask:0xf bank_mask:0xf
	v_pk_mul_f32 v[80:81], v[80:81], v[184:185] op_sel_hi:[1,0]
	v_pk_mul_f32 v[72:73], v[68:69], s[0:1] op_sel_hi:[1,0]
	v_exp_f32_e32 v72, v72
	v_exp_f32_e32 v73, v73
	s_nop 0
	v_pk_add_f32 v[72:73], v[72:73], 1.0 op_sel_hi:[1,0]
	v_rcp_f32_e32 v72, v72
	v_rcp_f32_e32 v73, v73
	s_nop 0
	v_pk_mul_f32 v[68:69], v[68:69], v[72:73]
	v_pk_mul_f32 v[76:77], v[76:77], v[182:183] op_sel_hi:[1,0]
	v_pk_fma_f32 v[146:147], v[80:81], v[112:113], v[96:97]
	v_fmac_f32_dpp v146, v80, v100 row_shr:2 row_mask:0xf bank_mask:0xf
	v_fmac_f32_dpp v146, v88, v100 row_shl:14 row_mask:0xf bank_mask:0xf
	v_fmac_f32_dpp v147, v81, v101 row_shr:2 row_mask:0xf bank_mask:0xf
	v_fmac_f32_dpp v147, v89, v101 row_shl:14 row_mask:0xf bank_mask:0xf
	v_fmac_f32_dpp v146, v80, v108 row_shr:1 row_mask:0xf bank_mask:0xf
	v_fmac_f32_dpp v146, v88, v108 row_shl:15 row_mask:0xf bank_mask:0xf
	v_fmac_f32_dpp v147, v81, v109 row_shr:1 row_mask:0xf bank_mask:0xf
	v_fmac_f32_dpp v147, v89, v109 row_shl:15 row_mask:0xf bank_mask:0xf
	v_mov_b64_e32 v[88:89], v[146:147]
	v_pk_mul_f32 v[68:69], v[88:89], v[68:69]
	v_pk_fma_f32 v[72:73], v[76:77], v[124:125], v[104:105]
	v_fmac_f32_dpp v72, v76, v116 row_shr:2 row_mask:0xf bank_mask:0xf
	v_fmac_f32_dpp v72, v84, v116 row_shl:14 row_mask:0xf bank_mask:0xf
	v_fmac_f32_dpp v73, v77, v117 row_shr:2 row_mask:0xf bank_mask:0xf
	v_fmac_f32_dpp v73, v85, v117 row_shl:14 row_mask:0xf bank_mask:0xf
	v_fmac_f32_dpp v72, v76, v120 row_shr:1 row_mask:0xf bank_mask:0xf
	v_fmac_f32_dpp v72, v84, v120 row_shl:15 row_mask:0xf bank_mask:0xf
	v_fmac_f32_dpp v73, v77, v121 row_shr:1 row_mask:0xf bank_mask:0xf
	v_fmac_f32_dpp v73, v85, v121 row_shl:15 row_mask:0xf bank_mask:0xf
	v_pk_mul_f32 v[88:89], v[72:73], s[0:1] op_sel_hi:[1,0]
	v_exp_f32_e32 v88, v88
	v_exp_f32_e32 v89, v89
	v_mov_b32_dpp v84, v80 row_ror:1 row_mask:0xf bank_mask:0xf
	v_mov_b32_dpp v85, v81 row_ror:1 row_mask:0xf bank_mask:0xf
	v_mov_b32_dpp v92, v80 row_ror:2 row_mask:0xf bank_mask:0xf
; #define LAS __attribute__((address_space(3)))
; DI unsigned pk2(float lo, float hi) { f32x2 v = {lo, hi}; bf16x2_t b = __builtin_convertvector(v, bf16x2_t); return __builtin_bit_cast(unsigned, b); }
;     DI void operator()(const AccT& acc, const Unit& u, int wr, int wc, int fr, int fq) const {
;     ...
;                     const f32x2 bg = *(const LAS f32x2*)(P + lc + 2 * jp), g0 = *(const LAS f32x2*)(P + 32 + lc + 2 * jp), g1 = *(const LAS f32x2*)(P + 64 + lc + 2 * jp), g2 = *(const LAS f32x2*)(P + 96 + lc + 2 * jp);
;                     const f32x2 bv = *(const LAS f32x2*)(P + 128 + lc + 2 * jp), v0 = *(const LAS f32x2*)(P + 160 + lc + 2 * jp), v1 = *(const LAS f32x2*)(P + 192 + lc + 2 * jp), v2 = *(const LAS f32x2*)(P + 224 + lc + 2 * jp);
;                     f32x2 G[4], V[4];
; #pragma unroll
;                     for (int m = 0; m < 4; ++m) { G[m] = (f32x2){acc[ai][0][m][n][2 * jp], acc[ai][0][m][n][2 * jp + 1]} * rs[m]; V[m] = (f32x2){acc[ai][1][m][n][2 * jp], acc[ai][1][m][n][2 * jp + 1]} * rs[m]; }
; #pragma unroll
;                     for (int m = 0; m < 4; ++m) {
;                         const f32x2 zz = {0.f, 0.f}; const f32x2 Gp = m ? G[m - 1] : zz, Vp = m ? V[m - 1] : zz;
;                         const f32x2 gp1 = {dpp_prev1(G[m].x, Gp.x), dpp_prev1(G[m].y, Gp.y)}, gp2 = {dpp_prev2(G[m].x, Gp.x), dpp_prev2(G[m].y, Gp.y)};
;                         const f32x2 vp1 = {dpp_prev1(V[m].x, Vp.x), dpp_prev1(V[m].y, Vp.y)}, vp2 = {dpp_prev2(V[m].x, Vp.x), dpp_prev2(V[m].y, Vp.y)};
;                         const f32x2 gc = bg + g0 * gp2 + g1 * gp1 + g2 * G[m];
;                         const f32x2 vc = bv + v0 * vp2 + v1 * vp1 + v2 * V[m];
;                         const f32x2 xe = gc * (-LOG2E);
;                         f32x2 dn = {__builtin_amdgcn_exp2f(xe.x), __builtin_amdgcn_exp2f(xe.y)}; dn = dn + 1.0f;
;                         const f32x2 rc = {__builtin_amdgcn_rcpf(dn.x), __builtin_amdgcn_rcpf(dn.y)};
;                         const f32x2 rr = gc * rc * vc;
;                         wpk[m][jp] = pk2(rr.x, rr.y); }
	v_mov_b32_dpp v93, v81 row_ror:2 row_mask:0xf bank_mask:0xf
	v_pk_add_f32 v[80:81], v[88:89], 1.0 op_sel_hi:[1,0]
	v_mov_b32_dpp v92, v140 row_shr:2 row_mask:0xf bank_mask:0xf
	v_rcp_f32_e32 v80, v80
	v_rcp_f32_e32 v81, v81
	v_mov_b32_dpp v93, v141 row_shr:2 row_mask:0xf bank_mask:0xf
	v_mov_b32_dpp v84, v140 row_shr:1 row_mask:0xf bank_mask:0xf
	v_mov_b32_dpp v85, v141 row_shr:1 row_mask:0xf bank_mask:0xf
	v_pk_fma_f32 v[88:89], v[100:101], v[92:93], v[96:97]
	v_pk_mul_f32 v[72:73], v[72:73], v[80:81]
	v_pk_fma_f32 v[84:85], v[108:109], v[84:85], v[88:89]
	v_pk_fma_f32 v[84:85], v[140:141], v[112:113], v[84:85]
	v_pk_mul_f32 v[72:73], v[84:85], v[72:73]
	v_pk_fma_f32 v[80:81], v[142:143], v[124:125], v[104:105]
	v_fmac_f32_dpp v80, v142, v116 row_shr:2 row_mask:0xf bank_mask:0xf
	v_fmac_f32_dpp v80, v76, v116 row_shl:14 row_mask:0xf bank_mask:0xf
	v_fmac_f32_dpp v81, v143, v117 row_shr:2 row_mask:0xf bank_mask:0xf
	v_fmac_f32_dpp v81, v77, v117 row_shl:14 row_mask:0xf bank_mask:0xf
	v_fmac_f32_dpp v80, v142, v120 row_shr:1 row_mask:0xf bank_mask:0xf
	v_fmac_f32_dpp v80, v76, v120 row_shl:15 row_mask:0xf bank_mask:0xf
	v_fmac_f32_dpp v81, v143, v121 row_shr:1 row_mask:0xf bank_mask:0xf
	v_fmac_f32_dpp v81, v77, v121 row_shl:15 row_mask:0xf bank_mask:0xf
	v_pk_mul_f32 v[84:85], v[80:81], s[0:1] op_sel_hi:[1,0]
	v_exp_f32_e32 v84, v84
	v_exp_f32_e32 v85, v85
	s_nop 0
	v_pk_add_f32 v[84:85], v[84:85], 1.0 op_sel_hi:[1,0]
	v_rcp_f32_e32 v84, v84
	v_rcp_f32_e32 v85, v85
	s_nop 0
	v_pk_mul_f32 v[80:81], v[80:81], v[84:85]
	v_pk_mul_f32 v[84:85], v[90:91], v[186:187] op_sel_hi:[1,0]
	v_pk_fma_f32 v[76:77], v[144:145], v[112:113], v[96:97]
	v_fmac_f32_dpp v76, v144, v100 row_shr:2 row_mask:0xf bank_mask:0xf
	v_fmac_f32_dpp v76, v140, v100 row_shl:14 row_mask:0xf bank_mask:0xf
	v_fmac_f32_dpp v77, v145, v101 row_shr:2 row_mask:0xf bank_mask:0xf
	v_fmac_f32_dpp v77, v141, v101 row_shl:14 row_mask:0xf bank_mask:0xf
	v_fmac_f32_dpp v76, v144, v108 row_shr:1 row_mask:0xf bank_mask:0xf
	v_fmac_f32_dpp v76, v140, v108 row_shl:15 row_mask:0xf bank_mask:0xf
	v_fmac_f32_dpp v77, v145, v109 row_shr:1 row_mask:0xf bank_mask:0xf
	v_fmac_f32_dpp v77, v141, v109 row_shl:15 row_mask:0xf bank_mask:0xf
	v_pk_mul_f32 v[76:77], v[76:77], v[80:81]
	v_pk_mul_f32 v[80:81], v[94:95], v[186:187] op_sel_hi:[1,0]
	v_pk_fma_f32 v[88:89], v[80:81], v[126:127], v[106:107]
	s_nop 1
	v_fmac_f32_dpp v88, v80, v118 row_shr:2 row_mask:0xf bank_mask:0xf
	v_fmac_f32_dpp v89, v81, v119 row_shr:2 row_mask:0xf bank_mask:0xf
	v_fmac_f32_dpp v88, v80, v122 row_shr:1 row_mask:0xf bank_mask:0xf
	v_fmac_f32_dpp v89, v81, v123 row_shr:1 row_mask:0xf bank_mask:0xf
	v_pk_mul_f32 v[90:91], v[88:89], s[0:1] op_sel_hi:[1,0]
	v_exp_f32_e32 v90, v90
	v_exp_f32_e32 v91, v91
	s_nop 0
	v_pk_add_f32 v[90:91], v[90:91], 1.0 op_sel_hi:[1,0]
	v_rcp_f32_e32 v90, v90
	v_rcp_f32_e32 v91, v91
	v_cvt_pk_bf16_f32 v230, v64, v65
	v_pk_mul_f32 v[88:89], v[88:89], v[90:91]
	v_pk_fma_f32 v[92:93], v[84:85], v[114:115], v[98:99]
	v_fmac_f32_dpp v92, v84, v102 row_shr:2 row_mask:0xf bank_mask:0xf
	v_fmac_f32_dpp v93, v85, v103 row_shr:2 row_mask:0xf bank_mask:0xf
	v_fmac_f32_dpp v92, v84, v110 row_shr:1 row_mask:0xf bank_mask:0xf
	v_fmac_f32_dpp v93, v85, v111 row_shr:1 row_mask:0xf bank_mask:0xf
	v_pk_mul_f32 v[88:89], v[92:93], v[88:89]
	v_pk_mul_f32 v[86:87], v[86:87], v[184:185] op_sel_hi:[1,0]
	v_cvt_pk_bf16_f32 v231, v88, v89
	v_pk_fma_f32 v[88:89], v[86:87], v[126:127], v[106:107]
	v_fmac_f32_dpp v88, v86, v118 row_shr:2 row_mask:0xf bank_mask:0xf
	v_fmac_f32_dpp v88, v80, v118 row_shl:14 row_mask:0xf bank_mask:0xf
	v_fmac_f32_dpp v89, v87, v119 row_shr:2 row_mask:0xf bank_mask:0xf
	v_fmac_f32_dpp v89, v81, v119 row_shl:14 row_mask:0xf bank_mask:0xf
	v_fmac_f32_dpp v88, v86, v122 row_shr:1 row_mask:0xf bank_mask:0xf
	v_fmac_f32_dpp v88, v80, v122 row_shl:15 row_mask:0xf bank_mask:0xf
	v_fmac_f32_dpp v89, v87, v123 row_shr:1 row_mask:0xf bank_mask:0xf
	v_fmac_f32_dpp v89, v81, v123 row_shl:15 row_mask:0xf bank_mask:0xf
	v_pk_mul_f32 v[90:91], v[88:89], s[0:1] op_sel_hi:[1,0]
	v_exp_f32_e32 v90, v90
	v_exp_f32_e32 v91, v91
	v_mov_b32_dpp v80, v84 row_ror:1 row_mask:0xf bank_mask:0xf
	v_mov_b32_dpp v81, v85 row_ror:1 row_mask:0xf bank_mask:0xf
	v_mov_b32_dpp v92, v84 row_ror:2 row_mask:0xf bank_mask:0xf
	v_mov_b32_dpp v93, v85 row_ror:2 row_mask:0xf bank_mask:0xf
	v_pk_add_f32 v[84:85], v[90:91], 1.0 op_sel_hi:[1,0]
	v_pk_mul_f32 v[82:83], v[82:83], v[184:185] op_sel_hi:[1,0]
	v_rcp_f32_e32 v84, v84
	v_rcp_f32_e32 v85, v85
	v_mov_b32_dpp v92, v82 row_shr:2 row_mask:0xf bank_mask:0xf
	v_mov_b32_dpp v93, v83 row_shr:2 row_mask:0xf bank_mask:0xf
	v_mov_b32_dpp v80, v82 row_shr:1 row_mask:0xf bank_mask:0xf
	v_mov_b32_dpp v81, v83 row_shr:1 row_mask:0xf bank_mask:0xf
	v_pk_fma_f32 v[90:91], v[102:103], v[92:93], v[98:99]
	v_pk_mul_f32 v[84:85], v[88:89], v[84:85]
	v_pk_fma_f32 v[80:81], v[110:111], v[80:81], v[90:91]
	v_cvt_pk_bf16_f32 v234, v68, v69
	v_pk_fma_f32 v[80:81], v[82:83], v[114:115], v[80:81]
	v_pk_mul_f32 v[78:79], v[78:79], v[182:183] op_sel_hi:[1,0]
	v_pk_mul_f32 v[80:81], v[80:81], v[84:85]
	v_cvt_pk_bf16_f32 v235, v80, v81
	v_pk_fma_f32 v[80:81], v[78:79], v[126:127], v[106:107]
	v_fmac_f32_dpp v80, v78, v118 row_shr:2 row_mask:0xf bank_mask:0xf
	v_fmac_f32_dpp v80, v86, v118 row_shl:14 row_mask:0xf bank_mask:0xf
	v_fmac_f32_dpp v81, v79, v119 row_shr:2 row_mask:0xf bank_mask:0xf
	v_fmac_f32_dpp v81, v87, v119 row_shl:14 row_mask:0xf bank_mask:0xf
	v_fmac_f32_dpp v80, v78, v122 row_shr:1 row_mask:0xf bank_mask:0xf
	v_fmac_f32_dpp v80, v86, v122 row_shl:15 row_mask:0xf bank_mask:0xf
; #define LAS __attribute__((address_space(3)))
;     DI void operator()(const AccT& acc, const Unit& u, int wr, int wc, int fr, int fq) const {
;     ...
;             const int tok0 = u.pm * 248 + 62 * (2 * ai + wr) - 2 + fr;
;             float rs[4];
; #pragma unroll
;     ...
;                     const f32x2 bg = *(const LAS f32x2*)(P + lc + 2 * jp), g0 = *(const LAS f32x2*)(P + 32 + lc + 2 * jp), g1 = *(const LAS f32x2*)(P + 64 + lc + 2 * jp), g2 = *(const LAS f32x2*)(P + 96 + lc + 2 * jp);
;                     const f32x2 bv = *(const LAS f32x2*)(P + 128 + lc + 2 * jp), v0 = *(const LAS f32x2*)(P + 160 + lc + 2 * jp), v1 = *(const LAS f32x2*)(P + 192 + lc + 2 * jp), v2 = *(const LAS f32x2*)(P + 224 + lc + 2 * jp);
;                     f32x2 G[4], V[4];
; #pragma unroll
;                     for (int m = 0; m < 4; ++m) { G[m] = (f32x2){acc[ai][0][m][n][2 * jp], acc[ai][0][m][n][2 * jp + 1]} * rs[m]; V[m] = (f32x2){acc[ai][1][m][n][2 * jp], acc[ai][1][m][n][2 * jp + 1]} * rs[m]; }
; #pragma unroll
;                     for (int m = 0; m < 4; ++m) {
;                         const f32x2 zz = {0.f, 0.f}; const f32x2 Gp = m ? G[m - 1] : zz, Vp = m ? V[m - 1] : zz;
;                         const f32x2 gp1 = {dpp_prev1(G[m].x, Gp.x), dpp_prev1(G[m].y, Gp.y)}, gp2 = {dpp_prev2(G[m].x, Gp.x), dpp_prev2(G[m].y, Gp.y)};
;                         const f32x2 vp1 = {dpp_prev1(V[m].x, Vp.x), dpp_prev1(V[m].y, Vp.y)}, vp2 = {dpp_prev2(V[m].x, Vp.x), dpp_prev2(V[m].y, Vp.y)};
;                         const f32x2 gc = bg + g0 * gp2 + g1 * gp1 + g2 * G[m];
;                         const f32x2 vc = bv + v0 * vp2 + v1 * vp1 + v2 * V[m];
;                         const f32x2 xe = gc * (-LOG2E);
;                         f32x2 dn = {__builtin_amdgcn_exp2f(xe.x), __builtin_amdgcn_exp2f(xe.y)}; dn = dn + 1.0f;
;                         const f32x2 rc = {__builtin_amdgcn_rcpf(dn.x), __builtin_amdgcn_rcpf(dn.y)};
;                         const f32x2 rr = gc * rc * vc;
;                         wpk[m][jp] = pk2(rr.x, rr.y); }
;                 }
; #pragma unroll
;                 for (int m = 0; m < 4; ++m) { const int row = m ? tok0 + 16 * m : row0;
;                     *(u32x2*)(ACT + (size_t)row * 2816 + cl + 4 * n) = (u32x2){wpk[m][0], wpk[m][1]}; }
	v_fmac_f32_dpp v81, v79, v123 row_shr:1 row_mask:0xf bank_mask:0xf
	v_fmac_f32_dpp v81, v87, v123 row_shl:15 row_mask:0xf bank_mask:0xf
	v_pk_mul_f32 v[84:85], v[80:81], s[0:1] op_sel_hi:[1,0]
	v_exp_f32_e32 v84, v84
	v_exp_f32_e32 v85, v85
	v_mov_b32_dpp v86, v82 row_ror:1 row_mask:0xf bank_mask:0xf
	v_mov_b32_dpp v87, v83 row_ror:1 row_mask:0xf bank_mask:0xf
	v_mov_b32_dpp v88, v82 row_ror:2 row_mask:0xf bank_mask:0xf
	v_mov_b32_dpp v89, v83 row_ror:2 row_mask:0xf bank_mask:0xf
	v_pk_add_f32 v[82:83], v[84:85], 1.0 op_sel_hi:[1,0]
	v_pk_mul_f32 v[74:75], v[74:75], v[182:183] op_sel_hi:[1,0]
	v_rcp_f32_e32 v82, v82
	v_rcp_f32_e32 v83, v83
	v_mov_b32_dpp v88, v74 row_shr:2 row_mask:0xf bank_mask:0xf
	v_mov_b32_dpp v89, v75 row_shr:2 row_mask:0xf bank_mask:0xf
	v_mov_b32_dpp v86, v74 row_shr:1 row_mask:0xf bank_mask:0xf
	v_mov_b32_dpp v87, v75 row_shr:1 row_mask:0xf bank_mask:0xf
	v_pk_fma_f32 v[84:85], v[102:103], v[88:89], v[98:99]
	v_pk_mul_f32 v[80:81], v[80:81], v[82:83]
	v_pk_fma_f32 v[84:85], v[110:111], v[86:87], v[84:85]
	v_pk_fma_f32 v[84:85], v[74:75], v[114:115], v[84:85]
	v_pk_mul_f32 v[80:81], v[84:85], v[80:81]
	v_cvt_pk_bf16_f32 v238, v72, v73
	v_pk_mul_f32 v[70:71], v[70:71], v[180:181] op_sel_hi:[1,0]
	v_cvt_pk_bf16_f32 v239, v80, v81
	v_pk_fma_f32 v[82:83], v[70:71], v[126:127], v[106:107]
	v_fmac_f32_dpp v82, v70, v118 row_shr:2 row_mask:0xf bank_mask:0xf
	v_fmac_f32_dpp v82, v78, v118 row_shl:14 row_mask:0xf bank_mask:0xf
	v_fmac_f32_dpp v83, v71, v119 row_shr:2 row_mask:0xf bank_mask:0xf
	v_fmac_f32_dpp v83, v79, v119 row_shl:14 row_mask:0xf bank_mask:0xf
	v_fmac_f32_dpp v82, v70, v122 row_shr:1 row_mask:0xf bank_mask:0xf
	v_fmac_f32_dpp v82, v78, v122 row_shl:15 row_mask:0xf bank_mask:0xf
	v_fmac_f32_dpp v83, v71, v123 row_shr:1 row_mask:0xf bank_mask:0xf
	v_fmac_f32_dpp v83, v79, v123 row_shl:15 row_mask:0xf bank_mask:0xf
	v_mov_b64_e32 v[70:71], v[82:83]
	v_pk_mul_f32 v[80:81], v[70:71], s[0:1] op_sel_hi:[1,0]
	v_exp_f32_e32 v80, v80
	v_exp_f32_e32 v81, v81
	v_mov_b32_dpp v78, v74 row_ror:1 row_mask:0xf bank_mask:0xf
	v_mov_b32_dpp v79, v75 row_ror:1 row_mask:0xf bank_mask:0xf
	v_mov_b32_dpp v84, v74 row_ror:2 row_mask:0xf bank_mask:0xf
	v_mov_b32_dpp v85, v75 row_ror:2 row_mask:0xf bank_mask:0xf
	v_pk_add_f32 v[74:75], v[80:81], 1.0 op_sel_hi:[1,0]
	v_pk_mul_f32 v[66:67], v[66:67], v[180:181] op_sel_hi:[1,0]
	v_rcp_f32_e32 v74, v74
	v_rcp_f32_e32 v75, v75
	v_mov_b32_dpp v84, v66 row_shr:2 row_mask:0xf bank_mask:0xf
	v_mov_b32_dpp v85, v67 row_shr:2 row_mask:0xf bank_mask:0xf
	v_mov_b32_dpp v78, v66 row_shr:1 row_mask:0xf bank_mask:0xf
	v_mov_b32_dpp v79, v67 row_shr:1 row_mask:0xf bank_mask:0xf
	v_pk_fma_f32 v[80:81], v[102:103], v[84:85], v[98:99]
	v_pk_mul_f32 v[70:71], v[70:71], v[74:75]
	v_pk_fma_f32 v[78:79], v[110:111], v[78:79], v[80:81]
	v_cvt_pk_bf16_f32 v254, v76, v77
	v_pk_fma_f32 v[66:67], v[66:67], v[114:115], v[78:79]
	s_nop 0
	v_pk_mul_f32 v[66:67], v[66:67], v[70:71]
	s_nop 0
	v_cvt_pk_bf16_f32 v255, v66, v67
	global_store_dwordx4 v[132:133], v[228:231], off
	global_store_dwordx4 v[134:135], v[232:235], off
	global_store_dwordx4 v[136:137], v[236:239], off
	global_store_dwordx4 v[138:139], v[252:255], off
	v_add_u32_e32 v96, 0x7c, v204
	v_med3_i32 v64, v96, 0, s51
	v_add_u32_e32 v97, 0x8c, v204
	v_add_u32_e32 v99, 0x9c, v204
	v_add_u32_e32 v101, 0xac, v204
	v_lshlrev_b32_e32 v64, 3, v64
	v_med3_i32 v65, v97, 0, s51
	v_med3_i32 v66, v99, 0, s51
	v_med3_i32 v67, v101, 0, s51
	v_lshlrev_b32_e32 v65, 3, v65
	v_lshlrev_b32_e32 v66, 3, v66
	v_lshlrev_b32_e32 v67, 3, v67
	v_cndmask_b32_e64 v103, v96, v190, s[6:7]
	ds_read_b128 v[72:75], v200
	ds_read_b128 v[84:87], v200 offset:128
	ds_read_b128 v[88:91], v200 offset:256
	ds_read_b128 v[92:95], v200 offset:384
	ds_read_b128 v[64:67], v200 offset:512
	ds_read_b128 v[68:71], v200 offset:640
	ds_read_b128 v[76:79], v200 offset:768
	ds_read_b128 v[80:83], v200 offset:896
	s_waitcnt vmcnt(4)
	v_mov_b32_e32 v104, v242
	v_mov_b32_e32 v105, v243
	v_mov_b32_e32 v106, v244
	v_mov_b32_e32 v107, v245
	v_mov_b32_e32 v108, v246
	v_mov_b32_e32 v109, v247
	v_mov_b32_e32 v110, v248
	v_mov_b32_e32 v111, v249
	v_ffbh_u32_e32 v98, v105
	v_ffbh_u32_e32 v100, v107
	v_ffbh_u32_e32 v102, v109
	v_min_u32_e32 v98, 32, v98
	v_min_u32_e32 v100, 32, v100
	v_min_u32_e32 v102, 32, v102
	v_lshlrev_b64 v[104:105], v98, v[104:105]
	v_ffbh_u32_e32 v114, v111
	v_lshlrev_b64 v[106:107], v100, v[106:107]
	v_lshlrev_b64 v[108:109], v102, v[108:109]
	v_min_u32_e32 v104, 1, v104
	v_min_u32_e32 v114, 32, v114
	v_min_u32_e32 v106, 1, v106
	v_min_u32_e32 v108, 1, v108
	v_or_b32_e32 v104, v105, v104
	v_lshlrev_b64 v[110:111], v114, v[110:111]
	v_or_b32_e32 v105, v107, v106
	v_or_b32_e32 v106, v109, v108
	v_cvt_f32_u32_e32 v104, v104
	v_min_u32_e32 v110, 1, v110
	v_cvt_f32_u32_e32 v105, v105
	v_cvt_f32_u32_e32 v106, v106
	v_or_b32_e32 v107, v111, v110
	v_sub_u32_e32 v98, 32, v98
	v_cvt_f32_u32_e32 v107, v107
	v_sub_u32_e32 v100, 32, v100
	v_sub_u32_e32 v102, 32, v102
	v_ldexp_f32 v98, v104, v98
	v_ldexp_f32 v100, v105, v100
	v_ldexp_f32 v102, v106, v102
	v_fmamk_f32 v98, v98, 0x30800000, v203
	v_sub_u32_e32 v114, 32, v114
	v_fmamk_f32 v100, v100, 0x30800000, v203
	v_fmamk_f32 v102, v102, 0x30800000, v203
	v_mul_f32_e32 v105, 0x4b800000, v98
	v_cmp_gt_f32_e32 vcc, s52, v98
	v_ldexp_f32 v104, v107, v114
	v_mul_f32_e32 v106, 0x4b800000, v100
	v_mul_f32_e32 v107, 0x4b800000, v102
	v_cndmask_b32_e32 v98, v98, v105, vcc
	v_cmp_gt_f32_e64 s[10:11], s52, v100
	v_cmp_gt_f32_e64 s[12:13], s52, v102
	v_fmamk_f32 v104, v104, 0x30800000, v203
	v_cndmask_b32_e64 v100, v100, v106, s[10:11]
	v_cndmask_b32_e64 v102, v102, v107, s[12:13]
	v_rsq_f32_e32 v98, v98
	v_mul_f32_e32 v108, 0x4b800000, v104
	v_cmp_gt_f32_e64 s[14:15], s52, v104
	v_rsq_f32_e32 v100, v100
	v_rsq_f32_e32 v102, v102
	v_cndmask_b32_e64 v104, v104, v108, s[14:15]
	v_rsq_f32_e32 v104, v104
	v_mul_f32_e32 v105, 0x45800000, v98
	v_mul_f32_e32 v106, 0x45800000, v100
	v_mul_f32_e32 v107, 0x45800000, v102
	v_cndmask_b32_e32 v98, v98, v105, vcc
	v_cmp_lt_i32_e32 vcc, -1, v96
	v_cndmask_b32_e64 v100, v100, v106, s[10:11]
	v_cndmask_b32_e64 v105, v102, v107, s[12:13]
	v_cndmask_b32_e32 v102, 0, v98, vcc
	v_cmp_lt_i32_e32 vcc, s53, v96
	v_mul_f32_e32 v108, 0x45800000, v104
	v_cndmask_b32_e64 v104, v104, v108, s[14:15]
	v_cndmask_b32_e32 v100, 0, v100, vcc
	v_cmp_lt_i32_e32 vcc, s54, v96
	v_pk_mul_f32 v[60:61], v[60:61], v[102:103] op_sel_hi:[1,0]
	v_pk_mul_f32 v[56:57], v[56:57], v[102:103] op_sel_hi:[1,0]
	v_cndmask_b32_e32 v98, 0, v105, vcc
	v_cmp_lt_i32_e32 vcc, s55, v96
	v_cndmask_b32_e32 v96, 0, v104, vcc
	v_pk_mul_f32 v[108:109], v[32:33], v[96:97] op_sel_hi:[1,0]
	v_pk_mul_f32 v[104:105], v[40:41], v[98:99] op_sel_hi:[1,0]
	s_waitcnt lgkmcnt(6)
; #define LAS __attribute__((address_space(3)))
; DI unsigned pk2(float lo, float hi) { f32x2 v = {lo, hi}; bf16x2_t b = __builtin_convertvector(v, bf16x2_t); return __builtin_bit_cast(unsigned, b); }
;     DI void operator()(const AccT& acc, const Unit& u, int wr, int wc, int fr, int fq) const {
;     ...
;                     const f32x2 bg = *(const LAS f32x2*)(P + lc + 2 * jp), g0 = *(const LAS f32x2*)(P + 32 + lc + 2 * jp), g1 = *(const LAS f32x2*)(P + 64 + lc + 2 * jp), g2 = *(const LAS f32x2*)(P + 96 + lc + 2 * jp);
;                     const f32x2 bv = *(const LAS f32x2*)(P + 128 + lc + 2 * jp), v0 = *(const LAS f32x2*)(P + 160 + lc + 2 * jp), v1 = *(const LAS f32x2*)(P + 192 + lc + 2 * jp), v2 = *(const LAS f32x2*)(P + 224 + lc + 2 * jp);
;                     f32x2 G[4], V[4];
; #pragma unroll
;                     for (int m = 0; m < 4; ++m) { G[m] = (f32x2){acc[ai][0][m][n][2 * jp], acc[ai][0][m][n][2 * jp + 1]} * rs[m]; V[m] = (f32x2){acc[ai][1][m][n][2 * jp], acc[ai][1][m][n][2 * jp + 1]} * rs[m]; }
; #pragma unroll
;                     for (int m = 0; m < 4; ++m) {
;                         const f32x2 zz = {0.f, 0.f}; const f32x2 Gp = m ? G[m - 1] : zz, Vp = m ? V[m - 1] : zz;
;                         const f32x2 gp1 = {dpp_prev1(G[m].x, Gp.x), dpp_prev1(G[m].y, Gp.y)}, gp2 = {dpp_prev2(G[m].x, Gp.x), dpp_prev2(G[m].y, Gp.y)};
;                         const f32x2 vp1 = {dpp_prev1(V[m].x, Vp.x), dpp_prev1(V[m].y, Vp.y)}, vp2 = {dpp_prev2(V[m].x, Vp.x), dpp_prev2(V[m].y, Vp.y)};
;                         const f32x2 gc = bg + g0 * gp2 + g1 * gp1 + g2 * G[m];
;                         const f32x2 vc = bv + v0 * vp2 + v1 * vp1 + v2 * V[m];
;                         const f32x2 xe = gc * (-LOG2E);
;                         f32x2 dn = {__builtin_amdgcn_exp2f(xe.x), __builtin_amdgcn_exp2f(xe.y)}; dn = dn + 1.0f;
;                         const f32x2 rc = {__builtin_amdgcn_rcpf(dn.x), __builtin_amdgcn_rcpf(dn.y)};
;                         const f32x2 rr = gc * rc * vc;
;                         wpk[m][jp] = pk2(rr.x, rr.y); }
	s_waitcnt lgkmcnt(5)
	s_waitcnt lgkmcnt(4)
	v_pk_fma_f32 v[32:33], v[92:93], v[60:61], v[72:73]
	v_fmac_f32_dpp v32, v60, v84 row_shr:2 row_mask:0xf bank_mask:0xf
	v_fmac_f32_dpp v33, v61, v85 row_shr:2 row_mask:0xf bank_mask:0xf
	v_fmac_f32_dpp v32, v60, v88 row_shr:1 row_mask:0xf bank_mask:0xf
	v_fmac_f32_dpp v33, v61, v89 row_shr:1 row_mask:0xf bank_mask:0xf
	v_pk_mul_f32 v[106:107], v[36:37], v[96:97] op_sel_hi:[1,0]
	v_pk_mul_f32 v[110:111], v[32:33], s[0:1] op_sel_hi:[1,0]
	v_exp_f32_e32 v110, v110
	v_exp_f32_e32 v111, v111
	s_nop 0
	v_pk_add_f32 v[110:111], v[110:111], 1.0 op_sel_hi:[1,0]
	v_rcp_f32_e32 v110, v110
	v_rcp_f32_e32 v111, v111
	s_waitcnt lgkmcnt(2)
	v_pk_mul_f32 v[52:53], v[52:53], v[100:101] op_sel_hi:[1,0]
	s_waitcnt lgkmcnt(1)
	v_pk_mul_f32 v[32:33], v[32:33], v[110:111]
	s_waitcnt lgkmcnt(0)
	v_pk_fma_f32 v[36:37], v[80:81], v[56:57], v[64:65]
	v_fmac_f32_dpp v36, v56, v68 row_shr:2 row_mask:0xf bank_mask:0xf
	v_fmac_f32_dpp v37, v57, v69 row_shr:2 row_mask:0xf bank_mask:0xf
	v_fmac_f32_dpp v36, v56, v76 row_shr:1 row_mask:0xf bank_mask:0xf
	v_fmac_f32_dpp v37, v57, v77 row_shr:1 row_mask:0xf bank_mask:0xf
	v_pk_mul_f32 v[32:33], v[36:37], v[32:33]
	v_pk_fma_f32 v[36:37], v[92:93], v[52:53], v[72:73]
	v_fmac_f32_dpp v36, v52, v84 row_shr:2 row_mask:0xf bank_mask:0xf
	v_fmac_f32_dpp v36, v60, v84 row_shl:14 row_mask:0xf bank_mask:0xf
	v_fmac_f32_dpp v37, v53, v85 row_shr:2 row_mask:0xf bank_mask:0xf
	v_fmac_f32_dpp v37, v61, v85 row_shl:14 row_mask:0xf bank_mask:0xf
	v_fmac_f32_dpp v36, v52, v88 row_shr:1 row_mask:0xf bank_mask:0xf
	v_fmac_f32_dpp v36, v60, v88 row_shl:15 row_mask:0xf bank_mask:0xf
	v_fmac_f32_dpp v37, v53, v89 row_shr:1 row_mask:0xf bank_mask:0xf
	v_fmac_f32_dpp v37, v61, v89 row_shl:15 row_mask:0xf bank_mask:0xf
	v_pk_mul_f32 v[48:49], v[48:49], v[100:101] op_sel_hi:[1,0]
	v_pk_mul_f32 v[40:41], v[36:37], s[0:1] op_sel_hi:[1,0]
	v_exp_f32_e32 v40, v40
	v_exp_f32_e32 v41, v41
	s_nop 0
	v_pk_add_f32 v[40:41], v[40:41], 1.0 op_sel_hi:[1,0]
	v_rcp_f32_e32 v40, v40
	v_rcp_f32_e32 v41, v41
	s_nop 0
	v_pk_mul_f32 v[36:37], v[36:37], v[40:41]
	v_pk_mul_f32 v[44:45], v[44:45], v[98:99] op_sel_hi:[1,0]
	v_pk_fma_f32 v[110:111], v[80:81], v[48:49], v[64:65]
	v_fmac_f32_dpp v110, v48, v68 row_shr:2 row_mask:0xf bank_mask:0xf
	v_fmac_f32_dpp v110, v56, v68 row_shl:14 row_mask:0xf bank_mask:0xf
	v_fmac_f32_dpp v111, v49, v69 row_shr:2 row_mask:0xf bank_mask:0xf
	v_fmac_f32_dpp v111, v57, v69 row_shl:14 row_mask:0xf bank_mask:0xf
	v_fmac_f32_dpp v110, v48, v76 row_shr:1 row_mask:0xf bank_mask:0xf
	v_fmac_f32_dpp v110, v56, v76 row_shl:15 row_mask:0xf bank_mask:0xf
	v_fmac_f32_dpp v111, v49, v77 row_shr:1 row_mask:0xf bank_mask:0xf
	v_fmac_f32_dpp v111, v57, v77 row_shl:15 row_mask:0xf bank_mask:0xf
	v_mov_b64_e32 v[56:57], v[110:111]
	v_pk_mul_f32 v[36:37], v[56:57], v[36:37]
	v_pk_fma_f32 v[40:41], v[92:93], v[44:45], v[72:73]
	v_fmac_f32_dpp v40, v44, v84 row_shr:2 row_mask:0xf bank_mask:0xf
	v_fmac_f32_dpp v40, v52, v84 row_shl:14 row_mask:0xf bank_mask:0xf
	v_fmac_f32_dpp v41, v45, v85 row_shr:2 row_mask:0xf bank_mask:0xf
	v_fmac_f32_dpp v41, v53, v85 row_shl:14 row_mask:0xf bank_mask:0xf
	v_fmac_f32_dpp v40, v44, v88 row_shr:1 row_mask:0xf bank_mask:0xf
	v_fmac_f32_dpp v40, v52, v88 row_shl:15 row_mask:0xf bank_mask:0xf
	v_fmac_f32_dpp v41, v45, v89 row_shr:1 row_mask:0xf bank_mask:0xf
	v_fmac_f32_dpp v41, v53, v89 row_shl:15 row_mask:0xf bank_mask:0xf
	v_pk_mul_f32 v[56:57], v[40:41], s[0:1] op_sel_hi:[1,0]
	v_exp_f32_e32 v56, v56
	v_exp_f32_e32 v57, v57
	v_mov_b32_dpp v52, v48 row_ror:1 row_mask:0xf bank_mask:0xf
	v_mov_b32_dpp v53, v49 row_ror:1 row_mask:0xf bank_mask:0xf
	v_mov_b32_dpp v60, v48 row_ror:2 row_mask:0xf bank_mask:0xf
	v_mov_b32_dpp v61, v49 row_ror:2 row_mask:0xf bank_mask:0xf
	v_pk_add_f32 v[48:49], v[56:57], 1.0 op_sel_hi:[1,0]
	v_mov_b32_dpp v60, v104 row_shr:2 row_mask:0xf bank_mask:0xf
	v_rcp_f32_e32 v48, v48
	v_rcp_f32_e32 v49, v49
	v_mov_b32_dpp v61, v105 row_shr:2 row_mask:0xf bank_mask:0xf
	v_mov_b32_dpp v52, v104 row_shr:1 row_mask:0xf bank_mask:0xf
	v_mov_b32_dpp v53, v105 row_shr:1 row_mask:0xf bank_mask:0xf
	v_pk_fma_f32 v[56:57], v[68:69], v[60:61], v[64:65]
	v_pk_mul_f32 v[40:41], v[40:41], v[48:49]
	v_pk_fma_f32 v[52:53], v[76:77], v[52:53], v[56:57]
	v_pk_fma_f32 v[52:53], v[80:81], v[104:105], v[52:53]
	v_pk_mul_f32 v[40:41], v[52:53], v[40:41]
	v_pk_fma_f32 v[48:49], v[92:93], v[106:107], v[72:73]
	v_fmac_f32_dpp v48, v106, v84 row_shr:2 row_mask:0xf bank_mask:0xf
	v_fmac_f32_dpp v48, v44, v84 row_shl:14 row_mask:0xf bank_mask:0xf
	v_fmac_f32_dpp v49, v107, v85 row_shr:2 row_mask:0xf bank_mask:0xf
	v_fmac_f32_dpp v49, v45, v85 row_shl:14 row_mask:0xf bank_mask:0xf
	v_fmac_f32_dpp v48, v106, v88 row_shr:1 row_mask:0xf bank_mask:0xf
	v_fmac_f32_dpp v48, v44, v88 row_shl:15 row_mask:0xf bank_mask:0xf
	v_fmac_f32_dpp v49, v107, v89 row_shr:1 row_mask:0xf bank_mask:0xf
	v_fmac_f32_dpp v49, v45, v89 row_shl:15 row_mask:0xf bank_mask:0xf
	v_pk_mul_f32 v[52:53], v[48:49], s[0:1] op_sel_hi:[1,0]
	v_exp_f32_e32 v52, v52
	v_exp_f32_e32 v53, v53
	s_nop 0
	v_pk_add_f32 v[52:53], v[52:53], 1.0 op_sel_hi:[1,0]
	v_rcp_f32_e32 v52, v52
	v_rcp_f32_e32 v53, v53
	s_nop 0
	v_pk_mul_f32 v[48:49], v[48:49], v[52:53]
	v_pk_mul_f32 v[52:53], v[58:59], v[102:103] op_sel_hi:[1,0]
	v_pk_fma_f32 v[44:45], v[80:81], v[108:109], v[64:65]
	v_fmac_f32_dpp v44, v108, v68 row_shr:2 row_mask:0xf bank_mask:0xf
	v_fmac_f32_dpp v44, v104, v68 row_shl:14 row_mask:0xf bank_mask:0xf
	v_fmac_f32_dpp v45, v109, v69 row_shr:2 row_mask:0xf bank_mask:0xf
	v_fmac_f32_dpp v45, v105, v69 row_shl:14 row_mask:0xf bank_mask:0xf
; #define LAS __attribute__((address_space(3)))
; DI unsigned pk2(float lo, float hi) { f32x2 v = {lo, hi}; bf16x2_t b = __builtin_convertvector(v, bf16x2_t); return __builtin_bit_cast(unsigned, b); }
;     DI void operator()(const AccT& acc, const Unit& u, int wr, int wc, int fr, int fq) const {
;     ...
;                     const f32x2 bg = *(const LAS f32x2*)(P + lc + 2 * jp), g0 = *(const LAS f32x2*)(P + 32 + lc + 2 * jp), g1 = *(const LAS f32x2*)(P + 64 + lc + 2 * jp), g2 = *(const LAS f32x2*)(P + 96 + lc + 2 * jp);
;                     const f32x2 bv = *(const LAS f32x2*)(P + 128 + lc + 2 * jp), v0 = *(const LAS f32x2*)(P + 160 + lc + 2 * jp), v1 = *(const LAS f32x2*)(P + 192 + lc + 2 * jp), v2 = *(const LAS f32x2*)(P + 224 + lc + 2 * jp);
;                     f32x2 G[4], V[4];
; #pragma unroll
;                     for (int m = 0; m < 4; ++m) { G[m] = (f32x2){acc[ai][0][m][n][2 * jp], acc[ai][0][m][n][2 * jp + 1]} * rs[m]; V[m] = (f32x2){acc[ai][1][m][n][2 * jp], acc[ai][1][m][n][2 * jp + 1]} * rs[m]; }
; #pragma unroll
;                     for (int m = 0; m < 4; ++m) {
;                         const f32x2 zz = {0.f, 0.f}; const f32x2 Gp = m ? G[m - 1] : zz, Vp = m ? V[m - 1] : zz;
;                         const f32x2 gp1 = {dpp_prev1(G[m].x, Gp.x), dpp_prev1(G[m].y, Gp.y)}, gp2 = {dpp_prev2(G[m].x, Gp.x), dpp_prev2(G[m].y, Gp.y)};
;                         const f32x2 vp1 = {dpp_prev1(V[m].x, Vp.x), dpp_prev1(V[m].y, Vp.y)}, vp2 = {dpp_prev2(V[m].x, Vp.x), dpp_prev2(V[m].y, Vp.y)};
;                         const f32x2 gc = bg + g0 * gp2 + g1 * gp1 + g2 * G[m];
;                         const f32x2 vc = bv + v0 * vp2 + v1 * vp1 + v2 * V[m];
;                         const f32x2 xe = gc * (-LOG2E);
;                         f32x2 dn = {__builtin_amdgcn_exp2f(xe.x), __builtin_amdgcn_exp2f(xe.y)}; dn = dn + 1.0f;
;                         const f32x2 rc = {__builtin_amdgcn_rcpf(dn.x), __builtin_amdgcn_rcpf(dn.y)};
;                         const f32x2 rr = gc * rc * vc;
;                         wpk[m][jp] = pk2(rr.x, rr.y); }
	v_fmac_f32_dpp v44, v108, v76 row_shr:1 row_mask:0xf bank_mask:0xf
	v_fmac_f32_dpp v44, v104, v76 row_shl:15 row_mask:0xf bank_mask:0xf
	v_fmac_f32_dpp v45, v109, v77 row_shr:1 row_mask:0xf bank_mask:0xf
	v_fmac_f32_dpp v45, v105, v77 row_shl:15 row_mask:0xf bank_mask:0xf
	v_pk_mul_f32 v[44:45], v[44:45], v[48:49]
	v_pk_mul_f32 v[48:49], v[62:63], v[102:103] op_sel_hi:[1,0]
	v_pk_fma_f32 v[56:57], v[48:49], v[94:95], v[74:75]
	s_nop 1
	v_fmac_f32_dpp v56, v48, v86 row_shr:2 row_mask:0xf bank_mask:0xf
	v_fmac_f32_dpp v57, v49, v87 row_shr:2 row_mask:0xf bank_mask:0xf
	v_fmac_f32_dpp v56, v48, v90 row_shr:1 row_mask:0xf bank_mask:0xf
	v_fmac_f32_dpp v57, v49, v91 row_shr:1 row_mask:0xf bank_mask:0xf
	v_pk_mul_f32 v[58:59], v[56:57], s[0:1] op_sel_hi:[1,0]
	v_exp_f32_e32 v58, v58
	v_exp_f32_e32 v59, v59
	s_nop 0
	v_pk_add_f32 v[58:59], v[58:59], 1.0 op_sel_hi:[1,0]
	v_rcp_f32_e32 v58, v58
	v_rcp_f32_e32 v59, v59
	v_cvt_pk_bf16_f32 v236, v32, v33
	v_pk_mul_f32 v[56:57], v[56:57], v[58:59]
	v_pk_fma_f32 v[60:61], v[52:53], v[82:83], v[66:67]
	v_fmac_f32_dpp v60, v52, v70 row_shr:2 row_mask:0xf bank_mask:0xf
	v_fmac_f32_dpp v61, v53, v71 row_shr:2 row_mask:0xf bank_mask:0xf
	v_fmac_f32_dpp v60, v52, v78 row_shr:1 row_mask:0xf bank_mask:0xf
	v_fmac_f32_dpp v61, v53, v79 row_shr:1 row_mask:0xf bank_mask:0xf
	v_pk_mul_f32 v[56:57], v[60:61], v[56:57]
	v_pk_mul_f32 v[54:55], v[54:55], v[100:101] op_sel_hi:[1,0]
	v_cvt_pk_bf16_f32 v237, v56, v57
	v_pk_fma_f32 v[56:57], v[54:55], v[94:95], v[74:75]
	v_fmac_f32_dpp v56, v54, v86 row_shr:2 row_mask:0xf bank_mask:0xf
	v_fmac_f32_dpp v56, v48, v86 row_shl:14 row_mask:0xf bank_mask:0xf
	v_fmac_f32_dpp v57, v55, v87 row_shr:2 row_mask:0xf bank_mask:0xf
	v_fmac_f32_dpp v57, v49, v87 row_shl:14 row_mask:0xf bank_mask:0xf
	v_fmac_f32_dpp v56, v54, v90 row_shr:1 row_mask:0xf bank_mask:0xf
	v_fmac_f32_dpp v56, v48, v90 row_shl:15 row_mask:0xf bank_mask:0xf
	v_fmac_f32_dpp v57, v55, v91 row_shr:1 row_mask:0xf bank_mask:0xf
	v_fmac_f32_dpp v57, v49, v91 row_shl:15 row_mask:0xf bank_mask:0xf
	v_pk_mul_f32 v[58:59], v[56:57], s[0:1] op_sel_hi:[1,0]
	v_exp_f32_e32 v58, v58
	v_exp_f32_e32 v59, v59
	v_mov_b32_dpp v48, v52 row_ror:1 row_mask:0xf bank_mask:0xf
	v_mov_b32_dpp v49, v53 row_ror:1 row_mask:0xf bank_mask:0xf
	v_mov_b32_dpp v60, v52 row_ror:2 row_mask:0xf bank_mask:0xf
	v_mov_b32_dpp v61, v53 row_ror:2 row_mask:0xf bank_mask:0xf
	v_pk_add_f32 v[52:53], v[58:59], 1.0 op_sel_hi:[1,0]
	v_pk_mul_f32 v[50:51], v[50:51], v[100:101] op_sel_hi:[1,0]
	v_rcp_f32_e32 v52, v52
	v_rcp_f32_e32 v53, v53
	v_mov_b32_dpp v60, v50 row_shr:2 row_mask:0xf bank_mask:0xf
	v_mov_b32_dpp v61, v51 row_shr:2 row_mask:0xf bank_mask:0xf
	v_mov_b32_dpp v48, v50 row_shr:1 row_mask:0xf bank_mask:0xf
	v_mov_b32_dpp v49, v51 row_shr:1 row_mask:0xf bank_mask:0xf
	v_pk_fma_f32 v[58:59], v[70:71], v[60:61], v[66:67]
	v_pk_mul_f32 v[52:53], v[56:57], v[52:53]
	v_pk_fma_f32 v[48:49], v[78:79], v[48:49], v[58:59]
	v_cvt_pk_bf16_f32 v244, v36, v37
	v_pk_fma_f32 v[48:49], v[50:51], v[82:83], v[48:49]
	v_pk_mul_f32 v[46:47], v[46:47], v[98:99] op_sel_hi:[1,0]
	v_pk_mul_f32 v[48:49], v[48:49], v[52:53]
	v_cvt_pk_bf16_f32 v245, v48, v49
	v_pk_fma_f32 v[48:49], v[46:47], v[94:95], v[74:75]
	v_fmac_f32_dpp v48, v46, v86 row_shr:2 row_mask:0xf bank_mask:0xf
	v_fmac_f32_dpp v48, v54, v86 row_shl:14 row_mask:0xf bank_mask:0xf
	v_fmac_f32_dpp v49, v47, v87 row_shr:2 row_mask:0xf bank_mask:0xf
	v_fmac_f32_dpp v49, v55, v87 row_shl:14 row_mask:0xf bank_mask:0xf
	v_fmac_f32_dpp v48, v46, v90 row_shr:1 row_mask:0xf bank_mask:0xf
	v_fmac_f32_dpp v48, v54, v90 row_shl:15 row_mask:0xf bank_mask:0xf
	v_fmac_f32_dpp v49, v47, v91 row_shr:1 row_mask:0xf bank_mask:0xf
	v_fmac_f32_dpp v49, v55, v91 row_shl:15 row_mask:0xf bank_mask:0xf
	v_pk_mul_f32 v[52:53], v[48:49], s[0:1] op_sel_hi:[1,0]
	v_exp_f32_e32 v52, v52
	v_exp_f32_e32 v53, v53
	v_mov_b32_dpp v54, v50 row_ror:1 row_mask:0xf bank_mask:0xf
	v_mov_b32_dpp v55, v51 row_ror:1 row_mask:0xf bank_mask:0xf
	v_mov_b32_dpp v56, v50 row_ror:2 row_mask:0xf bank_mask:0xf
	v_mov_b32_dpp v57, v51 row_ror:2 row_mask:0xf bank_mask:0xf
	v_pk_add_f32 v[50:51], v[52:53], 1.0 op_sel_hi:[1,0]
	v_pk_mul_f32 v[42:43], v[42:43], v[98:99] op_sel_hi:[1,0]
	v_rcp_f32_e32 v50, v50
	v_rcp_f32_e32 v51, v51
	v_mov_b32_dpp v56, v42 row_shr:2 row_mask:0xf bank_mask:0xf
	v_mov_b32_dpp v57, v43 row_shr:2 row_mask:0xf bank_mask:0xf
	v_mov_b32_dpp v54, v42 row_shr:1 row_mask:0xf bank_mask:0xf
	v_mov_b32_dpp v55, v43 row_shr:1 row_mask:0xf bank_mask:0xf
	v_pk_fma_f32 v[52:53], v[70:71], v[56:57], v[66:67]
	v_pk_mul_f32 v[48:49], v[48:49], v[50:51]
	v_pk_fma_f32 v[52:53], v[78:79], v[54:55], v[52:53]
	v_pk_fma_f32 v[52:53], v[42:43], v[82:83], v[52:53]
	v_pk_mul_f32 v[48:49], v[52:53], v[48:49]
	v_cvt_pk_bf16_f32 v248, v40, v41
	v_pk_mul_f32 v[38:39], v[38:39], v[96:97] op_sel_hi:[1,0]
	v_cvt_pk_bf16_f32 v249, v48, v49
	v_pk_fma_f32 v[50:51], v[38:39], v[94:95], v[74:75]
	v_fmac_f32_dpp v50, v38, v86 row_shr:2 row_mask:0xf bank_mask:0xf
	v_fmac_f32_dpp v50, v46, v86 row_shl:14 row_mask:0xf bank_mask:0xf
	v_fmac_f32_dpp v51, v39, v87 row_shr:2 row_mask:0xf bank_mask:0xf
	v_fmac_f32_dpp v51, v47, v87 row_shl:14 row_mask:0xf bank_mask:0xf
	v_fmac_f32_dpp v50, v38, v90 row_shr:1 row_mask:0xf bank_mask:0xf
	v_fmac_f32_dpp v50, v46, v90 row_shl:15 row_mask:0xf bank_mask:0xf
	v_fmac_f32_dpp v51, v39, v91 row_shr:1 row_mask:0xf bank_mask:0xf
	v_fmac_f32_dpp v51, v47, v91 row_shl:15 row_mask:0xf bank_mask:0xf
	v_mov_b64_e32 v[38:39], v[50:51]
	v_pk_mul_f32 v[48:49], v[38:39], s[0:1] op_sel_hi:[1,0]
	v_exp_f32_e32 v48, v48
	v_exp_f32_e32 v49, v49
; #define LAS __attribute__((address_space(3)))
; DI unsigned pk2(float lo, float hi) { f32x2 v = {lo, hi}; bf16x2_t b = __builtin_convertvector(v, bf16x2_t); return __builtin_bit_cast(unsigned, b); }
;     DI void operator()(const AccT& acc, const Unit& u, int wr, int wc, int fr, int fq) const {
;     ...
;                     const f32x2 bg = *(const LAS f32x2*)(P + lc + 2 * jp), g0 = *(const LAS f32x2*)(P + 32 + lc + 2 * jp), g1 = *(const LAS f32x2*)(P + 64 + lc + 2 * jp), g2 = *(const LAS f32x2*)(P + 96 + lc + 2 * jp);
;                     const f32x2 bv = *(const LAS f32x2*)(P + 128 + lc + 2 * jp), v0 = *(const LAS f32x2*)(P + 160 + lc + 2 * jp), v1 = *(const LAS f32x2*)(P + 192 + lc + 2 * jp), v2 = *(const LAS f32x2*)(P + 224 + lc + 2 * jp);
;                     f32x2 G[4], V[4];
; #pragma unroll
;                     for (int m = 0; m < 4; ++m) { G[m] = (f32x2){acc[ai][0][m][n][2 * jp], acc[ai][0][m][n][2 * jp + 1]} * rs[m]; V[m] = (f32x2){acc[ai][1][m][n][2 * jp], acc[ai][1][m][n][2 * jp + 1]} * rs[m]; }
; #pragma unroll
;                     for (int m = 0; m < 4; ++m) {
;                         const f32x2 zz = {0.f, 0.f}; const f32x2 Gp = m ? G[m - 1] : zz, Vp = m ? V[m - 1] : zz;
;                         const f32x2 gp1 = {dpp_prev1(G[m].x, Gp.x), dpp_prev1(G[m].y, Gp.y)}, gp2 = {dpp_prev2(G[m].x, Gp.x), dpp_prev2(G[m].y, Gp.y)};
;                         const f32x2 vp1 = {dpp_prev1(V[m].x, Vp.x), dpp_prev1(V[m].y, Vp.y)}, vp2 = {dpp_prev2(V[m].x, Vp.x), dpp_prev2(V[m].y, Vp.y)};
;                         const f32x2 gc = bg + g0 * gp2 + g1 * gp1 + g2 * G[m];
;                         const f32x2 vc = bv + v0 * vp2 + v1 * vp1 + v2 * V[m];
;                         const f32x2 xe = gc * (-LOG2E);
;                         f32x2 dn = {__builtin_amdgcn_exp2f(xe.x), __builtin_amdgcn_exp2f(xe.y)}; dn = dn + 1.0f;
;                         const f32x2 rc = {__builtin_amdgcn_rcpf(dn.x), __builtin_amdgcn_rcpf(dn.y)};
;                         const f32x2 rr = gc * rc * vc;
;                         wpk[m][jp] = pk2(rr.x, rr.y); }
;                 }
; #pragma unroll
;                 for (int m = 0; m < 4; ++m) { const int row = m ? tok0 + 16 * m : row0;
;                     *(u32x2*)(ACT + (size_t)row * 2816 + cl + 4 * n) = (u32x2){wpk[m][0], wpk[m][1]}; }
	v_mov_b32_dpp v46, v42 row_ror:1 row_mask:0xf bank_mask:0xf
	v_mov_b32_dpp v47, v43 row_ror:1 row_mask:0xf bank_mask:0xf
	v_mov_b32_dpp v52, v42 row_ror:2 row_mask:0xf bank_mask:0xf
	v_mov_b32_dpp v53, v43 row_ror:2 row_mask:0xf bank_mask:0xf
	v_pk_add_f32 v[42:43], v[48:49], 1.0 op_sel_hi:[1,0]
	v_pk_mul_f32 v[34:35], v[34:35], v[96:97] op_sel_hi:[1,0]
	v_rcp_f32_e32 v42, v42
	v_rcp_f32_e32 v43, v43
	v_mov_b32_dpp v52, v34 row_shr:2 row_mask:0xf bank_mask:0xf
	v_mov_b32_dpp v53, v35 row_shr:2 row_mask:0xf bank_mask:0xf
	v_mov_b32_dpp v46, v34 row_shr:1 row_mask:0xf bank_mask:0xf
	v_mov_b32_dpp v47, v35 row_shr:1 row_mask:0xf bank_mask:0xf
	v_pk_fma_f32 v[48:49], v[70:71], v[52:53], v[66:67]
	v_pk_mul_f32 v[38:39], v[38:39], v[42:43]
	v_pk_fma_f32 v[46:47], v[78:79], v[46:47], v[48:49]
	v_cvt_pk_bf16_f32 v252, v44, v45
	v_pk_fma_f32 v[34:35], v[34:35], v[82:83], v[46:47]
	s_nop 0
	v_pk_mul_f32 v[34:35], v[34:35], v[38:39]
	s_nop 0
	v_cvt_pk_bf16_f32 v253, v34, v35
	v_mad_i64_i32 v[34:35], s[10:11], v103, s48, v[128:129]
	v_lshl_add_u64 v[64:65], v[34:35], 0, v[130:131]
	v_mad_i64_i32 v[32:33], s[10:11], v97, s48, v[128:129]
	v_lshl_add_u64 v[66:67], v[32:33], 0, v[130:131]
	v_mad_i64_i32 v[32:33], s[10:11], v99, s48, v[128:129]
	v_lshl_add_u64 v[68:69], v[32:33], 0, v[130:131]
	v_mad_i64_i32 v[32:33], s[10:11], v101, s48, v[128:129]
	v_lshl_add_u64 v[70:71], v[32:33], 0, v[130:131]
	v_pk_mul_f32 v[30:31], v[30:31], v[102:103] op_sel_hi:[1,0]
	v_pk_mul_f32 v[22:23], v[22:23], v[100:101] op_sel_hi:[1,0]
	s_nop 0
	ds_read_b128 v[40:43], v200 offset:16
	ds_read_b128 v[52:55], v200 offset:144
	ds_read_b128 v[56:59], v200 offset:272
	ds_read_b128 v[60:63], v200 offset:400
	ds_read_b128 v[32:35], v200 offset:528
	ds_read_b128 v[36:39], v200 offset:656
	ds_read_b128 v[44:47], v200 offset:784
	ds_read_b128 v[48:51], v200 offset:912
	s_waitcnt lgkmcnt(6)
	v_pk_mul_f32 v[28:29], v[28:29], v[102:103] op_sel_hi:[1,0]
	v_pk_mul_f32 v[24:25], v[24:25], v[102:103] op_sel_hi:[1,0]
	v_pk_mul_f32 v[20:21], v[20:21], v[100:101] op_sel_hi:[1,0]
	v_pk_mul_f32 v[16:17], v[16:17], v[100:101] op_sel_hi:[1,0]
	v_pk_mul_f32 v[26:27], v[26:27], v[102:103] op_sel_hi:[1,0]
	v_pk_mul_f32 v[100:101], v[18:19], v[100:101] op_sel_hi:[1,0]
	s_waitcnt lgkmcnt(5)
	v_pk_mul_f32 v[76:77], v[12:13], v[98:99] op_sel_hi:[1,0]
	v_pk_mul_f32 v[72:73], v[8:9], v[98:99] op_sel_hi:[1,0]
	v_pk_mul_f32 v[14:15], v[14:15], v[98:99] op_sel_hi:[1,0]
	v_pk_mul_f32 v[10:11], v[10:11], v[98:99] op_sel_hi:[1,0]
	v_mov_b32_dpp v18, v22 row_ror:1 row_mask:0xf bank_mask:0xf
	v_mov_b32_dpp v19, v23 row_ror:1 row_mask:0xf bank_mask:0xf
	v_mov_b32_dpp v120, v22 row_ror:2 row_mask:0xf bank_mask:0xf
	v_mov_b32_dpp v121, v23 row_ror:2 row_mask:0xf bank_mask:0xf
	s_waitcnt lgkmcnt(4)
	v_pk_fma_f32 v[114:115], v[22:23], v[62:63], v[42:43]
	v_fmac_f32_dpp v114, v22, v54 row_shr:2 row_mask:0xf bank_mask:0xf
	v_fmac_f32_dpp v114, v30, v54 row_shl:14 row_mask:0xf bank_mask:0xf
	v_fmac_f32_dpp v115, v23, v55 row_shr:2 row_mask:0xf bank_mask:0xf
	v_fmac_f32_dpp v115, v31, v55 row_shl:14 row_mask:0xf bank_mask:0xf
	v_fmac_f32_dpp v114, v22, v58 row_shr:1 row_mask:0xf bank_mask:0xf
	v_fmac_f32_dpp v114, v30, v58 row_shl:15 row_mask:0xf bank_mask:0xf
	v_fmac_f32_dpp v115, v23, v59 row_shr:1 row_mask:0xf bank_mask:0xf
	v_fmac_f32_dpp v115, v31, v59 row_shl:15 row_mask:0xf bank_mask:0xf
	v_mov_b64_e32 v[22:23], v[114:115]
	v_pk_mul_f32 v[112:113], v[22:23], s[0:1] op_sel_hi:[1,0]
	v_exp_f32_e32 v112, v112
	v_exp_f32_e32 v113, v113
	v_pk_fma_f32 v[102:103], v[30:31], v[62:63], v[42:43]
	v_fmac_f32_dpp v102, v30, v54 row_shr:2 row_mask:0xf bank_mask:0xf
	v_fmac_f32_dpp v103, v31, v55 row_shr:2 row_mask:0xf bank_mask:0xf
	v_fmac_f32_dpp v102, v30, v58 row_shr:1 row_mask:0xf bank_mask:0xf
	v_fmac_f32_dpp v103, v31, v59 row_shr:1 row_mask:0xf bank_mask:0xf
	v_mov_b64_e32 v[30:31], v[102:103]
	v_pk_mul_f32 v[98:99], v[30:31], s[0:1] op_sel_hi:[1,0]
	v_pk_add_f32 v[112:113], v[112:113], 1.0 op_sel_hi:[1,0]
	v_exp_f32_e32 v98, v98
	v_exp_f32_e32 v99, v99
	v_rcp_f32_e32 v112, v112
	v_rcp_f32_e32 v113, v113
	s_waitcnt lgkmcnt(2)
	v_pk_add_f32 v[98:99], v[98:99], 1.0 op_sel_hi:[1,0]
	v_mov_b32_e32 v182, v183
	s_waitcnt lgkmcnt(1)
	v_rcp_f32_e32 v98, v98
	v_rcp_f32_e32 v99, v99
	v_pk_mul_f32 v[86:87], v[4:5], v[96:97] op_sel_hi:[1,0]
	v_mov_b32_e32 v12, v183
	v_mov_b32_e32 v13, v183
	v_mov_b32_e32 v4, v183
	v_mov_b32_e32 v5, v183
	v_mov_b32_e32 v180, v181
	v_mov_b32_dpp v182, v26 row_shr:2 row_mask:0xf bank_mask:0xf
	v_mov_b32_dpp v183, v27 row_shr:2 row_mask:0xf bank_mask:0xf
	v_mov_b32_dpp v122, v100 row_ror:1 row_mask:0xf bank_mask:0xf
	v_mov_b32_dpp v123, v101 row_ror:1 row_mask:0xf bank_mask:0xf
	v_mov_b32_dpp v124, v100 row_ror:2 row_mask:0xf bank_mask:0xf
	v_mov_b32_dpp v125, v101 row_ror:2 row_mask:0xf bank_mask:0xf
	s_waitcnt lgkmcnt(0)
; #define LAS __attribute__((address_space(3)))
; DI unsigned pk2(float lo, float hi) { f32x2 v = {lo, hi}; bf16x2_t b = __builtin_convertvector(v, bf16x2_t); return __builtin_bit_cast(unsigned, b); }
;     DI void operator()(const AccT& acc, const Unit& u, int wr, int wc, int fr, int fq) const {
;     ...
;                     const f32x2 bg = *(const LAS f32x2*)(P + lc + 2 * jp), g0 = *(const LAS f32x2*)(P + 32 + lc + 2 * jp), g1 = *(const LAS f32x2*)(P + 64 + lc + 2 * jp), g2 = *(const LAS f32x2*)(P + 96 + lc + 2 * jp);
;                     const f32x2 bv = *(const LAS f32x2*)(P + 128 + lc + 2 * jp), v0 = *(const LAS f32x2*)(P + 160 + lc + 2 * jp), v1 = *(const LAS f32x2*)(P + 192 + lc + 2 * jp), v2 = *(const LAS f32x2*)(P + 224 + lc + 2 * jp);
;                     f32x2 G[4], V[4];
; #pragma unroll
;                     for (int m = 0; m < 4; ++m) { G[m] = (f32x2){acc[ai][0][m][n][2 * jp], acc[ai][0][m][n][2 * jp + 1]} * rs[m]; V[m] = (f32x2){acc[ai][1][m][n][2 * jp], acc[ai][1][m][n][2 * jp + 1]} * rs[m]; }
; #pragma unroll
;                     for (int m = 0; m < 4; ++m) {
;                         const f32x2 zz = {0.f, 0.f}; const f32x2 Gp = m ? G[m - 1] : zz, Vp = m ? V[m - 1] : zz;
;                         const f32x2 gp1 = {dpp_prev1(G[m].x, Gp.x), dpp_prev1(G[m].y, Gp.y)}, gp2 = {dpp_prev2(G[m].x, Gp.x), dpp_prev2(G[m].y, Gp.y)};
;                         const f32x2 vp1 = {dpp_prev1(V[m].x, Vp.x), dpp_prev1(V[m].y, Vp.y)}, vp2 = {dpp_prev2(V[m].x, Vp.x), dpp_prev2(V[m].y, Vp.y)};
;                         const f32x2 gc = bg + g0 * gp2 + g1 * gp1 + g2 * G[m];
;                         const f32x2 vc = bv + v0 * vp2 + v1 * vp1 + v2 * V[m];
;                         const f32x2 xe = gc * (-LOG2E);
;                         f32x2 dn = {__builtin_amdgcn_exp2f(xe.x), __builtin_amdgcn_exp2f(xe.y)}; dn = dn + 1.0f;
;                         const f32x2 rc = {__builtin_amdgcn_rcpf(dn.x), __builtin_amdgcn_rcpf(dn.y)};
;                         const f32x2 rr = gc * rc * vc;
;                         wpk[m][jp] = pk2(rr.x, rr.y); }
	v_pk_fma_f32 v[118:119], v[100:101], v[50:51], v[34:35]
	v_fmac_f32_dpp v118, v100, v38 row_shr:2 row_mask:0xf bank_mask:0xf
	v_fmac_f32_dpp v118, v26, v38 row_shl:14 row_mask:0xf bank_mask:0xf
	v_fmac_f32_dpp v119, v101, v39 row_shr:2 row_mask:0xf bank_mask:0xf
	v_fmac_f32_dpp v119, v27, v39 row_shl:14 row_mask:0xf bank_mask:0xf
	v_fmac_f32_dpp v118, v100, v46 row_shr:1 row_mask:0xf bank_mask:0xf
	v_fmac_f32_dpp v118, v26, v46 row_shl:15 row_mask:0xf bank_mask:0xf
	v_fmac_f32_dpp v119, v101, v47 row_shr:1 row_mask:0xf bank_mask:0xf
	v_fmac_f32_dpp v119, v27, v47 row_shl:15 row_mask:0xf bank_mask:0xf
	v_mov_b64_e32 v[100:101], v[118:119]
	v_pk_mul_f32 v[22:23], v[22:23], v[112:113]
	v_pk_mul_f32 v[84:85], v[0:1], v[96:97] op_sel_hi:[1,0]
	v_mov_b32_e32 v8, v181
	v_mov_b32_e32 v9, v181
	v_mov_b32_e32 v0, v181
	v_mov_b32_e32 v1, v181
	v_mov_b32_dpp v180, v26 row_shr:1 row_mask:0xf bank_mask:0xf
	v_mov_b32_dpp v181, v27 row_shr:1 row_mask:0xf bank_mask:0xf
	v_pk_mul_f32 v[22:23], v[100:101], v[22:23]
	v_pk_fma_f32 v[100:101], v[38:39], v[182:183], v[34:35]
	v_pk_fma_f32 v[100:101], v[46:47], v[180:181], v[100:101]
	v_pk_fma_f32 v[26:27], v[26:27], v[50:51], v[100:101]
	v_pk_mul_f32 v[30:31], v[30:31], v[98:99]
	v_pk_mul_f32 v[26:27], v[26:27], v[30:31]
	v_mov_b32_dpp v12, v28 row_shr:2 row_mask:0xf bank_mask:0xf
	v_mov_b32_dpp v13, v29 row_shr:2 row_mask:0xf bank_mask:0xf
	v_pk_fma_f32 v[30:31], v[86:87], v[60:61], v[40:41]
	v_fmac_f32_dpp v30, v86, v52 row_shr:2 row_mask:0xf bank_mask:0xf
	v_fmac_f32_dpp v30, v76, v52 row_shl:14 row_mask:0xf bank_mask:0xf
	v_fmac_f32_dpp v31, v87, v53 row_shr:2 row_mask:0xf bank_mask:0xf
	v_fmac_f32_dpp v31, v77, v53 row_shl:14 row_mask:0xf bank_mask:0xf
	v_fmac_f32_dpp v30, v86, v56 row_shr:1 row_mask:0xf bank_mask:0xf
	v_fmac_f32_dpp v30, v76, v56 row_shl:15 row_mask:0xf bank_mask:0xf
	v_fmac_f32_dpp v31, v87, v57 row_shr:1 row_mask:0xf bank_mask:0xf
	v_fmac_f32_dpp v31, v77, v57 row_shl:15 row_mask:0xf bank_mask:0xf
	v_pk_mul_f32 v[86:87], v[30:31], s[0:1] op_sel_hi:[1,0]
	v_mov_b32_dpp v8, v28 row_shr:1 row_mask:0xf bank_mask:0xf
	v_mov_b32_dpp v9, v29 row_shr:1 row_mask:0xf bank_mask:0xf
	v_exp_f32_e32 v86, v86
	v_exp_f32_e32 v87, v87
	v_pk_fma_f32 v[12:13], v[52:53], v[12:13], v[40:41]
	v_mov_b32_dpp v120, v14 row_shr:2 row_mask:0xf bank_mask:0xf
	v_mov_b32_dpp v121, v15 row_shr:2 row_mask:0xf bank_mask:0xf
	v_pk_fma_f32 v[8:9], v[56:57], v[8:9], v[12:13]
	v_mov_b32_dpp v18, v14 row_shr:1 row_mask:0xf bank_mask:0xf
	v_mov_b32_dpp v19, v15 row_shr:1 row_mask:0xf bank_mask:0xf
	v_pk_fma_f32 v[120:121], v[54:55], v[120:121], v[42:43]
	v_pk_fma_f32 v[8:9], v[28:29], v[60:61], v[8:9]
	v_pk_fma_f32 v[18:19], v[58:59], v[18:19], v[120:121]
	v_pk_mul_f32 v[12:13], v[8:9], s[0:1] op_sel_hi:[1,0]
	v_pk_fma_f32 v[18:19], v[14:15], v[62:63], v[18:19]
	v_pk_add_f32 v[86:87], v[86:87], 1.0 op_sel_hi:[1,0]
	v_pk_fma_f32 v[92:93], v[76:77], v[60:61], v[40:41]
	v_fmac_f32_dpp v92, v76, v52 row_shr:2 row_mask:0xf bank_mask:0xf
	v_fmac_f32_dpp v92, v20, v52 row_shl:14 row_mask:0xf bank_mask:0xf
	v_fmac_f32_dpp v93, v77, v53 row_shr:2 row_mask:0xf bank_mask:0xf
	v_fmac_f32_dpp v93, v21, v53 row_shl:14 row_mask:0xf bank_mask:0xf
	v_fmac_f32_dpp v92, v76, v56 row_shr:1 row_mask:0xf bank_mask:0xf
	v_fmac_f32_dpp v92, v20, v56 row_shl:15 row_mask:0xf bank_mask:0xf
	v_fmac_f32_dpp v93, v77, v57 row_shr:1 row_mask:0xf bank_mask:0xf
	v_fmac_f32_dpp v93, v21, v57 row_shl:15 row_mask:0xf bank_mask:0xf
	v_mov_b64_e32 v[76:77], v[92:93]
	v_exp_f32_e32 v12, v12
	v_exp_f32_e32 v13, v13
	v_pk_mul_f32 v[120:121], v[18:19], s[0:1] op_sel_hi:[1,0]
	v_rcp_f32_e32 v86, v86
	v_rcp_f32_e32 v87, v87
	v_pk_mul_f32 v[88:89], v[76:77], s[0:1] op_sel_hi:[1,0]
	v_exp_f32_e32 v120, v120
	v_exp_f32_e32 v121, v121
	v_exp_f32_e32 v88, v88
	v_exp_f32_e32 v89, v89
	v_pk_mul_f32 v[2:3], v[2:3], v[96:97] op_sel_hi:[1,0]
	v_pk_mul_f32 v[6:7], v[6:7], v[96:97] op_sel_hi:[1,0]
	v_pk_add_f32 v[12:13], v[12:13], 1.0 op_sel_hi:[1,0]
	v_pk_mul_f32 v[30:31], v[30:31], v[86:87]
	v_pk_fma_f32 v[110:111], v[84:85], v[48:49], v[32:33]
	v_fmac_f32_dpp v110, v84, v36 row_shr:2 row_mask:0xf bank_mask:0xf
	v_fmac_f32_dpp v110, v72, v36 row_shl:14 row_mask:0xf bank_mask:0xf
	v_fmac_f32_dpp v111, v85, v37 row_shr:2 row_mask:0xf bank_mask:0xf
	v_fmac_f32_dpp v111, v73, v37 row_shl:14 row_mask:0xf bank_mask:0xf
	v_fmac_f32_dpp v110, v84, v44 row_shr:1 row_mask:0xf bank_mask:0xf
	v_fmac_f32_dpp v110, v72, v44 row_shl:15 row_mask:0xf bank_mask:0xf
	v_fmac_f32_dpp v111, v85, v45 row_shr:1 row_mask:0xf bank_mask:0xf
	v_fmac_f32_dpp v111, v73, v45 row_shl:15 row_mask:0xf bank_mask:0xf
	v_mov_b64_e32 v[84:85], v[110:111]
	v_rcp_f32_e32 v12, v12
	v_rcp_f32_e32 v13, v13
	v_mov_b32_dpp v4, v24 row_shr:2 row_mask:0xf bank_mask:0xf
	v_mov_b32_dpp v5, v25 row_shr:2 row_mask:0xf bank_mask:0xf
	v_pk_add_f32 v[120:121], v[120:121], 1.0 op_sel_hi:[1,0]
	v_pk_mul_f32 v[30:31], v[84:85], v[30:31]
	v_pk_add_f32 v[84:85], v[88:89], 1.0 op_sel_hi:[1,0]
	v_mov_b32_dpp v0, v24 row_shr:1 row_mask:0xf bank_mask:0xf
	v_mov_b32_dpp v1, v25 row_shr:1 row_mask:0xf bank_mask:0xf
	v_rcp_f32_e32 v120, v120
; #define LAS __attribute__((address_space(3)))
; DI unsigned pk2(float lo, float hi) { f32x2 v = {lo, hi}; bf16x2_t b = __builtin_convertvector(v, bf16x2_t); return __builtin_bit_cast(unsigned, b); }
;     DI void operator()(const AccT& acc, const Unit& u, int wr, int wc, int fr, int fq) const {
;     ...
;                     const f32x2 bg = *(const LAS f32x2*)(P + lc + 2 * jp), g0 = *(const LAS f32x2*)(P + 32 + lc + 2 * jp), g1 = *(const LAS f32x2*)(P + 64 + lc + 2 * jp), g2 = *(const LAS f32x2*)(P + 96 + lc + 2 * jp);
;                     const f32x2 bv = *(const LAS f32x2*)(P + 128 + lc + 2 * jp), v0 = *(const LAS f32x2*)(P + 160 + lc + 2 * jp), v1 = *(const LAS f32x2*)(P + 192 + lc + 2 * jp), v2 = *(const LAS f32x2*)(P + 224 + lc + 2 * jp);
;                     f32x2 G[4], V[4];
; #pragma unroll
;                     for (int m = 0; m < 4; ++m) { G[m] = (f32x2){acc[ai][0][m][n][2 * jp], acc[ai][0][m][n][2 * jp + 1]} * rs[m]; V[m] = (f32x2){acc[ai][1][m][n][2 * jp], acc[ai][1][m][n][2 * jp + 1]} * rs[m]; }
; #pragma unroll
;                     for (int m = 0; m < 4; ++m) {
;                         const f32x2 zz = {0.f, 0.f}; const f32x2 Gp = m ? G[m - 1] : zz, Vp = m ? V[m - 1] : zz;
;                         const f32x2 gp1 = {dpp_prev1(G[m].x, Gp.x), dpp_prev1(G[m].y, Gp.y)}, gp2 = {dpp_prev2(G[m].x, Gp.x), dpp_prev2(G[m].y, Gp.y)};
;                         const f32x2 vp1 = {dpp_prev1(V[m].x, Vp.x), dpp_prev1(V[m].y, Vp.y)}, vp2 = {dpp_prev2(V[m].x, Vp.x), dpp_prev2(V[m].y, Vp.y)};
;                         const f32x2 gc = bg + g0 * gp2 + g1 * gp1 + g2 * G[m];
;                         const f32x2 vc = bv + v0 * vp2 + v1 * vp1 + v2 * V[m];
;                         const f32x2 xe = gc * (-LOG2E);
;                         f32x2 dn = {__builtin_amdgcn_exp2f(xe.x), __builtin_amdgcn_exp2f(xe.y)}; dn = dn + 1.0f;
;                         const f32x2 rc = {__builtin_amdgcn_rcpf(dn.x), __builtin_amdgcn_rcpf(dn.y)};
;                         const f32x2 rr = gc * rc * vc;
;                         wpk[m][jp] = pk2(rr.x, rr.y); }
;                 }
; #pragma unroll
;                 for (int m = 0; m < 4; ++m) { const int row = m ? tok0 + 16 * m : row0;
;                     *(u32x2*)(ACT + (size_t)row * 2816 + cl + 4 * n) = (u32x2){wpk[m][0], wpk[m][1]}; }
	v_rcp_f32_e32 v121, v121
	v_rcp_f32_e32 v84, v84
	v_rcp_f32_e32 v85, v85
	v_pk_fma_f32 v[4:5], v[36:37], v[4:5], v[32:33]
	v_mov_b32_dpp v124, v10 row_shr:2 row_mask:0xf bank_mask:0xf
	v_mov_b32_dpp v125, v11 row_shr:2 row_mask:0xf bank_mask:0xf
	v_pk_fma_f32 v[0:1], v[44:45], v[0:1], v[4:5]
	v_mov_b32_dpp v122, v10 row_shr:1 row_mask:0xf bank_mask:0xf
	v_mov_b32_dpp v123, v11 row_shr:1 row_mask:0xf bank_mask:0xf
	v_pk_fma_f32 v[124:125], v[38:39], v[124:125], v[34:35]
	v_pk_fma_f32 v[0:1], v[24:25], v[48:49], v[0:1]
	v_pk_mul_f32 v[4:5], v[8:9], v[12:13]
	v_pk_fma_f32 v[122:123], v[46:47], v[122:123], v[124:125]
	v_pk_mul_f32 v[0:1], v[0:1], v[4:5]
	v_pk_fma_f32 v[122:123], v[10:11], v[50:51], v[122:123]
	v_pk_mul_f32 v[18:19], v[18:19], v[120:121]
	v_cvt_pk_bf16_f32 v239, v26, v27
	v_pk_fma_f32 v[94:95], v[72:73], v[48:49], v[32:33]
	v_fmac_f32_dpp v94, v72, v36 row_shr:2 row_mask:0xf bank_mask:0xf
	v_fmac_f32_dpp v94, v16, v36 row_shl:14 row_mask:0xf bank_mask:0xf
	v_fmac_f32_dpp v95, v73, v37 row_shr:2 row_mask:0xf bank_mask:0xf
	v_fmac_f32_dpp v95, v17, v37 row_shl:14 row_mask:0xf bank_mask:0xf
	v_fmac_f32_dpp v94, v72, v44 row_shr:1 row_mask:0xf bank_mask:0xf
	v_fmac_f32_dpp v94, v16, v44 row_shl:15 row_mask:0xf bank_mask:0xf
	v_fmac_f32_dpp v95, v73, v45 row_shr:1 row_mask:0xf bank_mask:0xf
	v_fmac_f32_dpp v95, v17, v45 row_shl:15 row_mask:0xf bank_mask:0xf
	v_mov_b64_e32 v[72:73], v[94:95]
	v_pk_mul_f32 v[76:77], v[76:77], v[84:85]
	v_cvt_pk_bf16_f32 v238, v0, v1
	v_pk_mul_f32 v[18:19], v[122:123], v[18:19]
	v_pk_mul_f32 v[72:73], v[72:73], v[76:77]
	v_cvt_pk_bf16_f32 v251, v18, v19
	v_cvt_pk_bf16_f32 v250, v72, v73
	v_pk_fma_f32 v[78:79], v[20:21], v[60:61], v[40:41]
	v_fmac_f32_dpp v78, v20, v52 row_shr:2 row_mask:0xf bank_mask:0xf
	v_fmac_f32_dpp v78, v28, v52 row_shl:14 row_mask:0xf bank_mask:0xf
	v_fmac_f32_dpp v79, v21, v53 row_shr:2 row_mask:0xf bank_mask:0xf
	v_fmac_f32_dpp v79, v29, v53 row_shl:14 row_mask:0xf bank_mask:0xf
	v_fmac_f32_dpp v78, v20, v56 row_shr:1 row_mask:0xf bank_mask:0xf
	v_fmac_f32_dpp v78, v28, v56 row_shl:15 row_mask:0xf bank_mask:0xf
	v_fmac_f32_dpp v79, v21, v57 row_shr:1 row_mask:0xf bank_mask:0xf
	v_fmac_f32_dpp v79, v29, v57 row_shl:15 row_mask:0xf bank_mask:0xf
	v_mov_b64_e32 v[20:21], v[78:79]
	v_pk_fma_f32 v[0:1], v[6:7], v[62:63], v[42:43]
	v_fmac_f32_dpp v0, v6, v54 row_shr:2 row_mask:0xf bank_mask:0xf
	v_fmac_f32_dpp v0, v14, v54 row_shl:14 row_mask:0xf bank_mask:0xf
	v_fmac_f32_dpp v1, v7, v55 row_shr:2 row_mask:0xf bank_mask:0xf
	v_fmac_f32_dpp v1, v15, v55 row_shl:14 row_mask:0xf bank_mask:0xf
	v_fmac_f32_dpp v0, v6, v58 row_shr:1 row_mask:0xf bank_mask:0xf
	v_fmac_f32_dpp v0, v14, v58 row_shl:15 row_mask:0xf bank_mask:0xf
	v_fmac_f32_dpp v1, v7, v59 row_shr:1 row_mask:0xf bank_mask:0xf
	v_fmac_f32_dpp v1, v15, v59 row_shl:15 row_mask:0xf bank_mask:0xf
	v_pk_mul_f32 v[72:73], v[20:21], s[0:1] op_sel_hi:[1,0]
	v_pk_mul_f32 v[4:5], v[0:1], s[0:1] op_sel_hi:[1,0]
	v_exp_f32_e32 v72, v72
	v_exp_f32_e32 v73, v73
	v_exp_f32_e32 v4, v4
	v_exp_f32_e32 v5, v5
	v_pk_add_f32 v[72:73], v[72:73], 1.0 op_sel_hi:[1,0]
	v_pk_add_f32 v[4:5], v[4:5], 1.0 op_sel_hi:[1,0]
	v_rcp_f32_e32 v72, v72
	v_rcp_f32_e32 v73, v73
	v_rcp_f32_e32 v4, v4
	v_rcp_f32_e32 v5, v5
	v_pk_fma_f32 v[82:83], v[16:17], v[48:49], v[32:33]
	v_fmac_f32_dpp v82, v16, v36 row_shr:2 row_mask:0xf bank_mask:0xf
	v_fmac_f32_dpp v82, v24, v36 row_shl:14 row_mask:0xf bank_mask:0xf
	v_fmac_f32_dpp v83, v17, v37 row_shr:2 row_mask:0xf bank_mask:0xf
	v_fmac_f32_dpp v83, v25, v37 row_shl:14 row_mask:0xf bank_mask:0xf
	v_fmac_f32_dpp v82, v16, v44 row_shr:1 row_mask:0xf bank_mask:0xf
	v_fmac_f32_dpp v82, v24, v44 row_shl:15 row_mask:0xf bank_mask:0xf
	v_fmac_f32_dpp v83, v17, v45 row_shr:1 row_mask:0xf bank_mask:0xf
	v_fmac_f32_dpp v83, v25, v45 row_shl:15 row_mask:0xf bank_mask:0xf
	v_mov_b64_e32 v[16:17], v[82:83]
	v_pk_mul_f32 v[20:21], v[20:21], v[72:73]
	v_pk_fma_f32 v[12:13], v[2:3], v[50:51], v[34:35]
	v_fmac_f32_dpp v12, v2, v38 row_shr:2 row_mask:0xf bank_mask:0xf
	v_fmac_f32_dpp v12, v10, v38 row_shl:14 row_mask:0xf bank_mask:0xf
	v_fmac_f32_dpp v13, v3, v39 row_shr:2 row_mask:0xf bank_mask:0xf
	v_fmac_f32_dpp v13, v11, v39 row_shl:14 row_mask:0xf bank_mask:0xf
	v_fmac_f32_dpp v12, v2, v46 row_shr:1 row_mask:0xf bank_mask:0xf
	v_fmac_f32_dpp v12, v10, v46 row_shl:15 row_mask:0xf bank_mask:0xf
	v_fmac_f32_dpp v13, v3, v47 row_shr:1 row_mask:0xf bank_mask:0xf
	v_fmac_f32_dpp v13, v11, v47 row_shl:15 row_mask:0xf bank_mask:0xf
	v_mov_b64_e32 v[2:3], v[12:13]
	v_pk_mul_f32 v[0:1], v[0:1], v[4:5]
	v_pk_mul_f32 v[16:17], v[16:17], v[20:21]
	v_pk_mul_f32 v[0:1], v[2:3], v[0:1]
	v_cvt_pk_bf16_f32 v247, v22, v23
	v_cvt_pk_bf16_f32 v254, v30, v31
	v_cvt_pk_bf16_f32 v246, v16, v17
	v_cvt_pk_bf16_f32 v255, v0, v1
	global_store_dwordx4 v[64:65], v[236:239], off
	global_store_dwordx4 v[66:67], v[244:247], off
	global_store_dwordx4 v[68:69], v[248:251], off
	global_store_dwordx4 v[70:71], v[252:255], off
	s_and_b64 vcc, exec, s[8:9]
	s_mov_b64 s[8:9], -1
	s_cbranch_vccnz .LBB0_1108
	s_andn2_b64 vcc, exec, s[2:3]
	s_cbranch_vccnz .LBB0_1107
	s_barrier
	s_branch .LBB0_1107

;     DI void operator()(const AccT& acc, const Unit& u, int wr, int wc, int fr, int fq) const {
;         const int cl = u.pn * 128 + wc * 32 + 8 * fq;
;         LAS float* P = (LAS float*)(plds + (wr * 4 + wc) * 1024);
;         { const int lane = fq * 16 + fr, kind = lane >> 3, c4 = 4 * (lane & 7), k3 = kind & 3;
;           const float* src = (k3 == 0 ? cb : cw + (k3 - 1) * 5632) + (kind >= 4 ? 2816 : 0) + u.pn * 128 + wc * 32 + c4;
;           *(LAS f32x4*)(P + kind * 32 + c4) = *(const f32x4*)src; }
; #pragma unroll
;         for (int ai = 0; ai < 2; ++ai) {
;             const int tok0 = u.pm * 248 + 62 * (2 * ai + wr) - 2 + fr;
;             float rs[4];
; #pragma unroll
;             for (int m = 0; m < 4; ++m) { const int t = tok0 + 16 * m; const int tc = t < 0 ? 0 : (t >= S ? S - 1 : t); const float r = rs_from_ss(rowss[tc]); rs[m] = t < 0 ? 0.f : r; }
;             const int row0 = fr < 2 ? (S + 236 + fr) : tok0;
; #pragma unroll
;             for (int n = 0; n < 2; ++n) {
;                 const int lc = 8 * fq + 4 * n;
;                 unsigned wpk[4][2];
; #pragma unroll
;                 for (int jp = 0; jp < 2; ++jp) {
;                     const f32x2 bg = *(const LAS f32x2*)(P + lc + 2 * jp), g0 = *(const LAS f32x2*)(P + 32 + lc + 2 * jp), g1 = *(const LAS f32x2*)(P + 64 + lc + 2 * jp), g2 = *(const LAS f32x2*)(P + 96 + lc + 2 * jp);
;                     const f32x2 bv = *(const LAS f32x2*)(P + 128 + lc + 2 * jp), v0 = *(const LAS f32x2*)(P + 160 + lc + 2 * jp), v1 = *(const LAS f32x2*)(P + 192 + lc + 2 * jp), v2 = *(const LAS f32x2*)(P + 224 + lc + 2 * jp);
;                     f32x2 G[4], V[4];
; #pragma unroll
;                     for (int m = 0; m < 4; ++m) { G[m] = (f32x2){acc[ai][0][m][n][2 * jp], acc[ai][0][m][n][2 * jp + 1]} * rs[m]; V[m] = (f32x2){acc[ai][1][m][n][2 * jp], acc[ai][1][m][n][2 * jp + 1]} * rs[m]; }
; #pragma unroll
;                     for (int m = 0; m < 4; ++m) {
;                         const f32x2 zz = {0.f, 0.f}; const f32x2 Gp = m ? G[m - 1] : zz, Vp = m ? V[m - 1] : zz;
;                         const f32x2 gp1 = {dpp_prev1(G[m].x, Gp.x), dpp_prev1(G[m].y, Gp.y)}, gp2 = {dpp_prev2(G[m].x, Gp.x), dpp_prev2(G[m].y, Gp.y)};
;                         const f32x2 vp1 = {dpp_prev1(V[m].x, Vp.x), dpp_prev1(V[m].y, Vp.y)}, vp2 = {dpp_prev2(V[m].x, Vp.x), dpp_prev2(V[m].y, Vp.y)};
.LBB0_1831:
	s_lshl_b32 s8, s58, 7
	s_ashr_i32 s9, s8, 31
	v_lshl_add_u64 v[128:129], s[8:9], 2, v[168:169]
	s_mul_i32 s9, s57, 0xf8
	v_add_u32_e32 v197, s9, v170
	v_med3_i32 v132, v197, 0, s51
	v_lshlrev_b32_e32 v132, 3, v132
	global_load_dwordx2 v[180:181], v132, s[18:19]
	v_add_u32_e32 v198, 16, v197
	v_med3_i32 v132, v198, 0, s51
	v_add_u32_e32 v199, 32, v197
	v_add_u32_e32 v200, 48, v197
	v_lshlrev_b32_e32 v132, 3, v132
	v_med3_i32 v133, v199, 0, s51
	v_med3_i32 v134, v200, 0, s51
	global_load_dwordx4 v[128:131], v[128:129], off
	v_lshlrev_b32_e32 v133, 3, v133
	v_lshlrev_b32_e32 v134, 3, v134
	global_load_dwordx2 v[182:183], v132, s[18:19]
	global_load_dwordx2 v[202:203], v133, s[18:19]
	global_load_dwordx2 v[204:205], v134, s[18:19]
	v_or_b32_e32 v188, s8, v187
	v_ashrrev_i32_e32 v189, 31, v188
	v_cndmask_b32_e64 v201, v197, v190, s[4:5]
	s_waitcnt vmcnt(0)
	v_add_u32_e32 v250, 0x7c, v197
	v_med3_i32 v250, v250, 0, s51
	v_lshlrev_b32_e32 v250, 3, v250
	global_load_dwordx2 v[242:243], v250, s[18:19]
	v_add_u32_e32 v250, 0x8c, v197
	v_med3_i32 v250, v250, 0, s51
	v_lshlrev_b32_e32 v250, 3, v250
	global_load_dwordx2 v[244:245], v250, s[18:19]
	v_add_u32_e32 v250, 0x9c, v197
	v_med3_i32 v250, v250, 0, s51
	v_lshlrev_b32_e32 v250, 3, v250
	global_load_dwordx2 v[246:247], v250, s[18:19]
	v_add_u32_e32 v250, 0xac, v197
	v_med3_i32 v250, v250, 0, s51
	v_lshlrev_b32_e32 v250, 3, v250
	global_load_dwordx2 v[248:249], v250, s[18:19]
	v_ffbh_u32_e32 v184, v181
	v_min_u32_e32 v184, 32, v184
	v_lshlrev_b64 v[180:181], v184, v[180:181]
	v_min_u32_e32 v180, 1, v180
	v_or_b32_e32 v180, v181, v180
	v_cvt_f32_u32_e32 v180, v180
	v_sub_u32_e32 v184, 32, v184
	ds_write_b128 v191, v[128:131]
	v_ffbh_u32_e32 v186, v183
	v_ffbh_u32_e32 v206, v203
	v_min_u32_e32 v186, 32, v186
	v_ffbh_u32_e32 v207, v205
	v_min_u32_e32 v206, 32, v206
	v_lshlrev_b64 v[182:183], v186, v[182:183]
	v_min_u32_e32 v207, 32, v207
	v_lshlrev_b64 v[202:203], v206, v[202:203]
	v_min_u32_e32 v181, 1, v182
	v_lshlrev_b64 v[204:205], v207, v[204:205]
	v_min_u32_e32 v182, 1, v202
	v_or_b32_e32 v181, v183, v181
	v_min_u32_e32 v202, 1, v204
	v_or_b32_e32 v182, v203, v182
	v_cvt_f32_u32_e32 v181, v181
	v_or_b32_e32 v183, v205, v202
	v_cvt_f32_u32_e32 v182, v182
	v_cvt_f32_u32_e32 v183, v183
	v_sub_u32_e32 v186, 32, v186
	v_ldexp_f32 v180, v180, v184
	v_sub_u32_e32 v206, 32, v206
	v_fmamk_f32 v180, v180, 0x30800000, v196
	v_ldexp_f32 v181, v181, v186
	v_sub_u32_e32 v207, 32, v207
	v_ldexp_f32 v182, v182, v206
	v_mul_f32_e32 v184, 0x4b800000, v180
	v_fmamk_f32 v181, v181, 0x30800000, v196
	v_cmp_gt_f32_e32 vcc, s52, v180
	v_ldexp_f32 v183, v183, v207
	v_fmamk_f32 v182, v182, 0x30800000, v196
	v_cndmask_b32_e32 v180, v180, v184, vcc
	v_mul_f32_e32 v184, 0x4b800000, v181
	v_cmp_gt_f32_e64 s[8:9], s52, v181
	v_fmamk_f32 v183, v183, 0x30800000, v196
	v_mul_f32_e32 v186, 0x4b800000, v182
	v_rsq_f32_e32 v180, v180
	v_cndmask_b32_e64 v181, v181, v184, s[8:9]
	v_cmp_gt_f32_e64 s[10:11], s52, v182
	v_mul_f32_e32 v202, 0x4b800000, v183
	v_cmp_gt_f32_e64 s[12:13], s52, v183
	v_cndmask_b32_e64 v182, v182, v186, s[10:11]
	v_rsq_f32_e32 v181, v181
	v_cndmask_b32_e64 v183, v183, v202, s[12:13]
	v_rsq_f32_e32 v182, v182
	v_rsq_f32_e32 v183, v183
	v_mul_f32_e32 v184, 0x45800000, v180
	v_cndmask_b32_e32 v180, v180, v184, vcc
	v_mul_f32_e32 v184, 0x45800000, v181
	v_cmp_lt_i32_e32 vcc, -1, v197
	v_mul_f32_e32 v202, 0x45800000, v182
	v_mul_f32_e32 v203, 0x45800000, v183
	v_cndmask_b32_e32 v186, 0, v180, vcc
	v_cndmask_b32_e64 v180, v181, v184, s[8:9]
	v_cmp_lt_i32_e32 vcc, s53, v197
	v_cndmask_b32_e64 v181, v182, v202, s[10:11]
	v_cndmask_b32_e64 v183, v183, v203, s[12:13]
	v_cndmask_b32_e32 v184, 0, v180, vcc
	v_cmp_lt_i32_e32 vcc, s54, v197
	v_pk_mul_f32 v[124:125], v[124:125], v[186:187] op_sel_hi:[1,0]
	ds_read_b128 v[136:139], v193
	ds_read_b128 v[148:151], v193 offset:128
	ds_read_b128 v[152:155], v193 offset:256
	ds_read_b128 v[156:159], v193 offset:384
	ds_read_b128 v[128:131], v193 offset:512
	ds_read_b128 v[132:135], v193 offset:640
	ds_read_b128 v[140:143], v193 offset:768
	ds_read_b128 v[144:147], v193 offset:896
	v_cndmask_b32_e32 v182, 0, v181, vcc
	v_cmp_lt_i32_e32 vcc, s55, v197
	v_pk_mul_f32 v[108:109], v[108:109], v[182:183] op_sel_hi:[1,0]
	v_pk_mul_f32 v[202:203], v[104:105], v[182:183] op_sel_hi:[1,0]
	v_cndmask_b32_e32 v180, 0, v183, vcc
	v_mov_b32_e32 v183, 0
	v_pk_mul_f32 v[204:205], v[100:101], v[180:181] op_sel_hi:[1,0]
	v_pk_mul_f32 v[206:207], v[96:97], v[180:181] op_sel_hi:[1,0]
	v_mov_b32_e32 v181, 0
	v_mov_b32_dpp v183, v183 row_ror:2 row_mask:0xf bank_mask:0xf
	s_nop 1
	v_mov_b32_dpp v181, v181 row_ror:1 row_mask:0xf bank_mask:0xf
	s_waitcnt lgkmcnt(6)
	v_pk_mul_f32 v[120:121], v[120:121], v[186:187] op_sel_hi:[1,0]
	s_waitcnt lgkmcnt(5)
	s_waitcnt lgkmcnt(4)
	v_pk_fma_f32 v[96:97], v[156:157], v[124:125], v[136:137]
	v_fmac_f32_dpp v96, v124, v148 row_shr:2 row_mask:0xf bank_mask:0xf
	v_fmac_f32_dpp v97, v125, v149 row_shr:2 row_mask:0xf bank_mask:0xf
	v_fmac_f32_dpp v96, v124, v152 row_shr:1 row_mask:0xf bank_mask:0xf
	v_fmac_f32_dpp v97, v125, v153 row_shr:1 row_mask:0xf bank_mask:0xf
	v_pk_mul_f32 v[100:101], v[96:97], s[2:3] op_sel_hi:[1,0]
	v_exp_f32_e32 v100, v100
	v_exp_f32_e32 v101, v101
	s_nop 0
	v_pk_add_f32 v[100:101], v[100:101], 1.0 op_sel_hi:[1,0]
	v_rcp_f32_e32 v100, v100
	v_rcp_f32_e32 v101, v101
	s_waitcnt lgkmcnt(2)
	v_pk_mul_f32 v[116:117], v[116:117], v[184:185] op_sel_hi:[1,0]
	s_waitcnt lgkmcnt(1)
	v_pk_mul_f32 v[96:97], v[96:97], v[100:101]
	s_waitcnt lgkmcnt(0)
; #define LAS __attribute__((address_space(3)))
; DI unsigned pk2(float lo, float hi) { f32x2 v = {lo, hi}; bf16x2_t b = __builtin_convertvector(v, bf16x2_t); return __builtin_bit_cast(unsigned, b); }
;     DI void operator()(const AccT& acc, const Unit& u, int wr, int wc, int fr, int fq) const {
;     ...
;                     const f32x2 bg = *(const LAS f32x2*)(P + lc + 2 * jp), g0 = *(const LAS f32x2*)(P + 32 + lc + 2 * jp), g1 = *(const LAS f32x2*)(P + 64 + lc + 2 * jp), g2 = *(const LAS f32x2*)(P + 96 + lc + 2 * jp);
;                     const f32x2 bv = *(const LAS f32x2*)(P + 128 + lc + 2 * jp), v0 = *(const LAS f32x2*)(P + 160 + lc + 2 * jp), v1 = *(const LAS f32x2*)(P + 192 + lc + 2 * jp), v2 = *(const LAS f32x2*)(P + 224 + lc + 2 * jp);
;                     f32x2 G[4], V[4];
; #pragma unroll
;                     for (int m = 0; m < 4; ++m) { G[m] = (f32x2){acc[ai][0][m][n][2 * jp], acc[ai][0][m][n][2 * jp + 1]} * rs[m]; V[m] = (f32x2){acc[ai][1][m][n][2 * jp], acc[ai][1][m][n][2 * jp + 1]} * rs[m]; }
; #pragma unroll
;                     for (int m = 0; m < 4; ++m) {
;                         const f32x2 zz = {0.f, 0.f}; const f32x2 Gp = m ? G[m - 1] : zz, Vp = m ? V[m - 1] : zz;
;                         const f32x2 gp1 = {dpp_prev1(G[m].x, Gp.x), dpp_prev1(G[m].y, Gp.y)}, gp2 = {dpp_prev2(G[m].x, Gp.x), dpp_prev2(G[m].y, Gp.y)};
;                         const f32x2 vp1 = {dpp_prev1(V[m].x, Vp.x), dpp_prev1(V[m].y, Vp.y)}, vp2 = {dpp_prev2(V[m].x, Vp.x), dpp_prev2(V[m].y, Vp.y)};
;                         const f32x2 gc = bg + g0 * gp2 + g1 * gp1 + g2 * G[m];
;                         const f32x2 vc = bv + v0 * vp2 + v1 * vp1 + v2 * V[m];
;                         const f32x2 xe = gc * (-LOG2E);
;                         f32x2 dn = {__builtin_amdgcn_exp2f(xe.x), __builtin_amdgcn_exp2f(xe.y)}; dn = dn + 1.0f;
;                         const f32x2 rc = {__builtin_amdgcn_rcpf(dn.x), __builtin_amdgcn_rcpf(dn.y)};
;                         const f32x2 rr = gc * rc * vc;
;                         wpk[m][jp] = pk2(rr.x, rr.y); }
	v_pk_fma_f32 v[104:105], v[144:145], v[120:121], v[128:129]
	v_fmac_f32_dpp v104, v120, v132 row_shr:2 row_mask:0xf bank_mask:0xf
	v_fmac_f32_dpp v105, v121, v133 row_shr:2 row_mask:0xf bank_mask:0xf
	v_fmac_f32_dpp v104, v120, v140 row_shr:1 row_mask:0xf bank_mask:0xf
	v_fmac_f32_dpp v105, v121, v141 row_shr:1 row_mask:0xf bank_mask:0xf
	v_pk_mul_f32 v[96:97], v[104:105], v[96:97]
	v_pk_fma_f32 v[100:101], v[156:157], v[116:117], v[136:137]
	v_fmac_f32_dpp v100, v116, v148 row_shr:2 row_mask:0xf bank_mask:0xf
	v_fmac_f32_dpp v100, v124, v148 row_shl:14 row_mask:0xf bank_mask:0xf
	v_fmac_f32_dpp v101, v117, v149 row_shr:2 row_mask:0xf bank_mask:0xf
	v_fmac_f32_dpp v101, v125, v149 row_shl:14 row_mask:0xf bank_mask:0xf
	v_fmac_f32_dpp v100, v116, v152 row_shr:1 row_mask:0xf bank_mask:0xf
	v_fmac_f32_dpp v100, v124, v152 row_shl:15 row_mask:0xf bank_mask:0xf
	v_fmac_f32_dpp v101, v117, v153 row_shr:1 row_mask:0xf bank_mask:0xf
	v_fmac_f32_dpp v101, v125, v153 row_shl:15 row_mask:0xf bank_mask:0xf
	v_pk_mul_f32 v[112:113], v[112:113], v[184:185] op_sel_hi:[1,0]
	v_pk_mul_f32 v[104:105], v[100:101], s[2:3] op_sel_hi:[1,0]
	v_exp_f32_e32 v104, v104
	v_exp_f32_e32 v105, v105
	s_nop 0
	v_pk_add_f32 v[104:105], v[104:105], 1.0 op_sel_hi:[1,0]
	v_rcp_f32_e32 v104, v104
	v_rcp_f32_e32 v105, v105
	s_nop 0
	v_pk_mul_f32 v[100:101], v[100:101], v[104:105]
	v_pk_fma_f32 v[208:209], v[144:145], v[112:113], v[128:129]
	v_fmac_f32_dpp v208, v112, v132 row_shr:2 row_mask:0xf bank_mask:0xf
	v_fmac_f32_dpp v208, v120, v132 row_shl:14 row_mask:0xf bank_mask:0xf
	v_fmac_f32_dpp v209, v113, v133 row_shr:2 row_mask:0xf bank_mask:0xf
	v_fmac_f32_dpp v209, v121, v133 row_shl:14 row_mask:0xf bank_mask:0xf
	v_fmac_f32_dpp v208, v112, v140 row_shr:1 row_mask:0xf bank_mask:0xf
	v_fmac_f32_dpp v208, v120, v140 row_shl:15 row_mask:0xf bank_mask:0xf
	v_fmac_f32_dpp v209, v113, v141 row_shr:1 row_mask:0xf bank_mask:0xf
	v_fmac_f32_dpp v209, v121, v141 row_shl:15 row_mask:0xf bank_mask:0xf
	v_mov_b64_e32 v[120:121], v[208:209]
	v_pk_mul_f32 v[100:101], v[120:121], v[100:101]
	v_pk_fma_f32 v[104:105], v[156:157], v[108:109], v[136:137]
	v_fmac_f32_dpp v104, v108, v148 row_shr:2 row_mask:0xf bank_mask:0xf
	v_fmac_f32_dpp v104, v116, v148 row_shl:14 row_mask:0xf bank_mask:0xf
	v_fmac_f32_dpp v105, v109, v149 row_shr:2 row_mask:0xf bank_mask:0xf
	v_fmac_f32_dpp v105, v117, v149 row_shl:14 row_mask:0xf bank_mask:0xf
	v_fmac_f32_dpp v104, v108, v152 row_shr:1 row_mask:0xf bank_mask:0xf
	v_fmac_f32_dpp v104, v116, v152 row_shl:15 row_mask:0xf bank_mask:0xf
	v_fmac_f32_dpp v105, v109, v153 row_shr:1 row_mask:0xf bank_mask:0xf
	v_fmac_f32_dpp v105, v117, v153 row_shl:15 row_mask:0xf bank_mask:0xf
	v_pk_mul_f32 v[120:121], v[104:105], s[2:3] op_sel_hi:[1,0]
	v_exp_f32_e32 v120, v120
	v_exp_f32_e32 v121, v121
	v_mov_b32_dpp v116, v112 row_ror:1 row_mask:0xf bank_mask:0xf
	v_mov_b32_dpp v117, v113 row_ror:1 row_mask:0xf bank_mask:0xf
	v_mov_b32_dpp v124, v112 row_ror:2 row_mask:0xf bank_mask:0xf
	v_mov_b32_dpp v125, v113 row_ror:2 row_mask:0xf bank_mask:0xf
	v_pk_add_f32 v[112:113], v[120:121], 1.0 op_sel_hi:[1,0]
	v_mov_b32_dpp v124, v202 row_shr:2 row_mask:0xf bank_mask:0xf
	v_rcp_f32_e32 v112, v112
	v_rcp_f32_e32 v113, v113
	v_mov_b32_dpp v125, v203 row_shr:2 row_mask:0xf bank_mask:0xf
	v_mov_b32_dpp v116, v202 row_shr:1 row_mask:0xf bank_mask:0xf
	v_mov_b32_dpp v117, v203 row_shr:1 row_mask:0xf bank_mask:0xf
	v_pk_fma_f32 v[120:121], v[132:133], v[124:125], v[128:129]
	v_pk_mul_f32 v[104:105], v[104:105], v[112:113]
	v_pk_fma_f32 v[116:117], v[140:141], v[116:117], v[120:121]
	v_pk_fma_f32 v[116:117], v[144:145], v[202:203], v[116:117]
	v_pk_mul_f32 v[104:105], v[116:117], v[104:105]
	v_pk_fma_f32 v[112:113], v[156:157], v[204:205], v[136:137]
	v_fmac_f32_dpp v112, v204, v148 row_shr:2 row_mask:0xf bank_mask:0xf
	v_fmac_f32_dpp v112, v108, v148 row_shl:14 row_mask:0xf bank_mask:0xf
	v_fmac_f32_dpp v113, v205, v149 row_shr:2 row_mask:0xf bank_mask:0xf
	v_fmac_f32_dpp v113, v109, v149 row_shl:14 row_mask:0xf bank_mask:0xf
	v_fmac_f32_dpp v112, v204, v152 row_shr:1 row_mask:0xf bank_mask:0xf
	v_fmac_f32_dpp v112, v108, v152 row_shl:15 row_mask:0xf bank_mask:0xf
	v_fmac_f32_dpp v113, v205, v153 row_shr:1 row_mask:0xf bank_mask:0xf
	v_fmac_f32_dpp v113, v109, v153 row_shl:15 row_mask:0xf bank_mask:0xf
	v_pk_mul_f32 v[116:117], v[112:113], s[2:3] op_sel_hi:[1,0]
	v_exp_f32_e32 v116, v116
	v_exp_f32_e32 v117, v117
	s_nop 0
	v_pk_add_f32 v[116:117], v[116:117], 1.0 op_sel_hi:[1,0]
	v_rcp_f32_e32 v116, v116
	v_rcp_f32_e32 v117, v117
	s_nop 0
	v_pk_mul_f32 v[112:113], v[112:113], v[116:117]
	v_pk_mul_f32 v[116:117], v[122:123], v[186:187] op_sel_hi:[1,0]
	v_pk_fma_f32 v[108:109], v[144:145], v[206:207], v[128:129]
	v_fmac_f32_dpp v108, v206, v132 row_shr:2 row_mask:0xf bank_mask:0xf
	v_fmac_f32_dpp v108, v202, v132 row_shl:14 row_mask:0xf bank_mask:0xf
	v_fmac_f32_dpp v109, v207, v133 row_shr:2 row_mask:0xf bank_mask:0xf
	v_fmac_f32_dpp v109, v203, v133 row_shl:14 row_mask:0xf bank_mask:0xf
	v_fmac_f32_dpp v108, v206, v140 row_shr:1 row_mask:0xf bank_mask:0xf
	v_fmac_f32_dpp v108, v202, v140 row_shl:15 row_mask:0xf bank_mask:0xf
	v_fmac_f32_dpp v109, v207, v141 row_shr:1 row_mask:0xf bank_mask:0xf
	v_fmac_f32_dpp v109, v203, v141 row_shl:15 row_mask:0xf bank_mask:0xf
	v_pk_mul_f32 v[108:109], v[108:109], v[112:113]
	v_pk_mul_f32 v[112:113], v[126:127], v[186:187] op_sel_hi:[1,0]
	v_pk_fma_f32 v[120:121], v[112:113], v[158:159], v[138:139]
	s_nop 1
	v_fmac_f32_dpp v120, v112, v150 row_shr:2 row_mask:0xf bank_mask:0xf
	v_fmac_f32_dpp v121, v113, v151 row_shr:2 row_mask:0xf bank_mask:0xf
; #define LAS __attribute__((address_space(3)))
; DI unsigned pk2(float lo, float hi) { f32x2 v = {lo, hi}; bf16x2_t b = __builtin_convertvector(v, bf16x2_t); return __builtin_bit_cast(unsigned, b); }
;     DI void operator()(const AccT& acc, const Unit& u, int wr, int wc, int fr, int fq) const {
;     ...
;                     const f32x2 bg = *(const LAS f32x2*)(P + lc + 2 * jp), g0 = *(const LAS f32x2*)(P + 32 + lc + 2 * jp), g1 = *(const LAS f32x2*)(P + 64 + lc + 2 * jp), g2 = *(const LAS f32x2*)(P + 96 + lc + 2 * jp);
;                     const f32x2 bv = *(const LAS f32x2*)(P + 128 + lc + 2 * jp), v0 = *(const LAS f32x2*)(P + 160 + lc + 2 * jp), v1 = *(const LAS f32x2*)(P + 192 + lc + 2 * jp), v2 = *(const LAS f32x2*)(P + 224 + lc + 2 * jp);
;                     f32x2 G[4], V[4];
; #pragma unroll
;                     for (int m = 0; m < 4; ++m) { G[m] = (f32x2){acc[ai][0][m][n][2 * jp], acc[ai][0][m][n][2 * jp + 1]} * rs[m]; V[m] = (f32x2){acc[ai][1][m][n][2 * jp], acc[ai][1][m][n][2 * jp + 1]} * rs[m]; }
; #pragma unroll
;                     for (int m = 0; m < 4; ++m) {
;                         const f32x2 zz = {0.f, 0.f}; const f32x2 Gp = m ? G[m - 1] : zz, Vp = m ? V[m - 1] : zz;
;                         const f32x2 gp1 = {dpp_prev1(G[m].x, Gp.x), dpp_prev1(G[m].y, Gp.y)}, gp2 = {dpp_prev2(G[m].x, Gp.x), dpp_prev2(G[m].y, Gp.y)};
;                         const f32x2 vp1 = {dpp_prev1(V[m].x, Vp.x), dpp_prev1(V[m].y, Vp.y)}, vp2 = {dpp_prev2(V[m].x, Vp.x), dpp_prev2(V[m].y, Vp.y)};
;                         const f32x2 gc = bg + g0 * gp2 + g1 * gp1 + g2 * G[m];
;                         const f32x2 vc = bv + v0 * vp2 + v1 * vp1 + v2 * V[m];
;                         const f32x2 xe = gc * (-LOG2E);
;                         f32x2 dn = {__builtin_amdgcn_exp2f(xe.x), __builtin_amdgcn_exp2f(xe.y)}; dn = dn + 1.0f;
;                         const f32x2 rc = {__builtin_amdgcn_rcpf(dn.x), __builtin_amdgcn_rcpf(dn.y)};
;                         const f32x2 rr = gc * rc * vc;
;                         wpk[m][jp] = pk2(rr.x, rr.y); }
	v_fmac_f32_dpp v120, v112, v154 row_shr:1 row_mask:0xf bank_mask:0xf
	v_fmac_f32_dpp v121, v113, v155 row_shr:1 row_mask:0xf bank_mask:0xf
	v_pk_mul_f32 v[122:123], v[120:121], s[2:3] op_sel_hi:[1,0]
	v_exp_f32_e32 v122, v122
	v_exp_f32_e32 v123, v123
	s_nop 0
	v_pk_add_f32 v[122:123], v[122:123], 1.0 op_sel_hi:[1,0]
	v_rcp_f32_e32 v122, v122
	v_rcp_f32_e32 v123, v123
	v_cvt_pk_bf16_f32 v228, v96, v97
	v_pk_mul_f32 v[120:121], v[120:121], v[122:123]
	v_pk_fma_f32 v[124:125], v[116:117], v[146:147], v[130:131]
	v_fmac_f32_dpp v124, v116, v134 row_shr:2 row_mask:0xf bank_mask:0xf
	v_fmac_f32_dpp v125, v117, v135 row_shr:2 row_mask:0xf bank_mask:0xf
	v_fmac_f32_dpp v124, v116, v142 row_shr:1 row_mask:0xf bank_mask:0xf
	v_fmac_f32_dpp v125, v117, v143 row_shr:1 row_mask:0xf bank_mask:0xf
	v_pk_mul_f32 v[120:121], v[124:125], v[120:121]
	v_pk_mul_f32 v[118:119], v[118:119], v[184:185] op_sel_hi:[1,0]
	v_cvt_pk_bf16_f32 v229, v120, v121
	v_pk_fma_f32 v[120:121], v[118:119], v[158:159], v[138:139]
	v_fmac_f32_dpp v120, v118, v150 row_shr:2 row_mask:0xf bank_mask:0xf
	v_fmac_f32_dpp v120, v112, v150 row_shl:14 row_mask:0xf bank_mask:0xf
	v_fmac_f32_dpp v121, v119, v151 row_shr:2 row_mask:0xf bank_mask:0xf
	v_fmac_f32_dpp v121, v113, v151 row_shl:14 row_mask:0xf bank_mask:0xf
	v_fmac_f32_dpp v120, v118, v154 row_shr:1 row_mask:0xf bank_mask:0xf
	v_fmac_f32_dpp v120, v112, v154 row_shl:15 row_mask:0xf bank_mask:0xf
	v_fmac_f32_dpp v121, v119, v155 row_shr:1 row_mask:0xf bank_mask:0xf
	v_fmac_f32_dpp v121, v113, v155 row_shl:15 row_mask:0xf bank_mask:0xf
	v_pk_mul_f32 v[122:123], v[120:121], s[2:3] op_sel_hi:[1,0]
	v_exp_f32_e32 v122, v122
	v_exp_f32_e32 v123, v123
	v_mov_b32_dpp v112, v116 row_ror:1 row_mask:0xf bank_mask:0xf
	v_mov_b32_dpp v113, v117 row_ror:1 row_mask:0xf bank_mask:0xf
	v_mov_b32_dpp v124, v116 row_ror:2 row_mask:0xf bank_mask:0xf
	v_mov_b32_dpp v125, v117 row_ror:2 row_mask:0xf bank_mask:0xf
	v_pk_add_f32 v[116:117], v[122:123], 1.0 op_sel_hi:[1,0]
	v_pk_mul_f32 v[114:115], v[114:115], v[184:185] op_sel_hi:[1,0]
	v_rcp_f32_e32 v116, v116
	v_rcp_f32_e32 v117, v117
	v_mov_b32_dpp v124, v114 row_shr:2 row_mask:0xf bank_mask:0xf
	v_mov_b32_dpp v125, v115 row_shr:2 row_mask:0xf bank_mask:0xf
	v_mov_b32_dpp v112, v114 row_shr:1 row_mask:0xf bank_mask:0xf
	v_mov_b32_dpp v113, v115 row_shr:1 row_mask:0xf bank_mask:0xf
	v_pk_fma_f32 v[122:123], v[134:135], v[124:125], v[130:131]
	v_pk_mul_f32 v[116:117], v[120:121], v[116:117]
	v_pk_fma_f32 v[112:113], v[142:143], v[112:113], v[122:123]
	v_cvt_pk_bf16_f32 v232, v100, v101
	v_pk_fma_f32 v[112:113], v[114:115], v[146:147], v[112:113]
	v_pk_mul_f32 v[110:111], v[110:111], v[182:183] op_sel_hi:[1,0]
	v_pk_mul_f32 v[112:113], v[112:113], v[116:117]
	v_cvt_pk_bf16_f32 v233, v112, v113
	v_pk_fma_f32 v[112:113], v[110:111], v[158:159], v[138:139]
	v_fmac_f32_dpp v112, v110, v150 row_shr:2 row_mask:0xf bank_mask:0xf
	v_fmac_f32_dpp v112, v118, v150 row_shl:14 row_mask:0xf bank_mask:0xf
	v_fmac_f32_dpp v113, v111, v151 row_shr:2 row_mask:0xf bank_mask:0xf
	v_fmac_f32_dpp v113, v119, v151 row_shl:14 row_mask:0xf bank_mask:0xf
	v_fmac_f32_dpp v112, v110, v154 row_shr:1 row_mask:0xf bank_mask:0xf
	v_fmac_f32_dpp v112, v118, v154 row_shl:15 row_mask:0xf bank_mask:0xf
	v_fmac_f32_dpp v113, v111, v155 row_shr:1 row_mask:0xf bank_mask:0xf
	v_fmac_f32_dpp v113, v119, v155 row_shl:15 row_mask:0xf bank_mask:0xf
	v_pk_mul_f32 v[116:117], v[112:113], s[2:3] op_sel_hi:[1,0]
	v_exp_f32_e32 v116, v116
	v_exp_f32_e32 v117, v117
	v_mov_b32_dpp v118, v114 row_ror:1 row_mask:0xf bank_mask:0xf
	v_mov_b32_dpp v119, v115 row_ror:1 row_mask:0xf bank_mask:0xf
	v_mov_b32_dpp v120, v114 row_ror:2 row_mask:0xf bank_mask:0xf
	v_mov_b32_dpp v121, v115 row_ror:2 row_mask:0xf bank_mask:0xf
	v_pk_add_f32 v[114:115], v[116:117], 1.0 op_sel_hi:[1,0]
	v_pk_mul_f32 v[106:107], v[106:107], v[182:183] op_sel_hi:[1,0]
	v_rcp_f32_e32 v114, v114
	v_rcp_f32_e32 v115, v115
	v_mov_b32_dpp v120, v106 row_shr:2 row_mask:0xf bank_mask:0xf
	v_mov_b32_dpp v121, v107 row_shr:2 row_mask:0xf bank_mask:0xf
	v_mov_b32_dpp v118, v106 row_shr:1 row_mask:0xf bank_mask:0xf
	v_mov_b32_dpp v119, v107 row_shr:1 row_mask:0xf bank_mask:0xf
	v_pk_fma_f32 v[116:117], v[134:135], v[120:121], v[130:131]
	v_pk_mul_f32 v[112:113], v[112:113], v[114:115]
	v_pk_fma_f32 v[116:117], v[142:143], v[118:119], v[116:117]
	v_pk_fma_f32 v[116:117], v[106:107], v[146:147], v[116:117]
	v_pk_mul_f32 v[112:113], v[116:117], v[112:113]
	v_cvt_pk_bf16_f32 v236, v104, v105
	v_pk_mul_f32 v[102:103], v[102:103], v[180:181] op_sel_hi:[1,0]
	v_cvt_pk_bf16_f32 v237, v112, v113
	v_pk_fma_f32 v[114:115], v[102:103], v[158:159], v[138:139]
	v_fmac_f32_dpp v114, v102, v150 row_shr:2 row_mask:0xf bank_mask:0xf
	v_fmac_f32_dpp v114, v110, v150 row_shl:14 row_mask:0xf bank_mask:0xf
	v_fmac_f32_dpp v115, v103, v151 row_shr:2 row_mask:0xf bank_mask:0xf
	v_fmac_f32_dpp v115, v111, v151 row_shl:14 row_mask:0xf bank_mask:0xf
	v_fmac_f32_dpp v114, v102, v154 row_shr:1 row_mask:0xf bank_mask:0xf
	v_fmac_f32_dpp v114, v110, v154 row_shl:15 row_mask:0xf bank_mask:0xf
	v_fmac_f32_dpp v115, v103, v155 row_shr:1 row_mask:0xf bank_mask:0xf
	v_fmac_f32_dpp v115, v111, v155 row_shl:15 row_mask:0xf bank_mask:0xf
	v_mov_b64_e32 v[102:103], v[114:115]
	v_pk_mul_f32 v[112:113], v[102:103], s[2:3] op_sel_hi:[1,0]
	v_exp_f32_e32 v112, v112
	v_exp_f32_e32 v113, v113
	v_mov_b32_dpp v110, v106 row_ror:1 row_mask:0xf bank_mask:0xf
	v_mov_b32_dpp v111, v107 row_ror:1 row_mask:0xf bank_mask:0xf
	v_mov_b32_dpp v116, v106 row_ror:2 row_mask:0xf bank_mask:0xf
	v_mov_b32_dpp v117, v107 row_ror:2 row_mask:0xf bank_mask:0xf
; DI float dpp_prev1(float cur, float prevm) {
;     const int o = __builtin_amdgcn_update_dpp(0, __builtin_bit_cast(int, prevm), 0x121, 0xf, 0xf, false);
;     return __builtin_bit_cast(float, __builtin_amdgcn_update_dpp(o, __builtin_bit_cast(int, cur), 0x111, 0xf, 0xf, false));
; }
;     DI void operator()(const AccT& acc, const Unit& u, int wr, int wc, int fr, int fq) const {
;     ...
;                     const f32x2 bg = *(const LAS f32x2*)(P + lc + 2 * jp), g0 = *(const LAS f32x2*)(P + 32 + lc + 2 * jp), g1 = *(const LAS f32x2*)(P + 64 + lc + 2 * jp), g2 = *(const LAS f32x2*)(P + 96 + lc + 2 * jp);
;                     const f32x2 bv = *(const LAS f32x2*)(P + 128 + lc + 2 * jp), v0 = *(const LAS f32x2*)(P + 160 + lc + 2 * jp), v1 = *(const LAS f32x2*)(P + 192 + lc + 2 * jp), v2 = *(const LAS f32x2*)(P + 224 + lc + 2 * jp);
;                     f32x2 G[4], V[4];
; #pragma unroll
;                     for (int m = 0; m < 4; ++m) { G[m] = (f32x2){acc[ai][0][m][n][2 * jp], acc[ai][0][m][n][2 * jp + 1]} * rs[m]; V[m] = (f32x2){acc[ai][1][m][n][2 * jp], acc[ai][1][m][n][2 * jp + 1]} * rs[m]; }
; #pragma unroll
;                     for (int m = 0; m < 4; ++m) {
;                         const f32x2 zz = {0.f, 0.f}; const f32x2 Gp = m ? G[m - 1] : zz, Vp = m ? V[m - 1] : zz;
;                         const f32x2 gp1 = {dpp_prev1(G[m].x, Gp.x), dpp_prev1(G[m].y, Gp.y)}, gp2 = {dpp_prev2(G[m].x, Gp.x), dpp_prev2(G[m].y, Gp.y)};
;                         const f32x2 vp1 = {dpp_prev1(V[m].x, Vp.x), dpp_prev1(V[m].y, Vp.y)}, vp2 = {dpp_prev2(V[m].x, Vp.x), dpp_prev2(V[m].y, Vp.y)};
;                         const f32x2 gc = bg + g0 * gp2 + g1 * gp1 + g2 * G[m];
;                         const f32x2 vc = bv + v0 * vp2 + v1 * vp1 + v2 * V[m];
;                         const f32x2 xe = gc * (-LOG2E);
;                         f32x2 dn = {__builtin_amdgcn_exp2f(xe.x), __builtin_amdgcn_exp2f(xe.y)}; dn = dn + 1.0f;
;                         const f32x2 rc = {__builtin_amdgcn_rcpf(dn.x), __builtin_amdgcn_rcpf(dn.y)};
;                         const f32x2 rr = gc * rc * vc;
;                         wpk[m][jp] = pk2(rr.x, rr.y); }
;                 }
; #pragma unroll
;                 for (int m = 0; m < 4; ++m) { const int row = m ? tok0 + 16 * m : row0;
;                     *(u32x2*)(ACT + (size_t)row * 2816 + cl + 4 * n) = (u32x2){wpk[m][0], wpk[m][1]}; }
	v_pk_add_f32 v[106:107], v[112:113], 1.0 op_sel_hi:[1,0]
	v_pk_mul_f32 v[98:99], v[98:99], v[180:181] op_sel_hi:[1,0]
	v_rcp_f32_e32 v106, v106
	v_rcp_f32_e32 v107, v107
	v_mov_b32_dpp v116, v98 row_shr:2 row_mask:0xf bank_mask:0xf
	v_mov_b32_dpp v117, v99 row_shr:2 row_mask:0xf bank_mask:0xf
	v_mov_b32_dpp v110, v98 row_shr:1 row_mask:0xf bank_mask:0xf
	v_mov_b32_dpp v111, v99 row_shr:1 row_mask:0xf bank_mask:0xf
	v_pk_fma_f32 v[112:113], v[134:135], v[116:117], v[130:131]
	v_pk_mul_f32 v[102:103], v[102:103], v[106:107]
	v_pk_fma_f32 v[110:111], v[142:143], v[110:111], v[112:113]
	v_mov_b64_e32 v[128:129], s[16:17]
	v_pk_fma_f32 v[98:99], v[98:99], v[146:147], v[110:111]
	v_cvt_pk_bf16_f32 v252, v108, v109
	v_pk_mul_f32 v[98:99], v[98:99], v[102:103]
	v_lshlrev_b64 v[130:131], 1, v[188:189]
	v_cvt_pk_bf16_f32 v253, v98, v99
	v_mad_i64_i32 v[98:99], s[8:9], v201, s48, v[128:129]
	v_lshl_add_u64 v[132:133], v[98:99], 0, v[130:131]
	v_mad_i64_i32 v[96:97], s[8:9], v198, s48, v[128:129]
	v_lshl_add_u64 v[134:135], v[96:97], 0, v[130:131]
	v_mad_i64_i32 v[96:97], s[8:9], v199, s48, v[128:129]
	v_lshl_add_u64 v[136:137], v[96:97], 0, v[130:131]
	v_mad_i64_i32 v[96:97], s[8:9], v200, s48, v[128:129]
	v_lshl_add_u64 v[138:139], v[96:97], 0, v[130:131]
	v_pk_mul_f32 v[92:93], v[92:93], v[186:187] op_sel_hi:[1,0]
	v_pk_mul_f32 v[142:143], v[68:69], v[180:181] op_sel_hi:[1,0]
	v_pk_mul_f32 v[144:145], v[64:65], v[180:181] op_sel_hi:[1,0]
	ds_read_b128 v[104:107], v193 offset:16
	ds_read_b128 v[116:119], v193 offset:144
	ds_read_b128 v[120:123], v193 offset:272
	ds_read_b128 v[124:127], v193 offset:400
	ds_read_b128 v[96:99], v193 offset:528
	ds_read_b128 v[100:103], v193 offset:656
	ds_read_b128 v[108:111], v193 offset:784
	ds_read_b128 v[112:115], v193 offset:912
	s_waitcnt lgkmcnt(6)
	v_pk_mul_f32 v[88:89], v[88:89], v[186:187] op_sel_hi:[1,0]
	s_waitcnt lgkmcnt(5)
	s_waitcnt lgkmcnt(4)
	v_pk_fma_f32 v[64:65], v[92:93], v[124:125], v[104:105]
	v_fmac_f32_dpp v64, v92, v116 row_shr:2 row_mask:0xf bank_mask:0xf
	v_fmac_f32_dpp v65, v93, v117 row_shr:2 row_mask:0xf bank_mask:0xf
	v_fmac_f32_dpp v64, v92, v120 row_shr:1 row_mask:0xf bank_mask:0xf
	v_fmac_f32_dpp v65, v93, v121 row_shr:1 row_mask:0xf bank_mask:0xf
	v_pk_mul_f32 v[68:69], v[64:65], s[2:3] op_sel_hi:[1,0]
	v_pk_mul_f32 v[140:141], v[72:73], v[182:183] op_sel_hi:[1,0]
	v_exp_f32_e32 v68, v68
	v_exp_f32_e32 v69, v69
	s_nop 0
	v_pk_add_f32 v[68:69], v[68:69], 1.0 op_sel_hi:[1,0]
	v_rcp_f32_e32 v68, v68
	v_rcp_f32_e32 v69, v69
	s_waitcnt lgkmcnt(2)
	v_pk_mul_f32 v[64:65], v[64:65], v[68:69]
	s_waitcnt lgkmcnt(1)
	v_pk_mul_f32 v[84:85], v[84:85], v[184:185] op_sel_hi:[1,0]
	s_waitcnt lgkmcnt(0)
	v_pk_fma_f32 v[72:73], v[88:89], v[112:113], v[96:97]
	v_fmac_f32_dpp v72, v88, v100 row_shr:2 row_mask:0xf bank_mask:0xf
	v_fmac_f32_dpp v73, v89, v101 row_shr:2 row_mask:0xf bank_mask:0xf
	v_fmac_f32_dpp v72, v88, v108 row_shr:1 row_mask:0xf bank_mask:0xf
	v_fmac_f32_dpp v73, v89, v109 row_shr:1 row_mask:0xf bank_mask:0xf
	v_pk_mul_f32 v[64:65], v[72:73], v[64:65]
	v_pk_fma_f32 v[68:69], v[84:85], v[124:125], v[104:105]
	v_fmac_f32_dpp v68, v84, v116 row_shr:2 row_mask:0xf bank_mask:0xf
	v_fmac_f32_dpp v68, v92, v116 row_shl:14 row_mask:0xf bank_mask:0xf
	v_fmac_f32_dpp v69, v85, v117 row_shr:2 row_mask:0xf bank_mask:0xf
	v_fmac_f32_dpp v69, v93, v117 row_shl:14 row_mask:0xf bank_mask:0xf
	v_fmac_f32_dpp v68, v84, v120 row_shr:1 row_mask:0xf bank_mask:0xf
	v_fmac_f32_dpp v68, v92, v120 row_shl:15 row_mask:0xf bank_mask:0xf
	v_fmac_f32_dpp v69, v85, v121 row_shr:1 row_mask:0xf bank_mask:0xf
	v_fmac_f32_dpp v69, v93, v121 row_shl:15 row_mask:0xf bank_mask:0xf
	v_pk_mul_f32 v[80:81], v[80:81], v[184:185] op_sel_hi:[1,0]
	v_pk_mul_f32 v[72:73], v[68:69], s[2:3] op_sel_hi:[1,0]
	v_exp_f32_e32 v72, v72
	v_exp_f32_e32 v73, v73
	s_nop 0
	v_pk_add_f32 v[72:73], v[72:73], 1.0 op_sel_hi:[1,0]
	v_rcp_f32_e32 v72, v72
	v_rcp_f32_e32 v73, v73
	s_nop 0
	v_pk_mul_f32 v[68:69], v[68:69], v[72:73]
	v_pk_mul_f32 v[76:77], v[76:77], v[182:183] op_sel_hi:[1,0]
	v_pk_fma_f32 v[146:147], v[80:81], v[112:113], v[96:97]
	v_fmac_f32_dpp v146, v80, v100 row_shr:2 row_mask:0xf bank_mask:0xf
	v_fmac_f32_dpp v146, v88, v100 row_shl:14 row_mask:0xf bank_mask:0xf
	v_fmac_f32_dpp v147, v81, v101 row_shr:2 row_mask:0xf bank_mask:0xf
	v_fmac_f32_dpp v147, v89, v101 row_shl:14 row_mask:0xf bank_mask:0xf
	v_fmac_f32_dpp v146, v80, v108 row_shr:1 row_mask:0xf bank_mask:0xf
	v_fmac_f32_dpp v146, v88, v108 row_shl:15 row_mask:0xf bank_mask:0xf
	v_fmac_f32_dpp v147, v81, v109 row_shr:1 row_mask:0xf bank_mask:0xf
	v_fmac_f32_dpp v147, v89, v109 row_shl:15 row_mask:0xf bank_mask:0xf
	v_mov_b64_e32 v[88:89], v[146:147]
	v_pk_mul_f32 v[68:69], v[88:89], v[68:69]
	v_pk_fma_f32 v[72:73], v[76:77], v[124:125], v[104:105]
	v_fmac_f32_dpp v72, v76, v116 row_shr:2 row_mask:0xf bank_mask:0xf
	v_fmac_f32_dpp v72, v84, v116 row_shl:14 row_mask:0xf bank_mask:0xf
	v_fmac_f32_dpp v73, v77, v117 row_shr:2 row_mask:0xf bank_mask:0xf
	v_fmac_f32_dpp v73, v85, v117 row_shl:14 row_mask:0xf bank_mask:0xf
	v_fmac_f32_dpp v72, v76, v120 row_shr:1 row_mask:0xf bank_mask:0xf
	v_fmac_f32_dpp v72, v84, v120 row_shl:15 row_mask:0xf bank_mask:0xf
	v_fmac_f32_dpp v73, v77, v121 row_shr:1 row_mask:0xf bank_mask:0xf
	v_fmac_f32_dpp v73, v85, v121 row_shl:15 row_mask:0xf bank_mask:0xf
	v_pk_mul_f32 v[88:89], v[72:73], s[2:3] op_sel_hi:[1,0]
	v_exp_f32_e32 v88, v88
	v_exp_f32_e32 v89, v89
	v_mov_b32_dpp v84, v80 row_ror:1 row_mask:0xf bank_mask:0xf
	v_mov_b32_dpp v85, v81 row_ror:1 row_mask:0xf bank_mask:0xf
	v_mov_b32_dpp v92, v80 row_ror:2 row_mask:0xf bank_mask:0xf
; DI unsigned pk2(float lo, float hi) { f32x2 v = {lo, hi}; bf16x2_t b = __builtin_convertvector(v, bf16x2_t); return __builtin_bit_cast(unsigned, b); }
; DI float dpp_prev1(float cur, float prevm) {
;     const int o = __builtin_amdgcn_update_dpp(0, __builtin_bit_cast(int, prevm), 0x121, 0xf, 0xf, false);
;     return __builtin_bit_cast(float, __builtin_amdgcn_update_dpp(o, __builtin_bit_cast(int, cur), 0x111, 0xf, 0xf, false));
; }
; DI float dpp_prev2(float cur, float prevm) {
;     const int o = __builtin_amdgcn_update_dpp(0, __builtin_bit_cast(int, prevm), 0x122, 0xf, 0xf, false);
;     return __builtin_bit_cast(float, __builtin_amdgcn_update_dpp(o, __builtin_bit_cast(int, cur), 0x112, 0xf, 0xf, false));
; }
;     DI void operator()(const AccT& acc, const Unit& u, int wr, int wc, int fr, int fq) const {
;     ...
;                     for (int m = 0; m < 4; ++m) { G[m] = (f32x2){acc[ai][0][m][n][2 * jp], acc[ai][0][m][n][2 * jp + 1]} * rs[m]; V[m] = (f32x2){acc[ai][1][m][n][2 * jp], acc[ai][1][m][n][2 * jp + 1]} * rs[m]; }
; #pragma unroll
;                     for (int m = 0; m < 4; ++m) {
;                         const f32x2 zz = {0.f, 0.f}; const f32x2 Gp = m ? G[m - 1] : zz, Vp = m ? V[m - 1] : zz;
;                         const f32x2 gp1 = {dpp_prev1(G[m].x, Gp.x), dpp_prev1(G[m].y, Gp.y)}, gp2 = {dpp_prev2(G[m].x, Gp.x), dpp_prev2(G[m].y, Gp.y)};
;                         const f32x2 vp1 = {dpp_prev1(V[m].x, Vp.x), dpp_prev1(V[m].y, Vp.y)}, vp2 = {dpp_prev2(V[m].x, Vp.x), dpp_prev2(V[m].y, Vp.y)};
;                         const f32x2 gc = bg + g0 * gp2 + g1 * gp1 + g2 * G[m];
;                         const f32x2 vc = bv + v0 * vp2 + v1 * vp1 + v2 * V[m];
;                         const f32x2 xe = gc * (-LOG2E);
;                         f32x2 dn = {__builtin_amdgcn_exp2f(xe.x), __builtin_amdgcn_exp2f(xe.y)}; dn = dn + 1.0f;
;                         const f32x2 rc = {__builtin_amdgcn_rcpf(dn.x), __builtin_amdgcn_rcpf(dn.y)};
;                         const f32x2 rr = gc * rc * vc;
;                         wpk[m][jp] = pk2(rr.x, rr.y); }
	v_mov_b32_dpp v93, v81 row_ror:2 row_mask:0xf bank_mask:0xf
	v_pk_add_f32 v[80:81], v[88:89], 1.0 op_sel_hi:[1,0]
	v_mov_b32_dpp v92, v140 row_shr:2 row_mask:0xf bank_mask:0xf
	v_rcp_f32_e32 v80, v80
	v_rcp_f32_e32 v81, v81
	v_mov_b32_dpp v93, v141 row_shr:2 row_mask:0xf bank_mask:0xf
	v_mov_b32_dpp v84, v140 row_shr:1 row_mask:0xf bank_mask:0xf
	v_mov_b32_dpp v85, v141 row_shr:1 row_mask:0xf bank_mask:0xf
	v_pk_fma_f32 v[88:89], v[100:101], v[92:93], v[96:97]
	v_pk_mul_f32 v[72:73], v[72:73], v[80:81]
	v_pk_fma_f32 v[84:85], v[108:109], v[84:85], v[88:89]
	v_pk_fma_f32 v[84:85], v[140:141], v[112:113], v[84:85]
	v_pk_mul_f32 v[72:73], v[84:85], v[72:73]
	v_pk_fma_f32 v[80:81], v[142:143], v[124:125], v[104:105]
	v_fmac_f32_dpp v80, v142, v116 row_shr:2 row_mask:0xf bank_mask:0xf
	v_fmac_f32_dpp v80, v76, v116 row_shl:14 row_mask:0xf bank_mask:0xf
	v_fmac_f32_dpp v81, v143, v117 row_shr:2 row_mask:0xf bank_mask:0xf
	v_fmac_f32_dpp v81, v77, v117 row_shl:14 row_mask:0xf bank_mask:0xf
	v_fmac_f32_dpp v80, v142, v120 row_shr:1 row_mask:0xf bank_mask:0xf
	v_fmac_f32_dpp v80, v76, v120 row_shl:15 row_mask:0xf bank_mask:0xf
	v_fmac_f32_dpp v81, v143, v121 row_shr:1 row_mask:0xf bank_mask:0xf
	v_fmac_f32_dpp v81, v77, v121 row_shl:15 row_mask:0xf bank_mask:0xf
	v_pk_mul_f32 v[84:85], v[80:81], s[2:3] op_sel_hi:[1,0]
	v_exp_f32_e32 v84, v84
	v_exp_f32_e32 v85, v85
	s_nop 0
	v_pk_add_f32 v[84:85], v[84:85], 1.0 op_sel_hi:[1,0]
	v_rcp_f32_e32 v84, v84
	v_rcp_f32_e32 v85, v85
	s_nop 0
	v_pk_mul_f32 v[80:81], v[80:81], v[84:85]
	v_pk_mul_f32 v[84:85], v[90:91], v[186:187] op_sel_hi:[1,0]
	v_pk_fma_f32 v[76:77], v[144:145], v[112:113], v[96:97]
	v_fmac_f32_dpp v76, v144, v100 row_shr:2 row_mask:0xf bank_mask:0xf
	v_fmac_f32_dpp v76, v140, v100 row_shl:14 row_mask:0xf bank_mask:0xf
	v_fmac_f32_dpp v77, v145, v101 row_shr:2 row_mask:0xf bank_mask:0xf
	v_fmac_f32_dpp v77, v141, v101 row_shl:14 row_mask:0xf bank_mask:0xf
	v_fmac_f32_dpp v76, v144, v108 row_shr:1 row_mask:0xf bank_mask:0xf
	v_fmac_f32_dpp v76, v140, v108 row_shl:15 row_mask:0xf bank_mask:0xf
	v_fmac_f32_dpp v77, v145, v109 row_shr:1 row_mask:0xf bank_mask:0xf
	v_fmac_f32_dpp v77, v141, v109 row_shl:15 row_mask:0xf bank_mask:0xf
	v_pk_mul_f32 v[76:77], v[76:77], v[80:81]
	v_pk_mul_f32 v[80:81], v[94:95], v[186:187] op_sel_hi:[1,0]
	v_pk_fma_f32 v[88:89], v[80:81], v[126:127], v[106:107]
	s_nop 1
	v_fmac_f32_dpp v88, v80, v118 row_shr:2 row_mask:0xf bank_mask:0xf
	v_fmac_f32_dpp v89, v81, v119 row_shr:2 row_mask:0xf bank_mask:0xf
	v_fmac_f32_dpp v88, v80, v122 row_shr:1 row_mask:0xf bank_mask:0xf
	v_fmac_f32_dpp v89, v81, v123 row_shr:1 row_mask:0xf bank_mask:0xf
	v_pk_mul_f32 v[90:91], v[88:89], s[2:3] op_sel_hi:[1,0]
	v_exp_f32_e32 v90, v90
	v_exp_f32_e32 v91, v91
	s_nop 0
	v_pk_add_f32 v[90:91], v[90:91], 1.0 op_sel_hi:[1,0]
	v_rcp_f32_e32 v90, v90
	v_rcp_f32_e32 v91, v91
	v_cvt_pk_bf16_f32 v230, v64, v65
	v_pk_mul_f32 v[88:89], v[88:89], v[90:91]
	v_pk_fma_f32 v[92:93], v[84:85], v[114:115], v[98:99]
	v_fmac_f32_dpp v92, v84, v102 row_shr:2 row_mask:0xf bank_mask:0xf
	v_fmac_f32_dpp v93, v85, v103 row_shr:2 row_mask:0xf bank_mask:0xf
	v_fmac_f32_dpp v92, v84, v110 row_shr:1 row_mask:0xf bank_mask:0xf
	v_fmac_f32_dpp v93, v85, v111 row_shr:1 row_mask:0xf bank_mask:0xf
	v_pk_mul_f32 v[88:89], v[92:93], v[88:89]
	v_pk_mul_f32 v[86:87], v[86:87], v[184:185] op_sel_hi:[1,0]
	v_cvt_pk_bf16_f32 v231, v88, v89
	v_pk_fma_f32 v[88:89], v[86:87], v[126:127], v[106:107]
	v_fmac_f32_dpp v88, v86, v118 row_shr:2 row_mask:0xf bank_mask:0xf
	v_fmac_f32_dpp v88, v80, v118 row_shl:14 row_mask:0xf bank_mask:0xf
	v_fmac_f32_dpp v89, v87, v119 row_shr:2 row_mask:0xf bank_mask:0xf
	v_fmac_f32_dpp v89, v81, v119 row_shl:14 row_mask:0xf bank_mask:0xf
	v_fmac_f32_dpp v88, v86, v122 row_shr:1 row_mask:0xf bank_mask:0xf
	v_fmac_f32_dpp v88, v80, v122 row_shl:15 row_mask:0xf bank_mask:0xf
	v_fmac_f32_dpp v89, v87, v123 row_shr:1 row_mask:0xf bank_mask:0xf
	v_fmac_f32_dpp v89, v81, v123 row_shl:15 row_mask:0xf bank_mask:0xf
	v_pk_mul_f32 v[90:91], v[88:89], s[2:3] op_sel_hi:[1,0]
	v_exp_f32_e32 v90, v90
	v_exp_f32_e32 v91, v91
	v_mov_b32_dpp v80, v84 row_ror:1 row_mask:0xf bank_mask:0xf
	v_mov_b32_dpp v81, v85 row_ror:1 row_mask:0xf bank_mask:0xf
	v_mov_b32_dpp v92, v84 row_ror:2 row_mask:0xf bank_mask:0xf
	v_mov_b32_dpp v93, v85 row_ror:2 row_mask:0xf bank_mask:0xf
	v_pk_add_f32 v[84:85], v[90:91], 1.0 op_sel_hi:[1,0]
	v_pk_mul_f32 v[82:83], v[82:83], v[184:185] op_sel_hi:[1,0]
	v_rcp_f32_e32 v84, v84
	v_rcp_f32_e32 v85, v85
	v_mov_b32_dpp v92, v82 row_shr:2 row_mask:0xf bank_mask:0xf
	v_mov_b32_dpp v93, v83 row_shr:2 row_mask:0xf bank_mask:0xf
	v_mov_b32_dpp v80, v82 row_shr:1 row_mask:0xf bank_mask:0xf
	v_mov_b32_dpp v81, v83 row_shr:1 row_mask:0xf bank_mask:0xf
	v_pk_fma_f32 v[90:91], v[102:103], v[92:93], v[98:99]
	v_pk_mul_f32 v[84:85], v[88:89], v[84:85]
	v_pk_fma_f32 v[80:81], v[110:111], v[80:81], v[90:91]
	v_cvt_pk_bf16_f32 v234, v68, v69
	v_pk_fma_f32 v[80:81], v[82:83], v[114:115], v[80:81]
	v_pk_mul_f32 v[78:79], v[78:79], v[182:183] op_sel_hi:[1,0]
	v_pk_mul_f32 v[80:81], v[80:81], v[84:85]
	v_cvt_pk_bf16_f32 v235, v80, v81
	v_pk_fma_f32 v[80:81], v[78:79], v[126:127], v[106:107]
	v_fmac_f32_dpp v80, v78, v118 row_shr:2 row_mask:0xf bank_mask:0xf
	v_fmac_f32_dpp v80, v86, v118 row_shl:14 row_mask:0xf bank_mask:0xf
	v_fmac_f32_dpp v81, v79, v119 row_shr:2 row_mask:0xf bank_mask:0xf
	v_fmac_f32_dpp v81, v87, v119 row_shl:14 row_mask:0xf bank_mask:0xf
	v_fmac_f32_dpp v80, v78, v122 row_shr:1 row_mask:0xf bank_mask:0xf
	v_fmac_f32_dpp v80, v86, v122 row_shl:15 row_mask:0xf bank_mask:0xf
;     DI void operator()(const AccT& acc, const Unit& u, int wr, int wc, int fr, int fq) const {
;     ...
;             for (int m = 0; m < 4; ++m) { const int t = tok0 + 16 * m; const int tc = t < 0 ? 0 : (t >= S ? S - 1 : t); const float r = rs_from_ss(rowss[tc]); rs[m] = t < 0 ? 0.f : r; }
;             const int row0 = fr < 2 ? (S + 236 + fr) : tok0;
; #pragma unroll
;             for (int n = 0; n < 2; ++n) {
;                 const int lc = 8 * fq + 4 * n;
;                 unsigned wpk[4][2];
; #pragma unroll
;                 for (int jp = 0; jp < 2; ++jp) {
;                     const f32x2 bg = *(const LAS f32x2*)(P + lc + 2 * jp), g0 = *(const LAS f32x2*)(P + 32 + lc + 2 * jp), g1 = *(const LAS f32x2*)(P + 64 + lc + 2 * jp), g2 = *(const LAS f32x2*)(P + 96 + lc + 2 * jp);
;                     const f32x2 bv = *(const LAS f32x2*)(P + 128 + lc + 2 * jp), v0 = *(const LAS f32x2*)(P + 160 + lc + 2 * jp), v1 = *(const LAS f32x2*)(P + 192 + lc + 2 * jp), v2 = *(const LAS f32x2*)(P + 224 + lc + 2 * jp);
;                     f32x2 G[4], V[4];
; #pragma unroll
;                     for (int m = 0; m < 4; ++m) { G[m] = (f32x2){acc[ai][0][m][n][2 * jp], acc[ai][0][m][n][2 * jp + 1]} * rs[m]; V[m] = (f32x2){acc[ai][1][m][n][2 * jp], acc[ai][1][m][n][2 * jp + 1]} * rs[m]; }
; #pragma unroll
;                     for (int m = 0; m < 4; ++m) {
;                         const f32x2 zz = {0.f, 0.f}; const f32x2 Gp = m ? G[m - 1] : zz, Vp = m ? V[m - 1] : zz;
;                         const f32x2 gp1 = {dpp_prev1(G[m].x, Gp.x), dpp_prev1(G[m].y, Gp.y)}, gp2 = {dpp_prev2(G[m].x, Gp.x), dpp_prev2(G[m].y, Gp.y)};
;                         const f32x2 vp1 = {dpp_prev1(V[m].x, Vp.x), dpp_prev1(V[m].y, Vp.y)}, vp2 = {dpp_prev2(V[m].x, Vp.x), dpp_prev2(V[m].y, Vp.y)};
;                         const f32x2 gc = bg + g0 * gp2 + g1 * gp1 + g2 * G[m];
;                         const f32x2 vc = bv + v0 * vp2 + v1 * vp1 + v2 * V[m];
;                         const f32x2 xe = gc * (-LOG2E);
;                         f32x2 dn = {__builtin_amdgcn_exp2f(xe.x), __builtin_amdgcn_exp2f(xe.y)}; dn = dn + 1.0f;
;                         const f32x2 rc = {__builtin_amdgcn_rcpf(dn.x), __builtin_amdgcn_rcpf(dn.y)};
;                         const f32x2 rr = gc * rc * vc;
;                         wpk[m][jp] = pk2(rr.x, rr.y); }
;                 }
; #pragma unroll
	v_fmac_f32_dpp v81, v79, v123 row_shr:1 row_mask:0xf bank_mask:0xf
	v_fmac_f32_dpp v81, v87, v123 row_shl:15 row_mask:0xf bank_mask:0xf
	v_pk_mul_f32 v[84:85], v[80:81], s[2:3] op_sel_hi:[1,0]
	v_exp_f32_e32 v84, v84
	v_exp_f32_e32 v85, v85
	v_mov_b32_dpp v86, v82 row_ror:1 row_mask:0xf bank_mask:0xf
	v_mov_b32_dpp v87, v83 row_ror:1 row_mask:0xf bank_mask:0xf
	v_mov_b32_dpp v88, v82 row_ror:2 row_mask:0xf bank_mask:0xf
	v_mov_b32_dpp v89, v83 row_ror:2 row_mask:0xf bank_mask:0xf
	v_pk_add_f32 v[82:83], v[84:85], 1.0 op_sel_hi:[1,0]
	v_pk_mul_f32 v[74:75], v[74:75], v[182:183] op_sel_hi:[1,0]
	v_rcp_f32_e32 v82, v82
	v_rcp_f32_e32 v83, v83
	v_mov_b32_dpp v88, v74 row_shr:2 row_mask:0xf bank_mask:0xf
	v_mov_b32_dpp v89, v75 row_shr:2 row_mask:0xf bank_mask:0xf
	v_mov_b32_dpp v86, v74 row_shr:1 row_mask:0xf bank_mask:0xf
	v_mov_b32_dpp v87, v75 row_shr:1 row_mask:0xf bank_mask:0xf
	v_pk_fma_f32 v[84:85], v[102:103], v[88:89], v[98:99]
	v_pk_mul_f32 v[80:81], v[80:81], v[82:83]
	v_pk_fma_f32 v[84:85], v[110:111], v[86:87], v[84:85]
	v_pk_fma_f32 v[84:85], v[74:75], v[114:115], v[84:85]
	v_pk_mul_f32 v[80:81], v[84:85], v[80:81]
	v_cvt_pk_bf16_f32 v238, v72, v73
	v_pk_mul_f32 v[70:71], v[70:71], v[180:181] op_sel_hi:[1,0]
	v_cvt_pk_bf16_f32 v239, v80, v81
	v_pk_fma_f32 v[82:83], v[70:71], v[126:127], v[106:107]
	v_fmac_f32_dpp v82, v70, v118 row_shr:2 row_mask:0xf bank_mask:0xf
	v_fmac_f32_dpp v82, v78, v118 row_shl:14 row_mask:0xf bank_mask:0xf
	v_fmac_f32_dpp v83, v71, v119 row_shr:2 row_mask:0xf bank_mask:0xf
	v_fmac_f32_dpp v83, v79, v119 row_shl:14 row_mask:0xf bank_mask:0xf
	v_fmac_f32_dpp v82, v70, v122 row_shr:1 row_mask:0xf bank_mask:0xf
	v_fmac_f32_dpp v82, v78, v122 row_shl:15 row_mask:0xf bank_mask:0xf
	v_fmac_f32_dpp v83, v71, v123 row_shr:1 row_mask:0xf bank_mask:0xf
	v_fmac_f32_dpp v83, v79, v123 row_shl:15 row_mask:0xf bank_mask:0xf
	v_mov_b64_e32 v[70:71], v[82:83]
	v_pk_mul_f32 v[80:81], v[70:71], s[2:3] op_sel_hi:[1,0]
	v_exp_f32_e32 v80, v80
	v_exp_f32_e32 v81, v81
	v_mov_b32_dpp v78, v74 row_ror:1 row_mask:0xf bank_mask:0xf
	v_mov_b32_dpp v79, v75 row_ror:1 row_mask:0xf bank_mask:0xf
	v_mov_b32_dpp v84, v74 row_ror:2 row_mask:0xf bank_mask:0xf
	v_mov_b32_dpp v85, v75 row_ror:2 row_mask:0xf bank_mask:0xf
	v_pk_add_f32 v[74:75], v[80:81], 1.0 op_sel_hi:[1,0]
	v_pk_mul_f32 v[66:67], v[66:67], v[180:181] op_sel_hi:[1,0]
	v_rcp_f32_e32 v74, v74
	v_rcp_f32_e32 v75, v75
	v_mov_b32_dpp v84, v66 row_shr:2 row_mask:0xf bank_mask:0xf
	v_mov_b32_dpp v85, v67 row_shr:2 row_mask:0xf bank_mask:0xf
	v_mov_b32_dpp v78, v66 row_shr:1 row_mask:0xf bank_mask:0xf
	v_mov_b32_dpp v79, v67 row_shr:1 row_mask:0xf bank_mask:0xf
	v_pk_fma_f32 v[80:81], v[102:103], v[84:85], v[98:99]
	v_pk_mul_f32 v[70:71], v[70:71], v[74:75]
	v_pk_fma_f32 v[78:79], v[110:111], v[78:79], v[80:81]
	v_cvt_pk_bf16_f32 v254, v76, v77
	v_pk_fma_f32 v[66:67], v[66:67], v[114:115], v[78:79]
	s_nop 0
	v_pk_mul_f32 v[66:67], v[66:67], v[70:71]
	s_nop 0
	v_cvt_pk_bf16_f32 v255, v66, v67
	global_store_dwordx4 v[132:133], v[228:231], off
	global_store_dwordx4 v[134:135], v[232:235], off
	global_store_dwordx4 v[136:137], v[236:239], off
	global_store_dwordx4 v[138:139], v[252:255], off
	v_add_u32_e32 v96, 0x7c, v197
	v_med3_i32 v64, v96, 0, s51
	v_add_u32_e32 v97, 0x8c, v197
	v_add_u32_e32 v99, 0x9c, v197
	v_add_u32_e32 v101, 0xac, v197
	v_lshlrev_b32_e32 v64, 3, v64
	v_med3_i32 v65, v97, 0, s51
	v_med3_i32 v66, v99, 0, s51
	v_med3_i32 v67, v101, 0, s51
	v_lshlrev_b32_e32 v65, 3, v65
	v_lshlrev_b32_e32 v66, 3, v66
	v_lshlrev_b32_e32 v67, 3, v67
	v_cndmask_b32_e64 v103, v96, v190, s[4:5]
	ds_read_b128 v[72:75], v193
	ds_read_b128 v[84:87], v193 offset:128
	ds_read_b128 v[88:91], v193 offset:256
	ds_read_b128 v[92:95], v193 offset:384
	ds_read_b128 v[64:67], v193 offset:512
	ds_read_b128 v[68:71], v193 offset:640
	ds_read_b128 v[76:79], v193 offset:768
	ds_read_b128 v[80:83], v193 offset:896
	s_waitcnt vmcnt(4)
	v_mov_b32_e32 v104, v242
	v_mov_b32_e32 v105, v243
	v_mov_b32_e32 v106, v244
	v_mov_b32_e32 v107, v245
	v_mov_b32_e32 v108, v246
	v_mov_b32_e32 v109, v247
	v_mov_b32_e32 v110, v248
	v_mov_b32_e32 v111, v249
	v_ffbh_u32_e32 v98, v105
	v_ffbh_u32_e32 v100, v107
	v_ffbh_u32_e32 v102, v109
	v_min_u32_e32 v98, 32, v98
	v_min_u32_e32 v100, 32, v100
	v_min_u32_e32 v102, 32, v102
	v_lshlrev_b64 v[104:105], v98, v[104:105]
	v_ffbh_u32_e32 v114, v111
	v_lshlrev_b64 v[106:107], v100, v[106:107]
	v_lshlrev_b64 v[108:109], v102, v[108:109]
	v_min_u32_e32 v104, 1, v104
	v_min_u32_e32 v114, 32, v114
	v_min_u32_e32 v106, 1, v106
	v_min_u32_e32 v108, 1, v108
	v_or_b32_e32 v104, v105, v104
	v_lshlrev_b64 v[110:111], v114, v[110:111]
	v_or_b32_e32 v105, v107, v106
	v_or_b32_e32 v106, v109, v108
	v_cvt_f32_u32_e32 v104, v104
	v_min_u32_e32 v110, 1, v110
	v_cvt_f32_u32_e32 v105, v105
	v_cvt_f32_u32_e32 v106, v106
	v_or_b32_e32 v107, v111, v110
	v_sub_u32_e32 v98, 32, v98
	v_cvt_f32_u32_e32 v107, v107
	v_sub_u32_e32 v100, 32, v100
	v_sub_u32_e32 v102, 32, v102
	v_ldexp_f32 v98, v104, v98
	v_ldexp_f32 v100, v105, v100
	v_ldexp_f32 v102, v106, v102
	v_fmamk_f32 v98, v98, 0x30800000, v196
	v_sub_u32_e32 v114, 32, v114
	v_fmamk_f32 v100, v100, 0x30800000, v196
	v_fmamk_f32 v102, v102, 0x30800000, v196
	v_mul_f32_e32 v105, 0x4b800000, v98
	v_cmp_gt_f32_e32 vcc, s52, v98
	v_ldexp_f32 v104, v107, v114
	v_mul_f32_e32 v106, 0x4b800000, v100
	v_mul_f32_e32 v107, 0x4b800000, v102
	v_cndmask_b32_e32 v98, v98, v105, vcc
	v_cmp_gt_f32_e64 s[8:9], s52, v100
	v_cmp_gt_f32_e64 s[10:11], s52, v102
	v_fmamk_f32 v104, v104, 0x30800000, v196
	v_cndmask_b32_e64 v100, v100, v106, s[8:9]
	v_cndmask_b32_e64 v102, v102, v107, s[10:11]
	v_rsq_f32_e32 v98, v98
	v_mul_f32_e32 v108, 0x4b800000, v104
	v_cmp_gt_f32_e64 s[12:13], s52, v104
	v_rsq_f32_e32 v100, v100
	v_rsq_f32_e32 v102, v102
	v_cndmask_b32_e64 v104, v104, v108, s[12:13]
	v_rsq_f32_e32 v104, v104
	v_mul_f32_e32 v105, 0x45800000, v98
	v_mul_f32_e32 v106, 0x45800000, v100
	v_mul_f32_e32 v107, 0x45800000, v102
	v_cndmask_b32_e32 v98, v98, v105, vcc
	v_cmp_lt_i32_e32 vcc, -1, v96
	v_cndmask_b32_e64 v100, v100, v106, s[8:9]
	v_cndmask_b32_e64 v105, v102, v107, s[10:11]
	v_cndmask_b32_e32 v102, 0, v98, vcc
	v_cmp_lt_i32_e32 vcc, s53, v96
	v_mul_f32_e32 v108, 0x45800000, v104
	v_cndmask_b32_e64 v104, v104, v108, s[12:13]
	v_cndmask_b32_e32 v100, 0, v100, vcc
	v_cmp_lt_i32_e32 vcc, s54, v96
	v_pk_mul_f32 v[60:61], v[60:61], v[102:103] op_sel_hi:[1,0]
	v_pk_mul_f32 v[56:57], v[56:57], v[102:103] op_sel_hi:[1,0]
	v_cndmask_b32_e32 v98, 0, v105, vcc
	v_cmp_lt_i32_e32 vcc, s55, v96
	v_cndmask_b32_e32 v96, 0, v104, vcc
	v_pk_mul_f32 v[108:109], v[32:33], v[96:97] op_sel_hi:[1,0]
	v_pk_mul_f32 v[104:105], v[40:41], v[98:99] op_sel_hi:[1,0]
	s_waitcnt lgkmcnt(6)
; DI unsigned pk2(float lo, float hi) { f32x2 v = {lo, hi}; bf16x2_t b = __builtin_convertvector(v, bf16x2_t); return __builtin_bit_cast(unsigned, b); }
; DI float dpp_prev1(float cur, float prevm) {
;     const int o = __builtin_amdgcn_update_dpp(0, __builtin_bit_cast(int, prevm), 0x121, 0xf, 0xf, false);
;     return __builtin_bit_cast(float, __builtin_amdgcn_update_dpp(o, __builtin_bit_cast(int, cur), 0x111, 0xf, 0xf, false));
; }
; DI float dpp_prev2(float cur, float prevm) {
;     const int o = __builtin_amdgcn_update_dpp(0, __builtin_bit_cast(int, prevm), 0x122, 0xf, 0xf, false);
;     return __builtin_bit_cast(float, __builtin_amdgcn_update_dpp(o, __builtin_bit_cast(int, cur), 0x112, 0xf, 0xf, false));
; }
;     DI void operator()(const AccT& acc, const Unit& u, int wr, int wc, int fr, int fq) const {
;     ...
;                     for (int m = 0; m < 4; ++m) { G[m] = (f32x2){acc[ai][0][m][n][2 * jp], acc[ai][0][m][n][2 * jp + 1]} * rs[m]; V[m] = (f32x2){acc[ai][1][m][n][2 * jp], acc[ai][1][m][n][2 * jp + 1]} * rs[m]; }
; #pragma unroll
;                     for (int m = 0; m < 4; ++m) {
;                         const f32x2 zz = {0.f, 0.f}; const f32x2 Gp = m ? G[m - 1] : zz, Vp = m ? V[m - 1] : zz;
;                         const f32x2 gp1 = {dpp_prev1(G[m].x, Gp.x), dpp_prev1(G[m].y, Gp.y)}, gp2 = {dpp_prev2(G[m].x, Gp.x), dpp_prev2(G[m].y, Gp.y)};
;                         const f32x2 vp1 = {dpp_prev1(V[m].x, Vp.x), dpp_prev1(V[m].y, Vp.y)}, vp2 = {dpp_prev2(V[m].x, Vp.x), dpp_prev2(V[m].y, Vp.y)};
;                         const f32x2 gc = bg + g0 * gp2 + g1 * gp1 + g2 * G[m];
;                         const f32x2 vc = bv + v0 * vp2 + v1 * vp1 + v2 * V[m];
;                         const f32x2 xe = gc * (-LOG2E);
;                         f32x2 dn = {__builtin_amdgcn_exp2f(xe.x), __builtin_amdgcn_exp2f(xe.y)}; dn = dn + 1.0f;
;                         const f32x2 rc = {__builtin_amdgcn_rcpf(dn.x), __builtin_amdgcn_rcpf(dn.y)};
;                         const f32x2 rr = gc * rc * vc;
;                         wpk[m][jp] = pk2(rr.x, rr.y); }
	s_waitcnt lgkmcnt(5)
	s_waitcnt lgkmcnt(4)
	v_pk_fma_f32 v[32:33], v[92:93], v[60:61], v[72:73]
	v_fmac_f32_dpp v32, v60, v84 row_shr:2 row_mask:0xf bank_mask:0xf
	v_fmac_f32_dpp v33, v61, v85 row_shr:2 row_mask:0xf bank_mask:0xf
	v_fmac_f32_dpp v32, v60, v88 row_shr:1 row_mask:0xf bank_mask:0xf
	v_fmac_f32_dpp v33, v61, v89 row_shr:1 row_mask:0xf bank_mask:0xf
	v_pk_mul_f32 v[106:107], v[36:37], v[96:97] op_sel_hi:[1,0]
	v_pk_mul_f32 v[110:111], v[32:33], s[2:3] op_sel_hi:[1,0]
	v_exp_f32_e32 v110, v110
	v_exp_f32_e32 v111, v111
	s_nop 0
	v_pk_add_f32 v[110:111], v[110:111], 1.0 op_sel_hi:[1,0]
	v_rcp_f32_e32 v110, v110
	v_rcp_f32_e32 v111, v111
	s_waitcnt lgkmcnt(2)
	v_pk_mul_f32 v[52:53], v[52:53], v[100:101] op_sel_hi:[1,0]
	s_waitcnt lgkmcnt(1)
	v_pk_mul_f32 v[32:33], v[32:33], v[110:111]
	s_waitcnt lgkmcnt(0)
	v_pk_fma_f32 v[36:37], v[80:81], v[56:57], v[64:65]
	v_fmac_f32_dpp v36, v56, v68 row_shr:2 row_mask:0xf bank_mask:0xf
	v_fmac_f32_dpp v37, v57, v69 row_shr:2 row_mask:0xf bank_mask:0xf
	v_fmac_f32_dpp v36, v56, v76 row_shr:1 row_mask:0xf bank_mask:0xf
	v_fmac_f32_dpp v37, v57, v77 row_shr:1 row_mask:0xf bank_mask:0xf
	v_pk_mul_f32 v[32:33], v[36:37], v[32:33]
	v_pk_fma_f32 v[36:37], v[92:93], v[52:53], v[72:73]
	v_fmac_f32_dpp v36, v52, v84 row_shr:2 row_mask:0xf bank_mask:0xf
	v_fmac_f32_dpp v36, v60, v84 row_shl:14 row_mask:0xf bank_mask:0xf
	v_fmac_f32_dpp v37, v53, v85 row_shr:2 row_mask:0xf bank_mask:0xf
	v_fmac_f32_dpp v37, v61, v85 row_shl:14 row_mask:0xf bank_mask:0xf
	v_fmac_f32_dpp v36, v52, v88 row_shr:1 row_mask:0xf bank_mask:0xf
	v_fmac_f32_dpp v36, v60, v88 row_shl:15 row_mask:0xf bank_mask:0xf
	v_fmac_f32_dpp v37, v53, v89 row_shr:1 row_mask:0xf bank_mask:0xf
	v_fmac_f32_dpp v37, v61, v89 row_shl:15 row_mask:0xf bank_mask:0xf
	v_pk_mul_f32 v[48:49], v[48:49], v[100:101] op_sel_hi:[1,0]
	v_pk_mul_f32 v[40:41], v[36:37], s[2:3] op_sel_hi:[1,0]
	v_exp_f32_e32 v40, v40
	v_exp_f32_e32 v41, v41
	s_nop 0
	v_pk_add_f32 v[40:41], v[40:41], 1.0 op_sel_hi:[1,0]
	v_rcp_f32_e32 v40, v40
	v_rcp_f32_e32 v41, v41
	s_nop 0
	v_pk_mul_f32 v[36:37], v[36:37], v[40:41]
	v_pk_mul_f32 v[44:45], v[44:45], v[98:99] op_sel_hi:[1,0]
	v_pk_fma_f32 v[110:111], v[80:81], v[48:49], v[64:65]
	v_fmac_f32_dpp v110, v48, v68 row_shr:2 row_mask:0xf bank_mask:0xf
	v_fmac_f32_dpp v110, v56, v68 row_shl:14 row_mask:0xf bank_mask:0xf
	v_fmac_f32_dpp v111, v49, v69 row_shr:2 row_mask:0xf bank_mask:0xf
	v_fmac_f32_dpp v111, v57, v69 row_shl:14 row_mask:0xf bank_mask:0xf
	v_fmac_f32_dpp v110, v48, v76 row_shr:1 row_mask:0xf bank_mask:0xf
	v_fmac_f32_dpp v110, v56, v76 row_shl:15 row_mask:0xf bank_mask:0xf
	v_fmac_f32_dpp v111, v49, v77 row_shr:1 row_mask:0xf bank_mask:0xf
	v_fmac_f32_dpp v111, v57, v77 row_shl:15 row_mask:0xf bank_mask:0xf
	v_mov_b64_e32 v[56:57], v[110:111]
	v_pk_mul_f32 v[36:37], v[56:57], v[36:37]
	v_pk_fma_f32 v[40:41], v[92:93], v[44:45], v[72:73]
	v_fmac_f32_dpp v40, v44, v84 row_shr:2 row_mask:0xf bank_mask:0xf
	v_fmac_f32_dpp v40, v52, v84 row_shl:14 row_mask:0xf bank_mask:0xf
	v_fmac_f32_dpp v41, v45, v85 row_shr:2 row_mask:0xf bank_mask:0xf
	v_fmac_f32_dpp v41, v53, v85 row_shl:14 row_mask:0xf bank_mask:0xf
	v_fmac_f32_dpp v40, v44, v88 row_shr:1 row_mask:0xf bank_mask:0xf
	v_fmac_f32_dpp v40, v52, v88 row_shl:15 row_mask:0xf bank_mask:0xf
	v_fmac_f32_dpp v41, v45, v89 row_shr:1 row_mask:0xf bank_mask:0xf
	v_fmac_f32_dpp v41, v53, v89 row_shl:15 row_mask:0xf bank_mask:0xf
	v_pk_mul_f32 v[56:57], v[40:41], s[2:3] op_sel_hi:[1,0]
	v_exp_f32_e32 v56, v56
	v_exp_f32_e32 v57, v57
	v_mov_b32_dpp v52, v48 row_ror:1 row_mask:0xf bank_mask:0xf
	v_mov_b32_dpp v53, v49 row_ror:1 row_mask:0xf bank_mask:0xf
	v_mov_b32_dpp v60, v48 row_ror:2 row_mask:0xf bank_mask:0xf
	v_mov_b32_dpp v61, v49 row_ror:2 row_mask:0xf bank_mask:0xf
	v_pk_add_f32 v[48:49], v[56:57], 1.0 op_sel_hi:[1,0]
	v_mov_b32_dpp v60, v104 row_shr:2 row_mask:0xf bank_mask:0xf
	v_rcp_f32_e32 v48, v48
	v_rcp_f32_e32 v49, v49
	v_mov_b32_dpp v61, v105 row_shr:2 row_mask:0xf bank_mask:0xf
	v_mov_b32_dpp v52, v104 row_shr:1 row_mask:0xf bank_mask:0xf
	v_mov_b32_dpp v53, v105 row_shr:1 row_mask:0xf bank_mask:0xf
	v_pk_fma_f32 v[56:57], v[68:69], v[60:61], v[64:65]
	v_pk_mul_f32 v[40:41], v[40:41], v[48:49]
	v_pk_fma_f32 v[52:53], v[76:77], v[52:53], v[56:57]
	v_pk_fma_f32 v[52:53], v[80:81], v[104:105], v[52:53]
	v_pk_mul_f32 v[40:41], v[52:53], v[40:41]
	v_pk_fma_f32 v[48:49], v[92:93], v[106:107], v[72:73]
	v_fmac_f32_dpp v48, v106, v84 row_shr:2 row_mask:0xf bank_mask:0xf
	v_fmac_f32_dpp v48, v44, v84 row_shl:14 row_mask:0xf bank_mask:0xf
	v_fmac_f32_dpp v49, v107, v85 row_shr:2 row_mask:0xf bank_mask:0xf
	v_fmac_f32_dpp v49, v45, v85 row_shl:14 row_mask:0xf bank_mask:0xf
	v_fmac_f32_dpp v48, v106, v88 row_shr:1 row_mask:0xf bank_mask:0xf
	v_fmac_f32_dpp v48, v44, v88 row_shl:15 row_mask:0xf bank_mask:0xf
	v_fmac_f32_dpp v49, v107, v89 row_shr:1 row_mask:0xf bank_mask:0xf
	v_fmac_f32_dpp v49, v45, v89 row_shl:15 row_mask:0xf bank_mask:0xf
	v_pk_mul_f32 v[52:53], v[48:49], s[2:3] op_sel_hi:[1,0]
	v_exp_f32_e32 v52, v52
	v_exp_f32_e32 v53, v53
	s_nop 0
	v_pk_add_f32 v[52:53], v[52:53], 1.0 op_sel_hi:[1,0]
	v_rcp_f32_e32 v52, v52
	v_rcp_f32_e32 v53, v53
	s_nop 0
	v_pk_mul_f32 v[48:49], v[48:49], v[52:53]
	v_pk_mul_f32 v[52:53], v[58:59], v[102:103] op_sel_hi:[1,0]
	v_pk_fma_f32 v[44:45], v[80:81], v[108:109], v[64:65]
	v_fmac_f32_dpp v44, v108, v68 row_shr:2 row_mask:0xf bank_mask:0xf
	v_fmac_f32_dpp v44, v104, v68 row_shl:14 row_mask:0xf bank_mask:0xf
	v_fmac_f32_dpp v45, v109, v69 row_shr:2 row_mask:0xf bank_mask:0xf
	v_fmac_f32_dpp v45, v105, v69 row_shl:14 row_mask:0xf bank_mask:0xf
; DI unsigned pk2(float lo, float hi) { f32x2 v = {lo, hi}; bf16x2_t b = __builtin_convertvector(v, bf16x2_t); return __builtin_bit_cast(unsigned, b); }
; DI float dpp_prev1(float cur, float prevm) {
;     const int o = __builtin_amdgcn_update_dpp(0, __builtin_bit_cast(int, prevm), 0x121, 0xf, 0xf, false);
;     return __builtin_bit_cast(float, __builtin_amdgcn_update_dpp(o, __builtin_bit_cast(int, cur), 0x111, 0xf, 0xf, false));
; }
; DI float dpp_prev2(float cur, float prevm) {
;     const int o = __builtin_amdgcn_update_dpp(0, __builtin_bit_cast(int, prevm), 0x122, 0xf, 0xf, false);
;     return __builtin_bit_cast(float, __builtin_amdgcn_update_dpp(o, __builtin_bit_cast(int, cur), 0x112, 0xf, 0xf, false));
; }
;     DI void operator()(const AccT& acc, const Unit& u, int wr, int wc, int fr, int fq) const {
;     ...
;                     for (int m = 0; m < 4; ++m) { G[m] = (f32x2){acc[ai][0][m][n][2 * jp], acc[ai][0][m][n][2 * jp + 1]} * rs[m]; V[m] = (f32x2){acc[ai][1][m][n][2 * jp], acc[ai][1][m][n][2 * jp + 1]} * rs[m]; }
; #pragma unroll
;                     for (int m = 0; m < 4; ++m) {
;                         const f32x2 zz = {0.f, 0.f}; const f32x2 Gp = m ? G[m - 1] : zz, Vp = m ? V[m - 1] : zz;
;                         const f32x2 gp1 = {dpp_prev1(G[m].x, Gp.x), dpp_prev1(G[m].y, Gp.y)}, gp2 = {dpp_prev2(G[m].x, Gp.x), dpp_prev2(G[m].y, Gp.y)};
;                         const f32x2 vp1 = {dpp_prev1(V[m].x, Vp.x), dpp_prev1(V[m].y, Vp.y)}, vp2 = {dpp_prev2(V[m].x, Vp.x), dpp_prev2(V[m].y, Vp.y)};
;                         const f32x2 gc = bg + g0 * gp2 + g1 * gp1 + g2 * G[m];
;                         const f32x2 vc = bv + v0 * vp2 + v1 * vp1 + v2 * V[m];
;                         const f32x2 xe = gc * (-LOG2E);
;                         f32x2 dn = {__builtin_amdgcn_exp2f(xe.x), __builtin_amdgcn_exp2f(xe.y)}; dn = dn + 1.0f;
;                         const f32x2 rc = {__builtin_amdgcn_rcpf(dn.x), __builtin_amdgcn_rcpf(dn.y)};
;                         const f32x2 rr = gc * rc * vc;
;                         wpk[m][jp] = pk2(rr.x, rr.y); }
	v_fmac_f32_dpp v44, v108, v76 row_shr:1 row_mask:0xf bank_mask:0xf
	v_fmac_f32_dpp v44, v104, v76 row_shl:15 row_mask:0xf bank_mask:0xf
	v_fmac_f32_dpp v45, v109, v77 row_shr:1 row_mask:0xf bank_mask:0xf
	v_fmac_f32_dpp v45, v105, v77 row_shl:15 row_mask:0xf bank_mask:0xf
	v_pk_mul_f32 v[44:45], v[44:45], v[48:49]
	v_pk_mul_f32 v[48:49], v[62:63], v[102:103] op_sel_hi:[1,0]
	v_pk_fma_f32 v[56:57], v[48:49], v[94:95], v[74:75]
	s_nop 1
	v_fmac_f32_dpp v56, v48, v86 row_shr:2 row_mask:0xf bank_mask:0xf
	v_fmac_f32_dpp v57, v49, v87 row_shr:2 row_mask:0xf bank_mask:0xf
	v_fmac_f32_dpp v56, v48, v90 row_shr:1 row_mask:0xf bank_mask:0xf
	v_fmac_f32_dpp v57, v49, v91 row_shr:1 row_mask:0xf bank_mask:0xf
	v_pk_mul_f32 v[58:59], v[56:57], s[2:3] op_sel_hi:[1,0]
	v_exp_f32_e32 v58, v58
	v_exp_f32_e32 v59, v59
	s_nop 0
	v_pk_add_f32 v[58:59], v[58:59], 1.0 op_sel_hi:[1,0]
	v_rcp_f32_e32 v58, v58
	v_rcp_f32_e32 v59, v59
	v_cvt_pk_bf16_f32 v236, v32, v33
	v_pk_mul_f32 v[56:57], v[56:57], v[58:59]
	v_pk_fma_f32 v[60:61], v[52:53], v[82:83], v[66:67]
	v_fmac_f32_dpp v60, v52, v70 row_shr:2 row_mask:0xf bank_mask:0xf
	v_fmac_f32_dpp v61, v53, v71 row_shr:2 row_mask:0xf bank_mask:0xf
	v_fmac_f32_dpp v60, v52, v78 row_shr:1 row_mask:0xf bank_mask:0xf
	v_fmac_f32_dpp v61, v53, v79 row_shr:1 row_mask:0xf bank_mask:0xf
	v_pk_mul_f32 v[56:57], v[60:61], v[56:57]
	v_pk_mul_f32 v[54:55], v[54:55], v[100:101] op_sel_hi:[1,0]
	v_cvt_pk_bf16_f32 v237, v56, v57
	v_pk_fma_f32 v[56:57], v[54:55], v[94:95], v[74:75]
	v_fmac_f32_dpp v56, v54, v86 row_shr:2 row_mask:0xf bank_mask:0xf
	v_fmac_f32_dpp v56, v48, v86 row_shl:14 row_mask:0xf bank_mask:0xf
	v_fmac_f32_dpp v57, v55, v87 row_shr:2 row_mask:0xf bank_mask:0xf
	v_fmac_f32_dpp v57, v49, v87 row_shl:14 row_mask:0xf bank_mask:0xf
	v_fmac_f32_dpp v56, v54, v90 row_shr:1 row_mask:0xf bank_mask:0xf
	v_fmac_f32_dpp v56, v48, v90 row_shl:15 row_mask:0xf bank_mask:0xf
	v_fmac_f32_dpp v57, v55, v91 row_shr:1 row_mask:0xf bank_mask:0xf
	v_fmac_f32_dpp v57, v49, v91 row_shl:15 row_mask:0xf bank_mask:0xf
	v_pk_mul_f32 v[58:59], v[56:57], s[2:3] op_sel_hi:[1,0]
	v_exp_f32_e32 v58, v58
	v_exp_f32_e32 v59, v59
	v_mov_b32_dpp v48, v52 row_ror:1 row_mask:0xf bank_mask:0xf
	v_mov_b32_dpp v49, v53 row_ror:1 row_mask:0xf bank_mask:0xf
	v_mov_b32_dpp v60, v52 row_ror:2 row_mask:0xf bank_mask:0xf
	v_mov_b32_dpp v61, v53 row_ror:2 row_mask:0xf bank_mask:0xf
	v_pk_add_f32 v[52:53], v[58:59], 1.0 op_sel_hi:[1,0]
	v_pk_mul_f32 v[50:51], v[50:51], v[100:101] op_sel_hi:[1,0]
	v_rcp_f32_e32 v52, v52
	v_rcp_f32_e32 v53, v53
	v_mov_b32_dpp v60, v50 row_shr:2 row_mask:0xf bank_mask:0xf
	v_mov_b32_dpp v61, v51 row_shr:2 row_mask:0xf bank_mask:0xf
	v_mov_b32_dpp v48, v50 row_shr:1 row_mask:0xf bank_mask:0xf
	v_mov_b32_dpp v49, v51 row_shr:1 row_mask:0xf bank_mask:0xf
	v_pk_fma_f32 v[58:59], v[70:71], v[60:61], v[66:67]
	v_pk_mul_f32 v[52:53], v[56:57], v[52:53]
	v_pk_fma_f32 v[48:49], v[78:79], v[48:49], v[58:59]
	v_cvt_pk_bf16_f32 v244, v36, v37
	v_pk_fma_f32 v[48:49], v[50:51], v[82:83], v[48:49]
	v_pk_mul_f32 v[46:47], v[46:47], v[98:99] op_sel_hi:[1,0]
	v_pk_mul_f32 v[48:49], v[48:49], v[52:53]
	v_cvt_pk_bf16_f32 v245, v48, v49
	v_pk_fma_f32 v[48:49], v[46:47], v[94:95], v[74:75]
	v_fmac_f32_dpp v48, v46, v86 row_shr:2 row_mask:0xf bank_mask:0xf
	v_fmac_f32_dpp v48, v54, v86 row_shl:14 row_mask:0xf bank_mask:0xf
	v_fmac_f32_dpp v49, v47, v87 row_shr:2 row_mask:0xf bank_mask:0xf
	v_fmac_f32_dpp v49, v55, v87 row_shl:14 row_mask:0xf bank_mask:0xf
	v_fmac_f32_dpp v48, v46, v90 row_shr:1 row_mask:0xf bank_mask:0xf
	v_fmac_f32_dpp v48, v54, v90 row_shl:15 row_mask:0xf bank_mask:0xf
	v_fmac_f32_dpp v49, v47, v91 row_shr:1 row_mask:0xf bank_mask:0xf
	v_fmac_f32_dpp v49, v55, v91 row_shl:15 row_mask:0xf bank_mask:0xf
	v_pk_mul_f32 v[52:53], v[48:49], s[2:3] op_sel_hi:[1,0]
	v_exp_f32_e32 v52, v52
	v_exp_f32_e32 v53, v53
	v_mov_b32_dpp v54, v50 row_ror:1 row_mask:0xf bank_mask:0xf
	v_mov_b32_dpp v55, v51 row_ror:1 row_mask:0xf bank_mask:0xf
	v_mov_b32_dpp v56, v50 row_ror:2 row_mask:0xf bank_mask:0xf
	v_mov_b32_dpp v57, v51 row_ror:2 row_mask:0xf bank_mask:0xf
	v_pk_add_f32 v[50:51], v[52:53], 1.0 op_sel_hi:[1,0]
	v_pk_mul_f32 v[42:43], v[42:43], v[98:99] op_sel_hi:[1,0]
	v_rcp_f32_e32 v50, v50
	v_rcp_f32_e32 v51, v51
	v_mov_b32_dpp v56, v42 row_shr:2 row_mask:0xf bank_mask:0xf
	v_mov_b32_dpp v57, v43 row_shr:2 row_mask:0xf bank_mask:0xf
	v_mov_b32_dpp v54, v42 row_shr:1 row_mask:0xf bank_mask:0xf
	v_mov_b32_dpp v55, v43 row_shr:1 row_mask:0xf bank_mask:0xf
	v_pk_fma_f32 v[52:53], v[70:71], v[56:57], v[66:67]
	v_pk_mul_f32 v[48:49], v[48:49], v[50:51]
	v_pk_fma_f32 v[52:53], v[78:79], v[54:55], v[52:53]
	v_pk_fma_f32 v[52:53], v[42:43], v[82:83], v[52:53]
	v_pk_mul_f32 v[48:49], v[52:53], v[48:49]
	v_cvt_pk_bf16_f32 v248, v40, v41
	v_pk_mul_f32 v[38:39], v[38:39], v[96:97] op_sel_hi:[1,0]
	v_cvt_pk_bf16_f32 v249, v48, v49
	v_pk_fma_f32 v[50:51], v[38:39], v[94:95], v[74:75]
	v_fmac_f32_dpp v50, v38, v86 row_shr:2 row_mask:0xf bank_mask:0xf
	v_fmac_f32_dpp v50, v46, v86 row_shl:14 row_mask:0xf bank_mask:0xf
	v_fmac_f32_dpp v51, v39, v87 row_shr:2 row_mask:0xf bank_mask:0xf
	v_fmac_f32_dpp v51, v47, v87 row_shl:14 row_mask:0xf bank_mask:0xf
	v_fmac_f32_dpp v50, v38, v90 row_shr:1 row_mask:0xf bank_mask:0xf
	v_fmac_f32_dpp v50, v46, v90 row_shl:15 row_mask:0xf bank_mask:0xf
	v_fmac_f32_dpp v51, v39, v91 row_shr:1 row_mask:0xf bank_mask:0xf
	v_fmac_f32_dpp v51, v47, v91 row_shl:15 row_mask:0xf bank_mask:0xf
	v_mov_b64_e32 v[38:39], v[50:51]
	v_pk_mul_f32 v[48:49], v[38:39], s[2:3] op_sel_hi:[1,0]
	v_exp_f32_e32 v48, v48
	v_exp_f32_e32 v49, v49
; #define LAS __attribute__((address_space(3)))
; DI unsigned pk2(float lo, float hi) { f32x2 v = {lo, hi}; bf16x2_t b = __builtin_convertvector(v, bf16x2_t); return __builtin_bit_cast(unsigned, b); }
;     DI void operator()(const AccT& acc, const Unit& u, int wr, int wc, int fr, int fq) const {
;     ...
;                     const f32x2 bg = *(const LAS f32x2*)(P + lc + 2 * jp), g0 = *(const LAS f32x2*)(P + 32 + lc + 2 * jp), g1 = *(const LAS f32x2*)(P + 64 + lc + 2 * jp), g2 = *(const LAS f32x2*)(P + 96 + lc + 2 * jp);
;                     const f32x2 bv = *(const LAS f32x2*)(P + 128 + lc + 2 * jp), v0 = *(const LAS f32x2*)(P + 160 + lc + 2 * jp), v1 = *(const LAS f32x2*)(P + 192 + lc + 2 * jp), v2 = *(const LAS f32x2*)(P + 224 + lc + 2 * jp);
;                     f32x2 G[4], V[4];
; #pragma unroll
;                     for (int m = 0; m < 4; ++m) { G[m] = (f32x2){acc[ai][0][m][n][2 * jp], acc[ai][0][m][n][2 * jp + 1]} * rs[m]; V[m] = (f32x2){acc[ai][1][m][n][2 * jp], acc[ai][1][m][n][2 * jp + 1]} * rs[m]; }
; #pragma unroll
;                     for (int m = 0; m < 4; ++m) {
;                         const f32x2 zz = {0.f, 0.f}; const f32x2 Gp = m ? G[m - 1] : zz, Vp = m ? V[m - 1] : zz;
;                         const f32x2 gp1 = {dpp_prev1(G[m].x, Gp.x), dpp_prev1(G[m].y, Gp.y)}, gp2 = {dpp_prev2(G[m].x, Gp.x), dpp_prev2(G[m].y, Gp.y)};
;                         const f32x2 vp1 = {dpp_prev1(V[m].x, Vp.x), dpp_prev1(V[m].y, Vp.y)}, vp2 = {dpp_prev2(V[m].x, Vp.x), dpp_prev2(V[m].y, Vp.y)};
;                         const f32x2 gc = bg + g0 * gp2 + g1 * gp1 + g2 * G[m];
;                         const f32x2 vc = bv + v0 * vp2 + v1 * vp1 + v2 * V[m];
;                         const f32x2 xe = gc * (-LOG2E);
;                         f32x2 dn = {__builtin_amdgcn_exp2f(xe.x), __builtin_amdgcn_exp2f(xe.y)}; dn = dn + 1.0f;
;                         const f32x2 rc = {__builtin_amdgcn_rcpf(dn.x), __builtin_amdgcn_rcpf(dn.y)};
;                         const f32x2 rr = gc * rc * vc;
;                         wpk[m][jp] = pk2(rr.x, rr.y); }
;                 }
; #pragma unroll
;                 for (int m = 0; m < 4; ++m) { const int row = m ? tok0 + 16 * m : row0;
;                     *(u32x2*)(ACT + (size_t)row * 2816 + cl + 4 * n) = (u32x2){wpk[m][0], wpk[m][1]}; }
	v_mov_b32_dpp v46, v42 row_ror:1 row_mask:0xf bank_mask:0xf
	v_mov_b32_dpp v47, v43 row_ror:1 row_mask:0xf bank_mask:0xf
	v_mov_b32_dpp v52, v42 row_ror:2 row_mask:0xf bank_mask:0xf
	v_mov_b32_dpp v53, v43 row_ror:2 row_mask:0xf bank_mask:0xf
	v_pk_add_f32 v[42:43], v[48:49], 1.0 op_sel_hi:[1,0]
	v_pk_mul_f32 v[34:35], v[34:35], v[96:97] op_sel_hi:[1,0]
	v_rcp_f32_e32 v42, v42
	v_rcp_f32_e32 v43, v43
	v_mov_b32_dpp v52, v34 row_shr:2 row_mask:0xf bank_mask:0xf
	v_mov_b32_dpp v53, v35 row_shr:2 row_mask:0xf bank_mask:0xf
	v_mov_b32_dpp v46, v34 row_shr:1 row_mask:0xf bank_mask:0xf
	v_mov_b32_dpp v47, v35 row_shr:1 row_mask:0xf bank_mask:0xf
	v_pk_fma_f32 v[48:49], v[70:71], v[52:53], v[66:67]
	v_pk_mul_f32 v[38:39], v[38:39], v[42:43]
	v_pk_fma_f32 v[46:47], v[78:79], v[46:47], v[48:49]
	v_cvt_pk_bf16_f32 v252, v44, v45
	v_pk_fma_f32 v[34:35], v[34:35], v[82:83], v[46:47]
	s_nop 0
	v_pk_mul_f32 v[34:35], v[34:35], v[38:39]
	s_nop 0
	v_cvt_pk_bf16_f32 v253, v34, v35
	v_mad_i64_i32 v[34:35], s[8:9], v103, s48, v[128:129]
	v_lshl_add_u64 v[64:65], v[34:35], 0, v[130:131]
	v_mad_i64_i32 v[32:33], s[8:9], v97, s48, v[128:129]
	v_lshl_add_u64 v[66:67], v[32:33], 0, v[130:131]
	v_mad_i64_i32 v[32:33], s[8:9], v99, s48, v[128:129]
	v_lshl_add_u64 v[68:69], v[32:33], 0, v[130:131]
	v_mad_i64_i32 v[32:33], s[8:9], v101, s48, v[128:129]
	v_lshl_add_u64 v[70:71], v[32:33], 0, v[130:131]
	v_pk_mul_f32 v[30:31], v[30:31], v[102:103] op_sel_hi:[1,0]
	v_pk_mul_f32 v[22:23], v[22:23], v[100:101] op_sel_hi:[1,0]
	s_nop 0
	ds_read_b128 v[40:43], v193 offset:16
	ds_read_b128 v[52:55], v193 offset:144
	ds_read_b128 v[56:59], v193 offset:272
	ds_read_b128 v[60:63], v193 offset:400
	ds_read_b128 v[32:35], v193 offset:528
	ds_read_b128 v[36:39], v193 offset:656
	ds_read_b128 v[44:47], v193 offset:784
	ds_read_b128 v[48:51], v193 offset:912
	s_waitcnt lgkmcnt(6)
	v_pk_mul_f32 v[28:29], v[28:29], v[102:103] op_sel_hi:[1,0]
	v_pk_mul_f32 v[24:25], v[24:25], v[102:103] op_sel_hi:[1,0]
	v_pk_mul_f32 v[20:21], v[20:21], v[100:101] op_sel_hi:[1,0]
	v_pk_mul_f32 v[16:17], v[16:17], v[100:101] op_sel_hi:[1,0]
	v_pk_mul_f32 v[26:27], v[26:27], v[102:103] op_sel_hi:[1,0]
	v_pk_mul_f32 v[100:101], v[18:19], v[100:101] op_sel_hi:[1,0]
	s_waitcnt lgkmcnt(5)
	v_pk_mul_f32 v[76:77], v[12:13], v[98:99] op_sel_hi:[1,0]
	v_pk_mul_f32 v[72:73], v[8:9], v[98:99] op_sel_hi:[1,0]
	v_pk_mul_f32 v[14:15], v[14:15], v[98:99] op_sel_hi:[1,0]
	v_pk_mul_f32 v[10:11], v[10:11], v[98:99] op_sel_hi:[1,0]
	v_mov_b32_dpp v18, v22 row_ror:1 row_mask:0xf bank_mask:0xf
	v_mov_b32_dpp v19, v23 row_ror:1 row_mask:0xf bank_mask:0xf
	v_mov_b32_dpp v120, v22 row_ror:2 row_mask:0xf bank_mask:0xf
	v_mov_b32_dpp v121, v23 row_ror:2 row_mask:0xf bank_mask:0xf
	s_waitcnt lgkmcnt(4)
	v_pk_fma_f32 v[114:115], v[22:23], v[62:63], v[42:43]
	v_fmac_f32_dpp v114, v22, v54 row_shr:2 row_mask:0xf bank_mask:0xf
	v_fmac_f32_dpp v114, v30, v54 row_shl:14 row_mask:0xf bank_mask:0xf
	v_fmac_f32_dpp v115, v23, v55 row_shr:2 row_mask:0xf bank_mask:0xf
	v_fmac_f32_dpp v115, v31, v55 row_shl:14 row_mask:0xf bank_mask:0xf
	v_fmac_f32_dpp v114, v22, v58 row_shr:1 row_mask:0xf bank_mask:0xf
	v_fmac_f32_dpp v114, v30, v58 row_shl:15 row_mask:0xf bank_mask:0xf
	v_fmac_f32_dpp v115, v23, v59 row_shr:1 row_mask:0xf bank_mask:0xf
	v_fmac_f32_dpp v115, v31, v59 row_shl:15 row_mask:0xf bank_mask:0xf
	v_mov_b64_e32 v[22:23], v[114:115]
	v_pk_mul_f32 v[112:113], v[22:23], s[2:3] op_sel_hi:[1,0]
	v_exp_f32_e32 v112, v112
	v_exp_f32_e32 v113, v113
	v_pk_fma_f32 v[102:103], v[30:31], v[62:63], v[42:43]
	v_fmac_f32_dpp v102, v30, v54 row_shr:2 row_mask:0xf bank_mask:0xf
	v_fmac_f32_dpp v103, v31, v55 row_shr:2 row_mask:0xf bank_mask:0xf
	v_fmac_f32_dpp v102, v30, v58 row_shr:1 row_mask:0xf bank_mask:0xf
	v_fmac_f32_dpp v103, v31, v59 row_shr:1 row_mask:0xf bank_mask:0xf
	v_mov_b64_e32 v[30:31], v[102:103]
	v_pk_mul_f32 v[98:99], v[30:31], s[2:3] op_sel_hi:[1,0]
	v_pk_add_f32 v[112:113], v[112:113], 1.0 op_sel_hi:[1,0]
	v_exp_f32_e32 v98, v98
	v_exp_f32_e32 v99, v99
	v_rcp_f32_e32 v112, v112
	v_rcp_f32_e32 v113, v113
	s_waitcnt lgkmcnt(2)
	v_pk_add_f32 v[98:99], v[98:99], 1.0 op_sel_hi:[1,0]
	v_mov_b32_e32 v182, v183
	s_waitcnt lgkmcnt(1)
	v_rcp_f32_e32 v98, v98
	v_rcp_f32_e32 v99, v99
	v_pk_mul_f32 v[86:87], v[4:5], v[96:97] op_sel_hi:[1,0]
	v_mov_b32_e32 v12, v183
	v_mov_b32_e32 v13, v183
	v_mov_b32_e32 v4, v183
	v_mov_b32_e32 v5, v183
	v_mov_b32_e32 v180, v181
	v_mov_b32_dpp v182, v26 row_shr:2 row_mask:0xf bank_mask:0xf
	v_mov_b32_dpp v183, v27 row_shr:2 row_mask:0xf bank_mask:0xf
	v_mov_b32_dpp v122, v100 row_ror:1 row_mask:0xf bank_mask:0xf
	v_mov_b32_dpp v123, v101 row_ror:1 row_mask:0xf bank_mask:0xf
	v_mov_b32_dpp v124, v100 row_ror:2 row_mask:0xf bank_mask:0xf
	v_mov_b32_dpp v125, v101 row_ror:2 row_mask:0xf bank_mask:0xf
	s_waitcnt lgkmcnt(0)
; DI unsigned pk2(float lo, float hi) { f32x2 v = {lo, hi}; bf16x2_t b = __builtin_convertvector(v, bf16x2_t); return __builtin_bit_cast(unsigned, b); }
; DI float dpp_prev1(float cur, float prevm) {
;     const int o = __builtin_amdgcn_update_dpp(0, __builtin_bit_cast(int, prevm), 0x121, 0xf, 0xf, false);
;     return __builtin_bit_cast(float, __builtin_amdgcn_update_dpp(o, __builtin_bit_cast(int, cur), 0x111, 0xf, 0xf, false));
; }
; DI float dpp_prev2(float cur, float prevm) {
;     const int o = __builtin_amdgcn_update_dpp(0, __builtin_bit_cast(int, prevm), 0x122, 0xf, 0xf, false);
;     return __builtin_bit_cast(float, __builtin_amdgcn_update_dpp(o, __builtin_bit_cast(int, cur), 0x112, 0xf, 0xf, false));
; }
;     DI void operator()(const AccT& acc, const Unit& u, int wr, int wc, int fr, int fq) const {
;     ...
;                     for (int m = 0; m < 4; ++m) { G[m] = (f32x2){acc[ai][0][m][n][2 * jp], acc[ai][0][m][n][2 * jp + 1]} * rs[m]; V[m] = (f32x2){acc[ai][1][m][n][2 * jp], acc[ai][1][m][n][2 * jp + 1]} * rs[m]; }
; #pragma unroll
;                     for (int m = 0; m < 4; ++m) {
;                         const f32x2 zz = {0.f, 0.f}; const f32x2 Gp = m ? G[m - 1] : zz, Vp = m ? V[m - 1] : zz;
;                         const f32x2 gp1 = {dpp_prev1(G[m].x, Gp.x), dpp_prev1(G[m].y, Gp.y)}, gp2 = {dpp_prev2(G[m].x, Gp.x), dpp_prev2(G[m].y, Gp.y)};
;                         const f32x2 vp1 = {dpp_prev1(V[m].x, Vp.x), dpp_prev1(V[m].y, Vp.y)}, vp2 = {dpp_prev2(V[m].x, Vp.x), dpp_prev2(V[m].y, Vp.y)};
;                         const f32x2 gc = bg + g0 * gp2 + g1 * gp1 + g2 * G[m];
;                         const f32x2 vc = bv + v0 * vp2 + v1 * vp1 + v2 * V[m];
;                         const f32x2 xe = gc * (-LOG2E);
;                         f32x2 dn = {__builtin_amdgcn_exp2f(xe.x), __builtin_amdgcn_exp2f(xe.y)}; dn = dn + 1.0f;
;                         const f32x2 rc = {__builtin_amdgcn_rcpf(dn.x), __builtin_amdgcn_rcpf(dn.y)};
;                         const f32x2 rr = gc * rc * vc;
;                         wpk[m][jp] = pk2(rr.x, rr.y); }
	v_pk_fma_f32 v[118:119], v[100:101], v[50:51], v[34:35]
	v_fmac_f32_dpp v118, v100, v38 row_shr:2 row_mask:0xf bank_mask:0xf
	v_fmac_f32_dpp v118, v26, v38 row_shl:14 row_mask:0xf bank_mask:0xf
	v_fmac_f32_dpp v119, v101, v39 row_shr:2 row_mask:0xf bank_mask:0xf
	v_fmac_f32_dpp v119, v27, v39 row_shl:14 row_mask:0xf bank_mask:0xf
	v_fmac_f32_dpp v118, v100, v46 row_shr:1 row_mask:0xf bank_mask:0xf
	v_fmac_f32_dpp v118, v26, v46 row_shl:15 row_mask:0xf bank_mask:0xf
	v_fmac_f32_dpp v119, v101, v47 row_shr:1 row_mask:0xf bank_mask:0xf
	v_fmac_f32_dpp v119, v27, v47 row_shl:15 row_mask:0xf bank_mask:0xf
	v_mov_b64_e32 v[100:101], v[118:119]
	v_pk_mul_f32 v[22:23], v[22:23], v[112:113]
	v_pk_mul_f32 v[84:85], v[0:1], v[96:97] op_sel_hi:[1,0]
	v_mov_b32_e32 v8, v181
	v_mov_b32_e32 v9, v181
	v_mov_b32_e32 v0, v181
	v_mov_b32_e32 v1, v181
	v_mov_b32_dpp v180, v26 row_shr:1 row_mask:0xf bank_mask:0xf
	v_mov_b32_dpp v181, v27 row_shr:1 row_mask:0xf bank_mask:0xf
	v_pk_mul_f32 v[22:23], v[100:101], v[22:23]
	v_pk_fma_f32 v[100:101], v[38:39], v[182:183], v[34:35]
	v_pk_fma_f32 v[100:101], v[46:47], v[180:181], v[100:101]
	v_pk_fma_f32 v[26:27], v[26:27], v[50:51], v[100:101]
	v_pk_mul_f32 v[30:31], v[30:31], v[98:99]
	v_pk_mul_f32 v[26:27], v[26:27], v[30:31]
	v_mov_b32_dpp v12, v28 row_shr:2 row_mask:0xf bank_mask:0xf
	v_mov_b32_dpp v13, v29 row_shr:2 row_mask:0xf bank_mask:0xf
	v_pk_fma_f32 v[30:31], v[86:87], v[60:61], v[40:41]
	v_fmac_f32_dpp v30, v86, v52 row_shr:2 row_mask:0xf bank_mask:0xf
	v_fmac_f32_dpp v30, v76, v52 row_shl:14 row_mask:0xf bank_mask:0xf
	v_fmac_f32_dpp v31, v87, v53 row_shr:2 row_mask:0xf bank_mask:0xf
	v_fmac_f32_dpp v31, v77, v53 row_shl:14 row_mask:0xf bank_mask:0xf
	v_fmac_f32_dpp v30, v86, v56 row_shr:1 row_mask:0xf bank_mask:0xf
	v_fmac_f32_dpp v30, v76, v56 row_shl:15 row_mask:0xf bank_mask:0xf
	v_fmac_f32_dpp v31, v87, v57 row_shr:1 row_mask:0xf bank_mask:0xf
	v_fmac_f32_dpp v31, v77, v57 row_shl:15 row_mask:0xf bank_mask:0xf
	v_pk_mul_f32 v[86:87], v[30:31], s[2:3] op_sel_hi:[1,0]
	v_mov_b32_dpp v8, v28 row_shr:1 row_mask:0xf bank_mask:0xf
	v_mov_b32_dpp v9, v29 row_shr:1 row_mask:0xf bank_mask:0xf
	v_exp_f32_e32 v86, v86
	v_exp_f32_e32 v87, v87
	v_pk_fma_f32 v[12:13], v[52:53], v[12:13], v[40:41]
	v_mov_b32_dpp v120, v14 row_shr:2 row_mask:0xf bank_mask:0xf
	v_mov_b32_dpp v121, v15 row_shr:2 row_mask:0xf bank_mask:0xf
	v_pk_fma_f32 v[8:9], v[56:57], v[8:9], v[12:13]
	v_mov_b32_dpp v18, v14 row_shr:1 row_mask:0xf bank_mask:0xf
	v_mov_b32_dpp v19, v15 row_shr:1 row_mask:0xf bank_mask:0xf
	v_pk_fma_f32 v[120:121], v[54:55], v[120:121], v[42:43]
	v_pk_fma_f32 v[8:9], v[28:29], v[60:61], v[8:9]
	v_pk_fma_f32 v[18:19], v[58:59], v[18:19], v[120:121]
	v_pk_mul_f32 v[12:13], v[8:9], s[2:3] op_sel_hi:[1,0]
	v_pk_fma_f32 v[18:19], v[14:15], v[62:63], v[18:19]
	v_pk_add_f32 v[86:87], v[86:87], 1.0 op_sel_hi:[1,0]
	v_pk_fma_f32 v[92:93], v[76:77], v[60:61], v[40:41]
	v_fmac_f32_dpp v92, v76, v52 row_shr:2 row_mask:0xf bank_mask:0xf
	v_fmac_f32_dpp v92, v20, v52 row_shl:14 row_mask:0xf bank_mask:0xf
	v_fmac_f32_dpp v93, v77, v53 row_shr:2 row_mask:0xf bank_mask:0xf
	v_fmac_f32_dpp v93, v21, v53 row_shl:14 row_mask:0xf bank_mask:0xf
	v_fmac_f32_dpp v92, v76, v56 row_shr:1 row_mask:0xf bank_mask:0xf
	v_fmac_f32_dpp v92, v20, v56 row_shl:15 row_mask:0xf bank_mask:0xf
	v_fmac_f32_dpp v93, v77, v57 row_shr:1 row_mask:0xf bank_mask:0xf
	v_fmac_f32_dpp v93, v21, v57 row_shl:15 row_mask:0xf bank_mask:0xf
	v_mov_b64_e32 v[76:77], v[92:93]
	v_exp_f32_e32 v12, v12
	v_exp_f32_e32 v13, v13
	v_pk_mul_f32 v[120:121], v[18:19], s[2:3] op_sel_hi:[1,0]
	v_rcp_f32_e32 v86, v86
	v_rcp_f32_e32 v87, v87
	v_pk_mul_f32 v[88:89], v[76:77], s[2:3] op_sel_hi:[1,0]
	v_exp_f32_e32 v120, v120
	v_exp_f32_e32 v121, v121
	v_exp_f32_e32 v88, v88
	v_exp_f32_e32 v89, v89
	v_pk_mul_f32 v[2:3], v[2:3], v[96:97] op_sel_hi:[1,0]
	v_pk_mul_f32 v[6:7], v[6:7], v[96:97] op_sel_hi:[1,0]
	v_pk_add_f32 v[12:13], v[12:13], 1.0 op_sel_hi:[1,0]
	v_pk_mul_f32 v[30:31], v[30:31], v[86:87]
	v_pk_fma_f32 v[110:111], v[84:85], v[48:49], v[32:33]
	v_fmac_f32_dpp v110, v84, v36 row_shr:2 row_mask:0xf bank_mask:0xf
	v_fmac_f32_dpp v110, v72, v36 row_shl:14 row_mask:0xf bank_mask:0xf
	v_fmac_f32_dpp v111, v85, v37 row_shr:2 row_mask:0xf bank_mask:0xf
	v_fmac_f32_dpp v111, v73, v37 row_shl:14 row_mask:0xf bank_mask:0xf
	v_fmac_f32_dpp v110, v84, v44 row_shr:1 row_mask:0xf bank_mask:0xf
	v_fmac_f32_dpp v110, v72, v44 row_shl:15 row_mask:0xf bank_mask:0xf
	v_fmac_f32_dpp v111, v85, v45 row_shr:1 row_mask:0xf bank_mask:0xf
	v_fmac_f32_dpp v111, v73, v45 row_shl:15 row_mask:0xf bank_mask:0xf
	v_mov_b64_e32 v[84:85], v[110:111]
	v_rcp_f32_e32 v12, v12
	v_rcp_f32_e32 v13, v13
	v_mov_b32_dpp v4, v24 row_shr:2 row_mask:0xf bank_mask:0xf
	v_mov_b32_dpp v5, v25 row_shr:2 row_mask:0xf bank_mask:0xf
	v_pk_add_f32 v[120:121], v[120:121], 1.0 op_sel_hi:[1,0]
	v_pk_mul_f32 v[30:31], v[84:85], v[30:31]
	v_pk_add_f32 v[84:85], v[88:89], 1.0 op_sel_hi:[1,0]
	v_mov_b32_dpp v0, v24 row_shr:1 row_mask:0xf bank_mask:0xf
	v_mov_b32_dpp v1, v25 row_shr:1 row_mask:0xf bank_mask:0xf
	v_rcp_f32_e32 v120, v120
; DI unsigned pk2(float lo, float hi) { f32x2 v = {lo, hi}; bf16x2_t b = __builtin_convertvector(v, bf16x2_t); return __builtin_bit_cast(unsigned, b); }
;     DI void operator()(const AccT& acc, const Unit& u, int wr, int wc, int fr, int fq) const {
;     ...
;                     for (int m = 0; m < 4; ++m) { G[m] = (f32x2){acc[ai][0][m][n][2 * jp], acc[ai][0][m][n][2 * jp + 1]} * rs[m]; V[m] = (f32x2){acc[ai][1][m][n][2 * jp], acc[ai][1][m][n][2 * jp + 1]} * rs[m]; }
; #pragma unroll
;                     for (int m = 0; m < 4; ++m) {
;                         const f32x2 zz = {0.f, 0.f}; const f32x2 Gp = m ? G[m - 1] : zz, Vp = m ? V[m - 1] : zz;
;                         const f32x2 gp1 = {dpp_prev1(G[m].x, Gp.x), dpp_prev1(G[m].y, Gp.y)}, gp2 = {dpp_prev2(G[m].x, Gp.x), dpp_prev2(G[m].y, Gp.y)};
;                         const f32x2 vp1 = {dpp_prev1(V[m].x, Vp.x), dpp_prev1(V[m].y, Vp.y)}, vp2 = {dpp_prev2(V[m].x, Vp.x), dpp_prev2(V[m].y, Vp.y)};
;                         const f32x2 gc = bg + g0 * gp2 + g1 * gp1 + g2 * G[m];
;                         const f32x2 vc = bv + v0 * vp2 + v1 * vp1 + v2 * V[m];
;                         const f32x2 xe = gc * (-LOG2E);
;                         f32x2 dn = {__builtin_amdgcn_exp2f(xe.x), __builtin_amdgcn_exp2f(xe.y)}; dn = dn + 1.0f;
;                         const f32x2 rc = {__builtin_amdgcn_rcpf(dn.x), __builtin_amdgcn_rcpf(dn.y)};
;                         const f32x2 rr = gc * rc * vc;
;                         wpk[m][jp] = pk2(rr.x, rr.y); }
;                 }
; #pragma unroll
;                 for (int m = 0; m < 4; ++m) { const int row = m ? tok0 + 16 * m : row0;
;                     *(u32x2*)(ACT + (size_t)row * 2816 + cl + 4 * n) = (u32x2){wpk[m][0], wpk[m][1]}; }
	v_rcp_f32_e32 v121, v121
	v_rcp_f32_e32 v84, v84
	v_rcp_f32_e32 v85, v85
	v_pk_fma_f32 v[4:5], v[36:37], v[4:5], v[32:33]
	v_mov_b32_dpp v124, v10 row_shr:2 row_mask:0xf bank_mask:0xf
	v_mov_b32_dpp v125, v11 row_shr:2 row_mask:0xf bank_mask:0xf
	v_pk_fma_f32 v[0:1], v[44:45], v[0:1], v[4:5]
	v_mov_b32_dpp v122, v10 row_shr:1 row_mask:0xf bank_mask:0xf
	v_mov_b32_dpp v123, v11 row_shr:1 row_mask:0xf bank_mask:0xf
	v_pk_fma_f32 v[124:125], v[38:39], v[124:125], v[34:35]
	v_pk_fma_f32 v[0:1], v[24:25], v[48:49], v[0:1]
	v_pk_mul_f32 v[4:5], v[8:9], v[12:13]
	v_pk_fma_f32 v[122:123], v[46:47], v[122:123], v[124:125]
	v_pk_mul_f32 v[0:1], v[0:1], v[4:5]
	v_pk_fma_f32 v[122:123], v[10:11], v[50:51], v[122:123]
	v_pk_mul_f32 v[18:19], v[18:19], v[120:121]
	v_cvt_pk_bf16_f32 v239, v26, v27
	v_pk_fma_f32 v[94:95], v[72:73], v[48:49], v[32:33]
	v_fmac_f32_dpp v94, v72, v36 row_shr:2 row_mask:0xf bank_mask:0xf
	v_fmac_f32_dpp v94, v16, v36 row_shl:14 row_mask:0xf bank_mask:0xf
	v_fmac_f32_dpp v95, v73, v37 row_shr:2 row_mask:0xf bank_mask:0xf
	v_fmac_f32_dpp v95, v17, v37 row_shl:14 row_mask:0xf bank_mask:0xf
	v_fmac_f32_dpp v94, v72, v44 row_shr:1 row_mask:0xf bank_mask:0xf
	v_fmac_f32_dpp v94, v16, v44 row_shl:15 row_mask:0xf bank_mask:0xf
	v_fmac_f32_dpp v95, v73, v45 row_shr:1 row_mask:0xf bank_mask:0xf
	v_fmac_f32_dpp v95, v17, v45 row_shl:15 row_mask:0xf bank_mask:0xf
	v_mov_b64_e32 v[72:73], v[94:95]
	v_pk_mul_f32 v[76:77], v[76:77], v[84:85]
	v_cvt_pk_bf16_f32 v238, v0, v1
	v_pk_mul_f32 v[18:19], v[122:123], v[18:19]
	v_pk_mul_f32 v[72:73], v[72:73], v[76:77]
	v_cvt_pk_bf16_f32 v251, v18, v19
	v_cvt_pk_bf16_f32 v250, v72, v73
	v_pk_fma_f32 v[78:79], v[20:21], v[60:61], v[40:41]
	v_fmac_f32_dpp v78, v20, v52 row_shr:2 row_mask:0xf bank_mask:0xf
	v_fmac_f32_dpp v78, v28, v52 row_shl:14 row_mask:0xf bank_mask:0xf
	v_fmac_f32_dpp v79, v21, v53 row_shr:2 row_mask:0xf bank_mask:0xf
	v_fmac_f32_dpp v79, v29, v53 row_shl:14 row_mask:0xf bank_mask:0xf
	v_fmac_f32_dpp v78, v20, v56 row_shr:1 row_mask:0xf bank_mask:0xf
	v_fmac_f32_dpp v78, v28, v56 row_shl:15 row_mask:0xf bank_mask:0xf
	v_fmac_f32_dpp v79, v21, v57 row_shr:1 row_mask:0xf bank_mask:0xf
	v_fmac_f32_dpp v79, v29, v57 row_shl:15 row_mask:0xf bank_mask:0xf
	v_mov_b64_e32 v[20:21], v[78:79]
	v_pk_fma_f32 v[0:1], v[6:7], v[62:63], v[42:43]
	v_fmac_f32_dpp v0, v6, v54 row_shr:2 row_mask:0xf bank_mask:0xf
	v_fmac_f32_dpp v0, v14, v54 row_shl:14 row_mask:0xf bank_mask:0xf
	v_fmac_f32_dpp v1, v7, v55 row_shr:2 row_mask:0xf bank_mask:0xf
	v_fmac_f32_dpp v1, v15, v55 row_shl:14 row_mask:0xf bank_mask:0xf
	v_fmac_f32_dpp v0, v6, v58 row_shr:1 row_mask:0xf bank_mask:0xf
	v_fmac_f32_dpp v0, v14, v58 row_shl:15 row_mask:0xf bank_mask:0xf
	v_fmac_f32_dpp v1, v7, v59 row_shr:1 row_mask:0xf bank_mask:0xf
	v_fmac_f32_dpp v1, v15, v59 row_shl:15 row_mask:0xf bank_mask:0xf
	v_pk_mul_f32 v[72:73], v[20:21], s[2:3] op_sel_hi:[1,0]
	v_pk_mul_f32 v[4:5], v[0:1], s[2:3] op_sel_hi:[1,0]
	v_exp_f32_e32 v72, v72
	v_exp_f32_e32 v73, v73
	v_exp_f32_e32 v4, v4
	v_exp_f32_e32 v5, v5
	v_pk_add_f32 v[72:73], v[72:73], 1.0 op_sel_hi:[1,0]
	v_pk_add_f32 v[4:5], v[4:5], 1.0 op_sel_hi:[1,0]
	v_rcp_f32_e32 v72, v72
	v_rcp_f32_e32 v73, v73
	v_rcp_f32_e32 v4, v4
	v_rcp_f32_e32 v5, v5
	v_pk_fma_f32 v[82:83], v[16:17], v[48:49], v[32:33]
	v_fmac_f32_dpp v82, v16, v36 row_shr:2 row_mask:0xf bank_mask:0xf
	v_fmac_f32_dpp v82, v24, v36 row_shl:14 row_mask:0xf bank_mask:0xf
	v_fmac_f32_dpp v83, v17, v37 row_shr:2 row_mask:0xf bank_mask:0xf
	v_fmac_f32_dpp v83, v25, v37 row_shl:14 row_mask:0xf bank_mask:0xf
	v_fmac_f32_dpp v82, v16, v44 row_shr:1 row_mask:0xf bank_mask:0xf
	v_fmac_f32_dpp v82, v24, v44 row_shl:15 row_mask:0xf bank_mask:0xf
	v_fmac_f32_dpp v83, v17, v45 row_shr:1 row_mask:0xf bank_mask:0xf
	v_fmac_f32_dpp v83, v25, v45 row_shl:15 row_mask:0xf bank_mask:0xf
	v_mov_b64_e32 v[16:17], v[82:83]
	v_pk_mul_f32 v[20:21], v[20:21], v[72:73]
	v_pk_fma_f32 v[12:13], v[2:3], v[50:51], v[34:35]
	v_fmac_f32_dpp v12, v2, v38 row_shr:2 row_mask:0xf bank_mask:0xf
	v_fmac_f32_dpp v12, v10, v38 row_shl:14 row_mask:0xf bank_mask:0xf
	v_fmac_f32_dpp v13, v3, v39 row_shr:2 row_mask:0xf bank_mask:0xf
	v_fmac_f32_dpp v13, v11, v39 row_shl:14 row_mask:0xf bank_mask:0xf
	v_fmac_f32_dpp v12, v2, v46 row_shr:1 row_mask:0xf bank_mask:0xf
	v_fmac_f32_dpp v12, v10, v46 row_shl:15 row_mask:0xf bank_mask:0xf
	v_fmac_f32_dpp v13, v3, v47 row_shr:1 row_mask:0xf bank_mask:0xf
	v_fmac_f32_dpp v13, v11, v47 row_shl:15 row_mask:0xf bank_mask:0xf
	v_mov_b64_e32 v[2:3], v[12:13]
	v_pk_mul_f32 v[0:1], v[0:1], v[4:5]
	v_pk_mul_f32 v[16:17], v[16:17], v[20:21]
	v_pk_mul_f32 v[0:1], v[2:3], v[0:1]
	v_cvt_pk_bf16_f32 v247, v22, v23
	v_cvt_pk_bf16_f32 v254, v30, v31
	v_cvt_pk_bf16_f32 v246, v16, v17
	v_cvt_pk_bf16_f32 v255, v0, v1
	global_store_dwordx4 v[64:65], v[236:239], off
	global_store_dwordx4 v[66:67], v[244:247], off
	global_store_dwordx4 v[68:69], v[248:251], off
	global_store_dwordx4 v[70:71], v[252:255], off
	s_and_b64 vcc, exec, s[6:7]
	s_mov_b64 s[6:7], -1
	s_cbranch_vccnz .LBB0_1817
	s_andn2_b64 vcc, exec, s[14:15]
	s_cbranch_vccnz .LBB0_1816
	s_barrier
	s_branch .LBB0_1816
